# deferred full-XCC polls first test a copy of the flag line loaded for free at the preceding seam (skips round trip + vmcnt drain on the critical path)
# speedup vs baseline: 1.0124x; 1.0000x over previous
; __device__ __forceinline__ unsigned xb_ld(unsigned* p)              { return __hip_atomic_load(p, __ATOMIC_RELAXED, __HIP_MEMORY_SCOPE_AGENT); }
; #define XB_SPIN(cond, bar) do { unsigned _sp = 0; while (cond) { __builtin_amdgcn_s_sleep(1); \
;     if ((++_sp & 255u) == 0u) { if (xb_ld(&(bar)[XB_TMO])) break; if (_sp > XB_SPIN_CAP) { atomicAdd(&(bar)[XB_TMO], 1u); break; } } } } while (0)
; __device__ __forceinline__ bool is_t0(int wave) { return wave == 0 && olane() == 0; }
; __device__ __forceinline__ void xcdl_wait_t0(const XcdBarrier& b) {
;     if (is_t0(b.wave)) {
;         unsigned* bar = b.bar; asm volatile("" : "+s"(bar));
;         const unsigned gen = b.st[5];
;         XB_SPIN(xb_ld(&bar[XB_LGEN(b.x)]) == gen, bar);
;         __builtin_amdgcn_fence(__ATOMIC_ACQUIRE, "agent");
;         asm volatile("s_waitcnt vmcnt(0)" ::: "memory");
;     }
; }
.Lxbf_poll_S1:
	global_load_dword v3, v2, s[0:1] sc1
	global_load_dword v248, v2, s[0:1] offset:-1024 sc1
	s_waitcnt vmcnt(0)
	v_cmp_lt_u32_e32 vcc, v3, v1
	s_nop 1
	s_cmp_eq_u64 vcc, 0
	s_cbranch_scc1 .Lxbf_done_S1
	s_sleep 1
	s_add_u32 s8, s8, 1
	s_cmp_lt_u32 s8, 0x4000
	s_cbranch_scc1 .Lxbf_poll_S1
	v_mov_b32_e32 v3, 1
	v_mov_b32_e32 v2, 0x200
	global_store_dword v2, v3, s[26:27] sc1

; #define LAS __attribute__((address_space(3)))
; __device__ __forceinline__ int otid(int wave) { return wave * 64 + olane(); }
; #define BU_LOAD(buf, ib) do { _Pragma("unroll") for (int h = 0; h < 2; ++h) { const int it = (2 * (ib) + h + k2) & 7, l = 16 * w + 2 * it + rp; \
;             _Pragma("unroll") for (int s2 = 0; s2 < 8; ++s2) c4[buf][h][s2] = *(const GAS u32x4*)(z0 + (size_t)l * 2048 + 256 * s2); } } while (0)
; __device__ __forceinline__ void b_unit(Frame& F, int u, bool dry) {
;     ...
;     const int b = u >> 5, k2 = (u >> 2) & 7, g = u & 3;
;     const int w = F.wave, lane = otid(F.wave) & 63, sg = lane & 31, rp = lane >> 5;
;     LAS unsigned char* Bt = F.lds;
;     {
;         const f32x2* TW = (const f32x2*)(ws_ + WS_TW) + k2 * 256 + 8 * sg; const f32x2* W8 = (const f32x2*)(ws_ + WS_W8);
;         f32x2 tw[8], w8[8];
; #pragma unroll
;         for (int j = 0; j < 8; ++j) { tw[j] = TW[j]; w8[j] = W8[(j * k2) & 7]; }
;         const bf16_t* z0 = (const bf16_t*)(ws_ + WS_ZT) + (size_t)(b * 512 + g * 128) * 2048 + 8 * sg;
;         u32x4 c4[2][2][8];
;     ...
;         BU_LOAD(0, 0);
;         BU_LOAD(1, 1); BU_RED(0, 0);
;         BU_LOAD(0, 2); BU_RED(1, 1);
.LBB0_468:
	s_cmp_le_i32 s66, s16
	s_cselect_b64 s[0:1], -1, 0
	s_and_b64 s[4:5], s[0:1], s[4:5]
	s_andn2_b64 vcc, exec, s[4:5]
	s_cbranch_vccnz .LBB0_562
	s_mov_b64 s[2:3], s[82:83]
	v_readlane_b32 s0, v254, 23
	v_mbcnt_lo_u32_b32 v170, -1, 0
	v_mbcnt_hi_u32_b32 v170, -1, v170
	s_add_u32 s0, s2, s0
	v_and_b32_e32 v18, 31, v170
	s_addc_u32 s1, s3, 0
	v_lshlrev_b32_e32 v192, 6, v18
	v_lshl_add_u64 v[0:1], s[0:1], 0, v[192:193]
	s_mov_b64 s[0:1], 0x1dd0000
	v_lshl_add_u64 v[2:3], v[0:1], 0, s[0:1]
	s_mov_b32 s0, 0x1dd0000
	v_add_co_u32_e32 v0, vcc, s0, v0
	s_add_u32 s6, s2, 0x1dd4000
	s_nop 0
	v_addc_co_u32_e32 v1, vcc, 0, v1, vcc
	s_addc_u32 s7, s3, 0
	flat_load_dwordx4 v[8:11], v[0:1]
	v_mov_b32_e32 v0, s2
	s_mov_b32 s8, 0x1dd4000
	v_readlane_b32 s0, v254, 24
	v_add_co_u32_e32 v0, vcc, s8, v0
	v_mov_b32_e32 v1, s3
	s_add_u32 s0, s6, s0
	v_addc_co_u32_e32 v1, vcc, 0, v1, vcc
	s_addc_u32 s1, s7, 0
	flat_load_dwordx2 v[144:145], v[0:1]
	v_mov_b64_e32 v[0:1], s[0:1]
	v_readlane_b32 s0, v254, 25
	s_add_u32 s0, s6, s0
	s_addc_u32 s1, s7, 0
	flat_load_dwordx2 v[146:147], v[0:1]
	flat_load_dwordx4 v[12:15], v[2:3] offset:16
	v_mov_b64_e32 v[0:1], s[0:1]
	v_readlane_b32 s0, v254, 26
	s_add_u32 s0, s6, s0
	s_addc_u32 s1, s7, 0
	flat_load_dwordx2 v[148:149], v[0:1]
	v_mov_b64_e32 v[0:1], s[0:1]
	v_readlane_b32 s0, v254, 27
	s_add_u32 s0, s6, s0
	s_addc_u32 s1, s7, 0
	flat_load_dwordx2 v[150:151], v[0:1]
	flat_load_dwordx4 v[4:7], v[2:3] offset:32
	v_mov_b64_e32 v[0:1], s[0:1]
	v_readlane_b32 s0, v254, 28
	s_add_u32 s0, s6, s0
	s_addc_u32 s1, s7, 0
	flat_load_dwordx2 v[152:153], v[0:1]
	v_mov_b64_e32 v[0:1], s[0:1]
	v_readlane_b32 s0, v254, 29
	s_add_u32 s0, s6, s0
	s_addc_u32 s1, s7, 0
	v_mov_b64_e32 v[16:17], s[0:1]
	v_readlane_b32 s0, v254, 30
	s_add_u32 s0, s6, s0
	s_addc_u32 s1, s7, 0
	flat_load_dwordx2 v[154:155], v[0:1]
	s_nop 0
	flat_load_dwordx4 v[0:3], v[2:3] offset:48
	v_lshlrev_b32_e32 v192, 4, v18
	flat_load_dwordx2 v[156:157], v[16:17]
	v_mov_b64_e32 v[16:17], s[0:1]
	v_readlane_b32 s0, v253, 43
	v_readlane_b32 s1, v253, 44
	s_add_u32 s0, s2, s0
	s_addc_u32 s1, s3, s1
	flat_load_dwordx2 v[158:159], v[16:17]
	v_lshl_add_u64 v[16:17], s[0:1], 0, v[192:193]
	s_mov_b64 s[0:1], 0x8000000
	v_bfe_u32 v172, v170, 5, 1
	v_lshl_add_u64 v[162:163], v[16:17], 0, s[0:1]
	v_readlane_b32 s0, v253, 45
	v_mov_b32_e32 v139, v193
	v_readlane_b32 s1, v253, 46
	v_or_b32_e32 v138, s0, v172
	v_lshlrev_b64 v[16:17], 12, v[138:139]
	v_lshl_add_u64 v[16:17], v[162:163], 0, v[16:17]
	global_load_dwordx4 v[140:143], v[16:17], off sc1
	global_load_dwordx4 v[174:177], v[16:17], off offset:512 sc1
	global_load_dwordx4 v[72:75], v[16:17], off offset:1024 sc1
	global_load_dwordx4 v[104:107], v[16:17], off offset:1536 sc1
	global_load_dwordx4 v[112:115], v[16:17], off offset:2048 sc1
	global_load_dwordx4 v[116:119], v[16:17], off offset:2560 sc1
	global_load_dwordx4 v[120:123], v[16:17], off offset:3072 sc1
	global_load_dwordx4 v[124:127], v[16:17], off offset:3584 sc1
	v_or_b32_e32 v136, s1, v172
	v_mov_b32_e32 v137, v193
	v_lshlrev_b64 v[16:17], 12, v[136:137]
	v_lshl_add_u64 v[16:17], v[162:163], 0, v[16:17]
	global_load_dwordx4 v[108:111], v[16:17], off sc1
	global_load_dwordx4 v[76:79], v[16:17], off offset:512 sc1
	global_load_dwordx4 v[60:63], v[16:17], off offset:1024 sc1
	global_load_dwordx4 v[56:59], v[16:17], off offset:1536 sc1
	global_load_dwordx4 v[52:55], v[16:17], off offset:2048 sc1
	global_load_dwordx4 v[48:51], v[16:17], off offset:2560 sc1
	global_load_dwordx4 v[44:47], v[16:17], off offset:3072 sc1
	global_load_dwordx4 v[40:43], v[16:17], off offset:3584 sc1
	v_readlane_b32 s1, v253, 47
	v_mov_b32_e32 v167, v193
	v_mov_b32_e32 v165, v193
	v_or_b32_e32 v166, s1, v172
	v_lshlrev_b64 v[16:17], 12, v[166:167]
	v_lshl_add_u64 v[16:17], v[162:163], 0, v[16:17]
	global_load_dwordx4 v[132:135], v[16:17], off sc1
	global_load_dwordx4 v[128:131], v[16:17], off offset:512 sc1
	global_load_dwordx4 v[100:103], v[16:17], off offset:1024 sc1
	global_load_dwordx4 v[96:99], v[16:17], off offset:1536 sc1
	global_load_dwordx4 v[92:95], v[16:17], off offset:2048 sc1
	global_load_dwordx4 v[88:91], v[16:17], off offset:2560 sc1
	global_load_dwordx4 v[84:87], v[16:17], off offset:3072 sc1
	global_load_dwordx4 v[80:83], v[16:17], off offset:3584 sc1
	v_readlane_b32 s1, v253, 48
	s_movk_i32 s6, 0x410
	v_and_b32_e32 v171, 63, v170
	v_or_b32_e32 v164, s1, v172
	v_lshlrev_b64 v[16:17], 12, v[164:165]
	v_lshl_add_u64 v[16:17], v[162:163], 0, v[16:17]
	global_load_dwordx4 v[68:71], v[16:17], off sc1
	global_load_dwordx4 v[64:67], v[16:17], off offset:512 sc1
	global_load_dwordx4 v[36:39], v[16:17], off offset:1024 sc1
	global_load_dwordx4 v[32:35], v[16:17], off offset:1536 sc1
	global_load_dwordx4 v[28:31], v[16:17], off offset:2048 sc1
	global_load_dwordx4 v[24:27], v[16:17], off offset:2560 sc1
	global_load_dwordx4 v[20:23], v[16:17], off offset:3072 sc1
	s_nop 0
	global_load_dwordx4 v[16:19], v[16:17], off offset:3584 sc1
	s_mov_b32 s7, 0x1d90000
	s_mov_b64 s[28:29], s[82:83]
	s_waitcnt vmcnt(0)
	v_lshlrev_b32_e32 v160, 16, v140
	v_and_b32_e32 v161, 0xffff0000, v140
	v_lshlrev_b32_e32 v178, 16, v174
	v_and_b32_e32 v179, 0xffff0000, v174
	s_waitcnt lgkmcnt(0)
	v_pk_fma_f32 v[182:183], v[144:145], v[160:161], 0 op_sel_hi:[0,1,0]
	v_pk_fma_f32 v[160:161], v[144:145], v[160:161], 0 op_sel:[1,0,0] op_sel_hi:[1,1,0]
	v_pk_fma_f32 v[182:183], v[146:147], v[178:179], v[182:183] op_sel_hi:[0,1,1]
	v_pk_fma_f32 v[160:161], v[146:147], v[178:179], v[160:161] op_sel:[1,0,0]
	v_lshlrev_b32_e32 v178, 16, v72
	v_and_b32_e32 v179, 0xffff0000, v72
	v_pk_fma_f32 v[182:183], v[148:149], v[178:179], v[182:183] op_sel_hi:[0,1,1]
	v_pk_fma_f32 v[160:161], v[148:149], v[178:179], v[160:161] op_sel:[1,0,0]
	v_lshlrev_b32_e32 v178, 16, v104
	v_and_b32_e32 v179, 0xffff0000, v104
	v_pk_fma_f32 v[182:183], v[150:151], v[178:179], v[182:183] op_sel_hi:[0,1,1]
	v_pk_fma_f32 v[160:161], v[150:151], v[178:179], v[160:161] op_sel:[1,0,0]
	v_lshlrev_b32_e32 v178, 16, v112
	v_and_b32_e32 v179, 0xffff0000, v112
	v_pk_fma_f32 v[182:183], v[152:153], v[178:179], v[182:183] op_sel_hi:[0,1,1]
	v_pk_fma_f32 v[160:161], v[152:153], v[178:179], v[160:161] op_sel:[1,0,0]
	v_lshlrev_b32_e32 v178, 16, v116
	v_and_b32_e32 v179, 0xffff0000, v116
	v_pk_fma_f32 v[182:183], v[154:155], v[178:179], v[182:183] op_sel_hi:[0,1,1]
	v_pk_fma_f32 v[160:161], v[154:155], v[178:179], v[160:161] op_sel:[1,0,0]
	v_lshlrev_b32_e32 v178, 16, v120
	v_and_b32_e32 v179, 0xffff0000, v120
	v_pk_fma_f32 v[182:183], v[156:157], v[178:179], v[182:183] op_sel_hi:[0,1,1]
	v_pk_fma_f32 v[160:161], v[156:157], v[178:179], v[160:161] op_sel:[1,0,0]
	v_lshlrev_b32_e32 v178, 16, v124
	v_and_b32_e32 v179, 0xffff0000, v124
	v_pk_fma_f32 v[182:183], v[158:159], v[178:179], v[182:183] op_sel_hi:[0,1,1]
	v_pk_fma_f32 v[178:179], v[158:159], v[178:179], v[160:161] op_sel:[1,0,0]
	v_mov_b32_e32 v161, v10
	v_mov_b32_e32 v10, v9
	v_mov_b32_e32 v160, v8
	v_pk_mul_f32 v[8:9], v[10:11], v[178:179]
	v_lshlrev_b32_e32 v140, 16, v141
	v_and_b32_e32 v141, 0xffff0000, v141
	v_pk_fma_f32 v[184:185], v[160:161], v[182:183], v[8:9] neg_lo:[0,0,1] neg_hi:[0,0,1]
	v_pk_mul_f32 v[8:9], v[160:161], v[178:179]
	v_lshlrev_b32_e32 v174, 16, v175
	v_and_b32_e32 v175, 0xffff0000, v175
	v_pk_fma_f32 v[178:179], v[10:11], v[182:183], v[8:9]
	v_pk_fma_f32 v[8:9], v[144:145], v[140:141], 0 op_sel_hi:[0,1,0]
	v_pk_fma_f32 v[140:141], v[144:145], v[140:141], 0 op_sel:[1,0,0] op_sel_hi:[1,1,0]
	v_pk_fma_f32 v[8:9], v[146:147], v[174:175], v[8:9] op_sel_hi:[0,1,1]
	v_pk_fma_f32 v[140:141], v[146:147], v[174:175], v[140:141] op_sel:[1,0,0]
	v_lshlrev_b32_e32 v72, 16, v73
	v_and_b32_e32 v73, 0xffff0000, v73
	v_pk_fma_f32 v[8:9], v[148:149], v[72:73], v[8:9] op_sel_hi:[0,1,1]
	v_pk_fma_f32 v[72:73], v[148:149], v[72:73], v[140:141] op_sel:[1,0,0]
	v_lshlrev_b32_e32 v104, 16, v105
	v_and_b32_e32 v105, 0xffff0000, v105
	v_pk_fma_f32 v[8:9], v[150:151], v[104:105], v[8:9] op_sel_hi:[0,1,1]
	v_pk_fma_f32 v[72:73], v[150:151], v[104:105], v[72:73] op_sel:[1,0,0]
	v_lshlrev_b32_e32 v104, 16, v113
	v_and_b32_e32 v105, 0xffff0000, v113
	v_pk_fma_f32 v[8:9], v[152:153], v[104:105], v[8:9] op_sel_hi:[0,1,1]
	v_pk_fma_f32 v[72:73], v[152:153], v[104:105], v[72:73] op_sel:[1,0,0]
	v_lshlrev_b32_e32 v104, 16, v117
	v_and_b32_e32 v105, 0xffff0000, v117
	v_pk_fma_f32 v[8:9], v[154:155], v[104:105], v[8:9] op_sel_hi:[0,1,1]
	v_pk_fma_f32 v[72:73], v[154:155], v[104:105], v[72:73] op_sel:[1,0,0]
	v_lshlrev_b32_e32 v104, 16, v121
	v_and_b32_e32 v105, 0xffff0000, v121
	v_pk_fma_f32 v[8:9], v[156:157], v[104:105], v[8:9] op_sel_hi:[0,1,1]
	v_pk_fma_f32 v[72:73], v[156:157], v[104:105], v[72:73] op_sel:[1,0,0]
	v_lshlrev_b32_e32 v104, 16, v125
	v_and_b32_e32 v105, 0xffff0000, v125
	v_pk_fma_f32 v[112:113], v[158:159], v[104:105], v[8:9] op_sel_hi:[0,1,1]
	v_pk_fma_f32 v[72:73], v[158:159], v[104:105], v[72:73] op_sel:[1,0,0]
	v_mov_b32_e32 v9, v14
	v_mov_b32_e32 v14, v13
	v_mov_b32_e32 v8, v12
	v_pk_mul_f32 v[12:13], v[14:15], v[72:73]
	v_lshlrev_b32_e32 v168, 16, v142
	v_and_b32_e32 v169, 0xffff0000, v142
	v_pk_fma_f32 v[104:105], v[8:9], v[112:113], v[12:13] neg_lo:[0,0,1] neg_hi:[0,0,1]
	v_pk_mul_f32 v[12:13], v[8:9], v[72:73]
	v_lshlrev_b32_e32 v180, 16, v176
	v_and_b32_e32 v181, 0xffff0000, v176
	v_pk_fma_f32 v[112:113], v[14:15], v[112:113], v[12:13]
	v_pk_fma_f32 v[12:13], v[144:145], v[168:169], 0 op_sel_hi:[0,1,0]
	v_pk_fma_f32 v[72:73], v[144:145], v[168:169], 0 op_sel:[1,0,0] op_sel_hi:[1,1,0]
	v_pk_fma_f32 v[12:13], v[146:147], v[180:181], v[12:13] op_sel_hi:[0,1,1]
	v_pk_fma_f32 v[72:73], v[146:147], v[180:181], v[72:73] op_sel:[1,0,0]
	v_lshlrev_b32_e32 v116, 16, v74
	v_and_b32_e32 v117, 0xffff0000, v74
	v_pk_fma_f32 v[12:13], v[148:149], v[116:117], v[12:13] op_sel_hi:[0,1,1]
	v_pk_fma_f32 v[72:73], v[148:149], v[116:117], v[72:73] op_sel:[1,0,0]
	v_lshlrev_b32_e32 v116, 16, v106
	v_and_b32_e32 v117, 0xffff0000, v106
	v_pk_fma_f32 v[12:13], v[150:151], v[116:117], v[12:13] op_sel_hi:[0,1,1]
	v_pk_fma_f32 v[72:73], v[150:151], v[116:117], v[72:73] op_sel:[1,0,0]
	v_lshlrev_b32_e32 v116, 16, v114
	v_and_b32_e32 v117, 0xffff0000, v114
	v_pk_fma_f32 v[12:13], v[152:153], v[116:117], v[12:13] op_sel_hi:[0,1,1]
	v_pk_fma_f32 v[72:73], v[152:153], v[116:117], v[72:73] op_sel:[1,0,0]
	v_lshlrev_b32_e32 v116, 16, v118
	v_and_b32_e32 v117, 0xffff0000, v118
	v_pk_fma_f32 v[12:13], v[154:155], v[116:117], v[12:13] op_sel_hi:[0,1,1]
	v_pk_fma_f32 v[72:73], v[154:155], v[116:117], v[72:73] op_sel:[1,0,0]
	v_lshlrev_b32_e32 v116, 16, v122
	v_and_b32_e32 v117, 0xffff0000, v122
	v_pk_fma_f32 v[12:13], v[156:157], v[116:117], v[12:13] op_sel_hi:[0,1,1]
	v_pk_fma_f32 v[72:73], v[156:157], v[116:117], v[72:73] op_sel:[1,0,0]
	v_lshlrev_b32_e32 v116, 16, v126
	v_and_b32_e32 v117, 0xffff0000, v126
	v_pk_fma_f32 v[120:121], v[158:159], v[116:117], v[12:13] op_sel_hi:[0,1,1]
	v_pk_fma_f32 v[72:73], v[158:159], v[116:117], v[72:73] op_sel:[1,0,0]
	v_mov_b32_e32 v13, v6
	v_mov_b32_e32 v6, v5
	v_mov_b32_e32 v12, v4
	v_pk_mul_f32 v[4:5], v[6:7], v[72:73]
	v_lshlrev_b32_e32 v142, 16, v143
	v_and_b32_e32 v143, 0xffff0000, v143
	v_pk_fma_f32 v[116:117], v[12:13], v[120:121], v[4:5] neg_lo:[0,0,1] neg_hi:[0,0,1]
	v_pk_mul_f32 v[4:5], v[12:13], v[72:73]
	v_lshlrev_b32_e32 v176, 16, v177
	v_and_b32_e32 v177, 0xffff0000, v177
	v_pk_fma_f32 v[120:121], v[6:7], v[120:121], v[4:5]
	v_pk_fma_f32 v[4:5], v[144:145], v[142:143], 0 op_sel_hi:[0,1,0]
	v_pk_fma_f32 v[72:73], v[144:145], v[142:143], 0 op_sel:[1,0,0] op_sel_hi:[1,1,0]
	v_pk_fma_f32 v[4:5], v[146:147], v[176:177], v[4:5] op_sel_hi:[0,1,1]
	v_pk_fma_f32 v[72:73], v[146:147], v[176:177], v[72:73] op_sel:[1,0,0]
	v_lshlrev_b32_e32 v74, 16, v75
	v_and_b32_e32 v75, 0xffff0000, v75
	v_pk_fma_f32 v[4:5], v[148:149], v[74:75], v[4:5] op_sel_hi:[0,1,1]
	v_pk_fma_f32 v[72:73], v[148:149], v[74:75], v[72:73] op_sel:[1,0,0]
	v_lshlrev_b32_e32 v74, 16, v107
	v_and_b32_e32 v75, 0xffff0000, v107
	v_pk_fma_f32 v[4:5], v[150:151], v[74:75], v[4:5] op_sel_hi:[0,1,1]
	v_pk_fma_f32 v[72:73], v[150:151], v[74:75], v[72:73] op_sel:[1,0,0]
	v_lshlrev_b32_e32 v74, 16, v115
	v_and_b32_e32 v75, 0xffff0000, v115
	v_pk_fma_f32 v[4:5], v[152:153], v[74:75], v[4:5] op_sel_hi:[0,1,1]
	v_pk_fma_f32 v[72:73], v[152:153], v[74:75], v[72:73] op_sel:[1,0,0]
	v_lshlrev_b32_e32 v74, 16, v119
	v_and_b32_e32 v75, 0xffff0000, v119
	v_pk_fma_f32 v[4:5], v[154:155], v[74:75], v[4:5] op_sel_hi:[0,1,1]
	v_pk_fma_f32 v[72:73], v[154:155], v[74:75], v[72:73] op_sel:[1,0,0]
	v_lshlrev_b32_e32 v74, 16, v123
	v_and_b32_e32 v75, 0xffff0000, v123
	v_pk_fma_f32 v[4:5], v[156:157], v[74:75], v[4:5] op_sel_hi:[0,1,1]
	v_pk_fma_f32 v[72:73], v[156:157], v[74:75], v[72:73] op_sel:[1,0,0]
	v_lshlrev_b32_e32 v74, 16, v127
	v_and_b32_e32 v75, 0xffff0000, v127
	v_pk_fma_f32 v[106:107], v[158:159], v[74:75], v[4:5] op_sel_hi:[0,1,1]
	v_pk_fma_f32 v[72:73], v[158:159], v[74:75], v[72:73] op_sel:[1,0,0]
	v_mov_b32_e32 v5, v2
	v_mov_b32_e32 v2, v1
	v_mov_b32_e32 v4, v0
	v_pk_mul_f32 v[0:1], v[2:3], v[72:73]
	v_pk_mul_f32 v[72:73], v[4:5], v[72:73]
	v_pk_fma_f32 v[0:1], v[4:5], v[106:107], v[0:1] neg_lo:[0,0,1] neg_hi:[0,0,1]
	v_pk_fma_f32 v[106:107], v[2:3], v[106:107], v[72:73]
	v_cvt_pk_bf16_f32 v75, v0, v1
	v_mul_lo_u32 v0, v138, s6
	v_cvt_pk_bf16_f32 v72, v184, v185
	v_cvt_pk_bf16_f32 v73, v104, v105
	v_cvt_pk_bf16_f32 v74, v116, v117
	v_add3_u32 v0, 0, v0, v192
	ds_write_b128 v0, v[72:75]
	v_cvt_pk_bf16_f32 v72, v178, v179
	v_cvt_pk_bf16_f32 v73, v112, v113
	v_cvt_pk_bf16_f32 v74, v120, v121
	v_cvt_pk_bf16_f32 v75, v106, v107
	ds_write_b128 v0, v[72:75] offset:512
	v_lshlrev_b32_e32 v0, 16, v108
	v_and_b32_e32 v1, 0xffff0000, v108
	v_lshlrev_b32_e32 v74, 16, v110
	v_and_b32_e32 v75, 0xffff0000, v110
	v_lshlrev_b32_e32 v104, 16, v111
	v_and_b32_e32 v105, 0xffff0000, v111
	v_lshlrev_b32_e32 v106, 16, v76
	v_and_b32_e32 v107, 0xffff0000, v76
	v_pk_fma_f32 v[110:111], v[144:145], v[0:1], 0 op_sel_hi:[0,1,0]
	v_pk_fma_f32 v[0:1], v[144:145], v[0:1], 0 op_sel:[1,0,0] op_sel_hi:[1,1,0]
	v_pk_fma_f32 v[110:111], v[146:147], v[106:107], v[110:111] op_sel_hi:[0,1,1]
	v_pk_fma_f32 v[0:1], v[146:147], v[106:107], v[0:1] op_sel:[1,0,0]
	v_lshlrev_b32_e32 v106, 16, v60
	v_and_b32_e32 v107, 0xffff0000, v60
	v_pk_fma_f32 v[110:111], v[148:149], v[106:107], v[110:111] op_sel_hi:[0,1,1]
	v_pk_fma_f32 v[0:1], v[148:149], v[106:107], v[0:1] op_sel:[1,0,0]
	v_lshlrev_b32_e32 v106, 16, v56
	v_and_b32_e32 v107, 0xffff0000, v56
	v_pk_fma_f32 v[110:111], v[150:151], v[106:107], v[110:111] op_sel_hi:[0,1,1]
	v_pk_fma_f32 v[0:1], v[150:151], v[106:107], v[0:1] op_sel:[1,0,0]
	v_lshlrev_b32_e32 v106, 16, v52
	v_and_b32_e32 v107, 0xffff0000, v52
	v_pk_fma_f32 v[110:111], v[152:153], v[106:107], v[110:111] op_sel_hi:[0,1,1]
	v_pk_fma_f32 v[0:1], v[152:153], v[106:107], v[0:1] op_sel:[1,0,0]
	v_lshlrev_b32_e32 v106, 16, v48
	v_and_b32_e32 v107, 0xffff0000, v48
	v_pk_fma_f32 v[110:111], v[154:155], v[106:107], v[110:111] op_sel_hi:[0,1,1]
	v_pk_fma_f32 v[0:1], v[154:155], v[106:107], v[0:1] op_sel:[1,0,0]
	v_lshlrev_b32_e32 v106, 16, v44
	v_and_b32_e32 v107, 0xffff0000, v44
	v_pk_fma_f32 v[110:111], v[156:157], v[106:107], v[110:111] op_sel_hi:[0,1,1]
	v_pk_fma_f32 v[0:1], v[156:157], v[106:107], v[0:1] op_sel:[1,0,0]
	v_lshlrev_b32_e32 v106, 16, v40
	v_and_b32_e32 v107, 0xffff0000, v40
	v_pk_fma_f32 v[0:1], v[158:159], v[106:107], v[0:1] op_sel:[1,0,0]
	v_lshlrev_b32_e32 v72, 16, v109
	v_and_b32_e32 v73, 0xffff0000, v109
	v_pk_fma_f32 v[110:111], v[158:159], v[106:107], v[110:111] op_sel_hi:[0,1,1]
	v_pk_mul_f32 v[106:107], v[10:11], v[0:1]
	v_pk_mul_f32 v[0:1], v[160:161], v[0:1]
	v_lshlrev_b32_e32 v76, 16, v77
	v_and_b32_e32 v77, 0xffff0000, v77
	v_pk_fma_f32 v[106:107], v[160:161], v[110:111], v[106:107] neg_lo:[0,0,1] neg_hi:[0,0,1]
	v_pk_fma_f32 v[0:1], v[10:11], v[110:111], v[0:1]
	v_pk_fma_f32 v[110:111], v[144:145], v[72:73], 0 op_sel_hi:[0,1,0]
	v_pk_fma_f32 v[72:73], v[144:145], v[72:73], 0 op_sel:[1,0,0] op_sel_hi:[1,1,0]
	v_pk_fma_f32 v[110:111], v[146:147], v[76:77], v[110:111] op_sel_hi:[0,1,1]
	v_pk_fma_f32 v[72:73], v[146:147], v[76:77], v[72:73] op_sel:[1,0,0]
	v_lshlrev_b32_e32 v60, 16, v61
	v_and_b32_e32 v61, 0xffff0000, v61
	v_pk_fma_f32 v[76:77], v[148:149], v[60:61], v[110:111] op_sel_hi:[0,1,1]
	v_pk_fma_f32 v[60:61], v[148:149], v[60:61], v[72:73] op_sel:[1,0,0]
	v_lshlrev_b32_e32 v56, 16, v57
	v_and_b32_e32 v57, 0xffff0000, v57
	v_pk_fma_f32 v[72:73], v[150:151], v[56:57], v[76:77] op_sel_hi:[0,1,1]
	v_pk_fma_f32 v[56:57], v[150:151], v[56:57], v[60:61] op_sel:[1,0,0]
	v_lshlrev_b32_e32 v52, 16, v53
	v_and_b32_e32 v53, 0xffff0000, v53
	v_pk_fma_f32 v[60:61], v[152:153], v[52:53], v[72:73] op_sel_hi:[0,1,1]
	v_pk_fma_f32 v[52:53], v[152:153], v[52:53], v[56:57] op_sel:[1,0,0]
	v_lshlrev_b32_e32 v48, 16, v49
	v_and_b32_e32 v49, 0xffff0000, v49
	v_pk_fma_f32 v[56:57], v[154:155], v[48:49], v[60:61] op_sel_hi:[0,1,1]
	v_pk_fma_f32 v[48:49], v[154:155], v[48:49], v[52:53] op_sel:[1,0,0]
	v_lshlrev_b32_e32 v44, 16, v45
	v_and_b32_e32 v45, 0xffff0000, v45
	v_pk_fma_f32 v[52:53], v[156:157], v[44:45], v[56:57] op_sel_hi:[0,1,1]
	v_pk_fma_f32 v[44:45], v[156:157], v[44:45], v[48:49] op_sel:[1,0,0]
	v_lshlrev_b32_e32 v40, 16, v41
	v_and_b32_e32 v41, 0xffff0000, v41
	v_pk_fma_f32 v[48:49], v[158:159], v[40:41], v[52:53] op_sel_hi:[0,1,1]
	v_pk_fma_f32 v[40:41], v[158:159], v[40:41], v[44:45] op_sel:[1,0,0]
	v_lshlrev_b32_e32 v108, 16, v78
	v_pk_mul_f32 v[44:45], v[14:15], v[40:41]
	v_pk_mul_f32 v[40:41], v[8:9], v[40:41]
	v_and_b32_e32 v109, 0xffff0000, v78
	v_pk_fma_f32 v[44:45], v[8:9], v[48:49], v[44:45] neg_lo:[0,0,1] neg_hi:[0,0,1]
	v_pk_fma_f32 v[48:49], v[14:15], v[48:49], v[40:41]
	v_pk_fma_f32 v[40:41], v[144:145], v[74:75], 0 op_sel_hi:[0,1,0]
	v_pk_fma_f32 v[52:53], v[144:145], v[74:75], 0 op_sel:[1,0,0] op_sel_hi:[1,1,0]
	v_pk_fma_f32 v[40:41], v[146:147], v[108:109], v[40:41] op_sel_hi:[0,1,1]
	v_pk_fma_f32 v[52:53], v[146:147], v[108:109], v[52:53] op_sel:[1,0,0]
	v_lshlrev_b32_e32 v56, 16, v62
	v_and_b32_e32 v57, 0xffff0000, v62
	v_pk_fma_f32 v[40:41], v[148:149], v[56:57], v[40:41] op_sel_hi:[0,1,1]
	v_pk_fma_f32 v[52:53], v[148:149], v[56:57], v[52:53] op_sel:[1,0,0]
	v_lshlrev_b32_e32 v56, 16, v58
	v_and_b32_e32 v57, 0xffff0000, v58
	v_pk_fma_f32 v[40:41], v[150:151], v[56:57], v[40:41] op_sel_hi:[0,1,1]
	v_pk_fma_f32 v[52:53], v[150:151], v[56:57], v[52:53] op_sel:[1,0,0]
	v_lshlrev_b32_e32 v56, 16, v54
	v_and_b32_e32 v57, 0xffff0000, v54
	v_pk_fma_f32 v[40:41], v[152:153], v[56:57], v[40:41] op_sel_hi:[0,1,1]
	v_pk_fma_f32 v[52:53], v[152:153], v[56:57], v[52:53] op_sel:[1,0,0]
	v_lshlrev_b32_e32 v56, 16, v50
	v_and_b32_e32 v57, 0xffff0000, v50
	v_pk_fma_f32 v[40:41], v[154:155], v[56:57], v[40:41] op_sel_hi:[0,1,1]
	v_pk_fma_f32 v[52:53], v[154:155], v[56:57], v[52:53] op_sel:[1,0,0]
	v_lshlrev_b32_e32 v56, 16, v46
	v_and_b32_e32 v57, 0xffff0000, v46
	v_pk_fma_f32 v[40:41], v[156:157], v[56:57], v[40:41] op_sel_hi:[0,1,1]
	v_pk_fma_f32 v[52:53], v[156:157], v[56:57], v[52:53] op_sel:[1,0,0]
	v_lshlrev_b32_e32 v56, 16, v42
	v_and_b32_e32 v57, 0xffff0000, v42
	v_pk_fma_f32 v[52:53], v[158:159], v[56:57], v[52:53] op_sel:[1,0,0]
	v_pk_fma_f32 v[40:41], v[158:159], v[56:57], v[40:41] op_sel_hi:[0,1,1]
	v_pk_mul_f32 v[56:57], v[6:7], v[52:53]
	v_pk_mul_f32 v[52:53], v[12:13], v[52:53]
	v_lshlrev_b32_e32 v78, 16, v79
	v_and_b32_e32 v79, 0xffff0000, v79
	v_pk_fma_f32 v[56:57], v[12:13], v[40:41], v[56:57] neg_lo:[0,0,1] neg_hi:[0,0,1]
	v_pk_fma_f32 v[52:53], v[6:7], v[40:41], v[52:53]
	v_pk_fma_f32 v[40:41], v[144:145], v[104:105], 0 op_sel_hi:[0,1,0]
	v_pk_fma_f32 v[60:61], v[144:145], v[104:105], 0 op_sel:[1,0,0] op_sel_hi:[1,1,0]
	v_pk_fma_f32 v[40:41], v[146:147], v[78:79], v[40:41] op_sel_hi:[0,1,1]
	v_pk_fma_f32 v[60:61], v[146:147], v[78:79], v[60:61] op_sel:[1,0,0]
	v_lshlrev_b32_e32 v62, 16, v63
	v_and_b32_e32 v63, 0xffff0000, v63
	v_pk_fma_f32 v[40:41], v[148:149], v[62:63], v[40:41] op_sel_hi:[0,1,1]
	v_pk_fma_f32 v[60:61], v[148:149], v[62:63], v[60:61] op_sel:[1,0,0]
	v_lshlrev_b32_e32 v58, 16, v59
	v_and_b32_e32 v59, 0xffff0000, v59
	v_pk_fma_f32 v[40:41], v[150:151], v[58:59], v[40:41] op_sel_hi:[0,1,1]
	v_pk_fma_f32 v[58:59], v[150:151], v[58:59], v[60:61] op_sel:[1,0,0]
	v_lshlrev_b32_e32 v54, 16, v55
	v_and_b32_e32 v55, 0xffff0000, v55
	v_lshlrev_b32_e32 v174, 16, v132
	v_and_b32_e32 v175, 0xffff0000, v132
	v_pk_fma_f32 v[40:41], v[152:153], v[54:55], v[40:41] op_sel_hi:[0,1,1]
	v_pk_fma_f32 v[54:55], v[152:153], v[54:55], v[58:59] op_sel:[1,0,0]
	v_lshlrev_b32_e32 v50, 16, v51
	v_and_b32_e32 v51, 0xffff0000, v51
	v_lshlrev_b32_e32 v178, 16, v128
	v_and_b32_e32 v179, 0xffff0000, v128
	v_pk_fma_f32 v[182:183], v[144:145], v[174:175], 0 op_sel_hi:[0,1,0]
	v_pk_fma_f32 v[174:175], v[144:145], v[174:175], 0 op_sel:[1,0,0] op_sel_hi:[1,1,0]
	v_pk_fma_f32 v[40:41], v[154:155], v[50:51], v[40:41] op_sel_hi:[0,1,1]
	v_pk_fma_f32 v[50:51], v[154:155], v[50:51], v[54:55] op_sel:[1,0,0]
	v_lshlrev_b32_e32 v46, 16, v47
	v_and_b32_e32 v47, 0xffff0000, v47
	v_pk_fma_f32 v[182:183], v[146:147], v[178:179], v[182:183] op_sel_hi:[0,1,1]
	v_pk_fma_f32 v[174:175], v[146:147], v[178:179], v[174:175] op_sel:[1,0,0]
	v_lshlrev_b32_e32 v178, 16, v100
	v_and_b32_e32 v179, 0xffff0000, v100
	v_pk_fma_f32 v[40:41], v[156:157], v[46:47], v[40:41] op_sel_hi:[0,1,1]
	v_pk_fma_f32 v[46:47], v[156:157], v[46:47], v[50:51] op_sel:[1,0,0]
	v_lshlrev_b32_e32 v42, 16, v43
	v_and_b32_e32 v43, 0xffff0000, v43
	v_pk_fma_f32 v[182:183], v[148:149], v[178:179], v[182:183] op_sel_hi:[0,1,1]
	v_pk_fma_f32 v[174:175], v[148:149], v[178:179], v[174:175] op_sel:[1,0,0]
	v_lshlrev_b32_e32 v178, 16, v96
	v_and_b32_e32 v179, 0xffff0000, v96
	v_pk_fma_f32 v[40:41], v[158:159], v[42:43], v[40:41] op_sel_hi:[0,1,1]
	v_pk_fma_f32 v[42:43], v[158:159], v[42:43], v[46:47] op_sel:[1,0,0]
	v_pk_fma_f32 v[182:183], v[150:151], v[178:179], v[182:183] op_sel_hi:[0,1,1]
	v_pk_fma_f32 v[174:175], v[150:151], v[178:179], v[174:175] op_sel:[1,0,0]
	v_lshlrev_b32_e32 v178, 16, v92
	v_and_b32_e32 v179, 0xffff0000, v92
; #define BU_LOAD(buf, ib) do { _Pragma("unroll") for (int h = 0; h < 2; ++h) { const int it = (2 * (ib) + h + k2) & 7, l = 16 * w + 2 * it + rp; \
;             _Pragma("unroll") for (int s2 = 0; s2 < 8; ++s2) c4[buf][h][s2] = *(const GAS u32x4*)(z0 + (size_t)l * 2048 + 256 * s2); } } while (0)
; __device__ __forceinline__ void b_unit(Frame& F, int u, bool dry) {
;     ...
;         BU_LOAD(0, 0);
;         BU_LOAD(1, 1); BU_RED(0, 0);
	v_pk_mul_f32 v[46:47], v[2:3], v[42:43]
	v_pk_mul_f32 v[42:43], v[4:5], v[42:43]
	v_pk_fma_f32 v[182:183], v[152:153], v[178:179], v[182:183] op_sel_hi:[0,1,1]
	v_pk_fma_f32 v[174:175], v[152:153], v[178:179], v[174:175] op_sel:[1,0,0]
	v_lshlrev_b32_e32 v178, 16, v88
	v_and_b32_e32 v179, 0xffff0000, v88
	v_pk_fma_f32 v[46:47], v[4:5], v[40:41], v[46:47] neg_lo:[0,0,1] neg_hi:[0,0,1]
	v_pk_fma_f32 v[50:51], v[2:3], v[40:41], v[42:43]
	v_cvt_pk_bf16_f32 v41, v44, v45
	v_mul_lo_u32 v44, v136, s6
	v_pk_fma_f32 v[182:183], v[154:155], v[178:179], v[182:183] op_sel_hi:[0,1,1]
	v_pk_fma_f32 v[174:175], v[154:155], v[178:179], v[174:175] op_sel:[1,0,0]
	v_lshlrev_b32_e32 v178, 16, v84
	v_and_b32_e32 v179, 0xffff0000, v84
	v_cvt_pk_bf16_f32 v40, v106, v107
	v_cvt_pk_bf16_f32 v42, v56, v57
	v_cvt_pk_bf16_f32 v43, v46, v47
	v_add3_u32 v44, 0, v44, v192
	v_bitop3_b32 v168, v172, 8, s0 bitop3:0x36
	v_mov_b32_e32 v169, v193
	v_pk_fma_f32 v[182:183], v[156:157], v[178:179], v[182:183] op_sel_hi:[0,1,1]
	v_pk_fma_f32 v[174:175], v[156:157], v[178:179], v[174:175] op_sel:[1,0,0]
	v_lshlrev_b32_e32 v178, 16, v80
	v_and_b32_e32 v179, 0xffff0000, v80
	ds_write_b128 v44, v[40:43]
	v_cvt_pk_bf16_f32 v40, v0, v1
	v_cvt_pk_bf16_f32 v41, v48, v49
	v_cvt_pk_bf16_f32 v42, v52, v53
	v_cvt_pk_bf16_f32 v43, v50, v51
	v_lshlrev_b64 v[0:1], 12, v[168:169]
	v_pk_fma_f32 v[174:175], v[158:159], v[178:179], v[174:175] op_sel:[1,0,0]
	ds_write_b128 v44, v[40:43] offset:512
	v_lshl_add_u64 v[0:1], v[162:163], 0, v[0:1]
	v_lshlrev_b32_e32 v132, 16, v133
	v_and_b32_e32 v133, 0xffff0000, v133
	v_pk_fma_f32 v[182:183], v[158:159], v[178:179], v[182:183] op_sel_hi:[0,1,1]
	v_pk_mul_f32 v[178:179], v[10:11], v[174:175]
	v_pk_mul_f32 v[174:175], v[160:161], v[174:175]
	global_load_dwordx4 v[140:143], v[0:1], off sc1
	global_load_dwordx4 v[136:139], v[0:1], off offset:512 sc1
	global_load_dwordx4 v[124:127], v[0:1], off offset:1024 sc1
	global_load_dwordx4 v[120:123], v[0:1], off offset:1536 sc1
	global_load_dwordx4 v[116:119], v[0:1], off offset:2048 sc1
	global_load_dwordx4 v[112:115], v[0:1], off offset:2560 sc1
	global_load_dwordx4 v[108:111], v[0:1], off offset:3072 sc1
	global_load_dwordx4 v[104:107], v[0:1], off offset:3584 sc1
	v_lshlrev_b32_e32 v128, 16, v129
	v_and_b32_e32 v129, 0xffff0000, v129
	v_pk_fma_f32 v[178:179], v[160:161], v[182:183], v[178:179] neg_lo:[0,0,1] neg_hi:[0,0,1]
	v_pk_fma_f32 v[174:175], v[10:11], v[182:183], v[174:175]
	v_pk_fma_f32 v[182:183], v[144:145], v[132:133], 0 op_sel_hi:[0,1,0]
	v_pk_fma_f32 v[132:133], v[144:145], v[132:133], 0 op_sel:[1,0,0] op_sel_hi:[1,1,0]
	v_pk_fma_f32 v[182:183], v[146:147], v[128:129], v[182:183] op_sel_hi:[0,1,1]
	v_pk_fma_f32 v[128:129], v[146:147], v[128:129], v[132:133] op_sel:[1,0,0]
	v_lshlrev_b32_e32 v100, 16, v101
	v_and_b32_e32 v101, 0xffff0000, v101
	v_pk_fma_f32 v[132:133], v[148:149], v[100:101], v[182:183] op_sel_hi:[0,1,1]
	v_pk_fma_f32 v[100:101], v[148:149], v[100:101], v[128:129] op_sel:[1,0,0]
	v_lshlrev_b32_e32 v96, 16, v97
	v_and_b32_e32 v97, 0xffff0000, v97
	v_pk_fma_f32 v[128:129], v[150:151], v[96:97], v[132:133] op_sel_hi:[0,1,1]
	v_pk_fma_f32 v[96:97], v[150:151], v[96:97], v[100:101] op_sel:[1,0,0]
	v_lshlrev_b32_e32 v92, 16, v93
	v_and_b32_e32 v93, 0xffff0000, v93
	v_pk_fma_f32 v[100:101], v[152:153], v[92:93], v[128:129] op_sel_hi:[0,1,1]
	v_pk_fma_f32 v[92:93], v[152:153], v[92:93], v[96:97] op_sel:[1,0,0]
	v_lshlrev_b32_e32 v88, 16, v89
	v_and_b32_e32 v89, 0xffff0000, v89
	v_pk_fma_f32 v[96:97], v[154:155], v[88:89], v[100:101] op_sel_hi:[0,1,1]
	v_pk_fma_f32 v[88:89], v[154:155], v[88:89], v[92:93] op_sel:[1,0,0]
	v_lshlrev_b32_e32 v84, 16, v85
	v_and_b32_e32 v85, 0xffff0000, v85
	v_pk_fma_f32 v[92:93], v[156:157], v[84:85], v[96:97] op_sel_hi:[0,1,1]
	v_pk_fma_f32 v[84:85], v[156:157], v[84:85], v[88:89] op_sel:[1,0,0]
	v_lshlrev_b32_e32 v80, 16, v81
	v_and_b32_e32 v81, 0xffff0000, v81
	v_pk_fma_f32 v[88:89], v[158:159], v[80:81], v[92:93] op_sel_hi:[0,1,1]
	v_pk_fma_f32 v[80:81], v[158:159], v[80:81], v[84:85] op_sel:[1,0,0]
	v_lshlrev_b32_e32 v176, 16, v134
	v_and_b32_e32 v177, 0xffff0000, v134
	v_pk_mul_f32 v[84:85], v[14:15], v[80:81]
	v_pk_mul_f32 v[80:81], v[8:9], v[80:81]
	v_lshlrev_b32_e32 v180, 16, v130
	v_and_b32_e32 v181, 0xffff0000, v130
	v_pk_fma_f32 v[84:85], v[8:9], v[88:89], v[84:85] neg_lo:[0,0,1] neg_hi:[0,0,1]
	v_pk_fma_f32 v[88:89], v[14:15], v[88:89], v[80:81]
	v_pk_fma_f32 v[80:81], v[144:145], v[176:177], 0 op_sel_hi:[0,1,0]
	v_pk_fma_f32 v[92:93], v[144:145], v[176:177], 0 op_sel:[1,0,0] op_sel_hi:[1,1,0]
	v_pk_fma_f32 v[80:81], v[146:147], v[180:181], v[80:81] op_sel_hi:[0,1,1]
	v_pk_fma_f32 v[92:93], v[146:147], v[180:181], v[92:93] op_sel:[1,0,0]
	v_lshlrev_b32_e32 v96, 16, v102
	v_and_b32_e32 v97, 0xffff0000, v102
	v_pk_fma_f32 v[80:81], v[148:149], v[96:97], v[80:81] op_sel_hi:[0,1,1]
	v_pk_fma_f32 v[92:93], v[148:149], v[96:97], v[92:93] op_sel:[1,0,0]
	v_lshlrev_b32_e32 v96, 16, v98
	v_and_b32_e32 v97, 0xffff0000, v98
	v_pk_fma_f32 v[80:81], v[150:151], v[96:97], v[80:81] op_sel_hi:[0,1,1]
	v_pk_fma_f32 v[92:93], v[150:151], v[96:97], v[92:93] op_sel:[1,0,0]
	v_lshlrev_b32_e32 v96, 16, v94
	v_and_b32_e32 v97, 0xffff0000, v94
	v_pk_fma_f32 v[80:81], v[152:153], v[96:97], v[80:81] op_sel_hi:[0,1,1]
	v_pk_fma_f32 v[92:93], v[152:153], v[96:97], v[92:93] op_sel:[1,0,0]
	v_lshlrev_b32_e32 v96, 16, v90
	v_and_b32_e32 v97, 0xffff0000, v90
	v_pk_fma_f32 v[80:81], v[154:155], v[96:97], v[80:81] op_sel_hi:[0,1,1]
	v_pk_fma_f32 v[92:93], v[154:155], v[96:97], v[92:93] op_sel:[1,0,0]
	v_lshlrev_b32_e32 v96, 16, v86
	v_and_b32_e32 v97, 0xffff0000, v86
; #define BU_LOAD(buf, ib) do { _Pragma("unroll") for (int h = 0; h < 2; ++h) { const int it = (2 * (ib) + h + k2) & 7, l = 16 * w + 2 * it + rp; \
;             _Pragma("unroll") for (int s2 = 0; s2 < 8; ++s2) c4[buf][h][s2] = *(const GAS u32x4*)(z0 + (size_t)l * 2048 + 256 * s2); } } while (0)
; __device__ __forceinline__ void b_unit(Frame& F, int u, bool dry) {
;     ...
;         BU_LOAD(0, 0);
;         BU_LOAD(1, 1); BU_RED(0, 0);
	v_pk_fma_f32 v[80:81], v[156:157], v[96:97], v[80:81] op_sel_hi:[0,1,1]
	v_pk_fma_f32 v[92:93], v[156:157], v[96:97], v[92:93] op_sel:[1,0,0]
	v_lshlrev_b32_e32 v96, 16, v82
	v_and_b32_e32 v97, 0xffff0000, v82
	v_pk_fma_f32 v[92:93], v[158:159], v[96:97], v[92:93] op_sel:[1,0,0]
	v_lshlrev_b32_e32 v134, 16, v135
	v_and_b32_e32 v135, 0xffff0000, v135
	v_pk_fma_f32 v[80:81], v[158:159], v[96:97], v[80:81] op_sel_hi:[0,1,1]
	v_pk_mul_f32 v[96:97], v[6:7], v[92:93]
	v_pk_mul_f32 v[92:93], v[12:13], v[92:93]
	v_lshlrev_b32_e32 v130, 16, v131
	v_and_b32_e32 v131, 0xffff0000, v131
	v_pk_fma_f32 v[96:97], v[12:13], v[80:81], v[96:97] neg_lo:[0,0,1] neg_hi:[0,0,1]
	v_pk_fma_f32 v[92:93], v[6:7], v[80:81], v[92:93]
	v_pk_fma_f32 v[80:81], v[144:145], v[134:135], 0 op_sel_hi:[0,1,0]
	v_pk_fma_f32 v[100:101], v[144:145], v[134:135], 0 op_sel:[1,0,0] op_sel_hi:[1,1,0]
	v_pk_fma_f32 v[80:81], v[146:147], v[130:131], v[80:81] op_sel_hi:[0,1,1]
	v_pk_fma_f32 v[100:101], v[146:147], v[130:131], v[100:101] op_sel:[1,0,0]
	v_lshlrev_b32_e32 v102, 16, v103
	v_and_b32_e32 v103, 0xffff0000, v103
	v_pk_fma_f32 v[80:81], v[148:149], v[102:103], v[80:81] op_sel_hi:[0,1,1]
	v_pk_fma_f32 v[100:101], v[148:149], v[102:103], v[100:101] op_sel:[1,0,0]
	v_lshlrev_b32_e32 v98, 16, v99
	v_and_b32_e32 v99, 0xffff0000, v99
	v_pk_fma_f32 v[80:81], v[150:151], v[98:99], v[80:81] op_sel_hi:[0,1,1]
	v_pk_fma_f32 v[98:99], v[150:151], v[98:99], v[100:101] op_sel:[1,0,0]
	v_lshlrev_b32_e32 v94, 16, v95
	v_and_b32_e32 v95, 0xffff0000, v95
	v_pk_fma_f32 v[80:81], v[152:153], v[94:95], v[80:81] op_sel_hi:[0,1,1]
	v_pk_fma_f32 v[94:95], v[152:153], v[94:95], v[98:99] op_sel:[1,0,0]
	v_lshlrev_b32_e32 v90, 16, v91
	v_and_b32_e32 v91, 0xffff0000, v91
	v_pk_fma_f32 v[80:81], v[154:155], v[90:91], v[80:81] op_sel_hi:[0,1,1]
	v_pk_fma_f32 v[90:91], v[154:155], v[90:91], v[94:95] op_sel:[1,0,0]
	v_lshlrev_b32_e32 v86, 16, v87
	v_and_b32_e32 v87, 0xffff0000, v87
	v_pk_fma_f32 v[80:81], v[156:157], v[86:87], v[80:81] op_sel_hi:[0,1,1]
	v_pk_fma_f32 v[86:87], v[156:157], v[86:87], v[90:91] op_sel:[1,0,0]
	v_lshlrev_b32_e32 v82, 16, v83
	v_and_b32_e32 v83, 0xffff0000, v83
	v_readlane_b32 s0, v253, 49
	v_pk_fma_f32 v[80:81], v[158:159], v[82:83], v[80:81] op_sel_hi:[0,1,1]
	v_pk_fma_f32 v[82:83], v[158:159], v[82:83], v[86:87] op_sel:[1,0,0]
	v_or_b32_e32 v0, s0, v172
	v_mov_b32_e32 v1, v193
	v_pk_mul_f32 v[86:87], v[2:3], v[82:83]
	v_lshlrev_b64 v[40:41], 12, v[0:1]
	v_pk_fma_f32 v[86:87], v[4:5], v[80:81], v[86:87] neg_lo:[0,0,1] neg_hi:[0,0,1]
	v_pk_mul_f32 v[82:83], v[4:5], v[82:83]
	v_mul_lo_u32 v1, v166, s6
	v_lshl_add_u64 v[40:41], v[162:163], 0, v[40:41]
	v_pk_fma_f32 v[90:91], v[2:3], v[80:81], v[82:83]
	v_cvt_pk_bf16_f32 v80, v178, v179
	v_cvt_pk_bf16_f32 v81, v84, v85
	v_cvt_pk_bf16_f32 v82, v96, v97
	v_cvt_pk_bf16_f32 v83, v86, v87
	v_add3_u32 v1, 0, v1, v192
	global_load_dwordx4 v[76:79], v[40:41], off sc1
	global_load_dwordx4 v[72:75], v[40:41], off offset:512 sc1
	global_load_dwordx4 v[60:63], v[40:41], off offset:1024 sc1
	global_load_dwordx4 v[56:59], v[40:41], off offset:1536 sc1
	global_load_dwordx4 v[52:55], v[40:41], off offset:2048 sc1
	global_load_dwordx4 v[48:51], v[40:41], off offset:2560 sc1
	global_load_dwordx4 v[44:47], v[40:41], off offset:3072 sc1
	s_nop 0
	global_load_dwordx4 v[40:43], v[40:41], off offset:3584 sc1
	ds_write_b128 v1, v[80:83]
	v_cvt_pk_bf16_f32 v80, v174, v175
	v_cvt_pk_bf16_f32 v81, v88, v89
	v_cvt_pk_bf16_f32 v82, v92, v93
	v_cvt_pk_bf16_f32 v83, v90, v91
	ds_write_b128 v1, v[80:83] offset:512
	v_lshlrev_b32_e32 v80, 16, v68
	v_and_b32_e32 v81, 0xffff0000, v68
	v_lshlrev_b32_e32 v84, 16, v64
	v_and_b32_e32 v85, 0xffff0000, v64
	v_pk_fma_f32 v[88:89], v[144:145], v[80:81], 0 op_sel_hi:[0,1,0]
	v_pk_fma_f32 v[80:81], v[144:145], v[80:81], 0 op_sel:[1,0,0] op_sel_hi:[1,1,0]
	v_pk_fma_f32 v[88:89], v[146:147], v[84:85], v[88:89] op_sel_hi:[0,1,1]
	v_pk_fma_f32 v[80:81], v[146:147], v[84:85], v[80:81] op_sel:[1,0,0]
	v_lshlrev_b32_e32 v84, 16, v36
	v_and_b32_e32 v85, 0xffff0000, v36
	v_pk_fma_f32 v[88:89], v[148:149], v[84:85], v[88:89] op_sel_hi:[0,1,1]
	v_pk_fma_f32 v[80:81], v[148:149], v[84:85], v[80:81] op_sel:[1,0,0]
	v_lshlrev_b32_e32 v84, 16, v32
	v_and_b32_e32 v85, 0xffff0000, v32
	v_pk_fma_f32 v[88:89], v[150:151], v[84:85], v[88:89] op_sel_hi:[0,1,1]
	v_pk_fma_f32 v[80:81], v[150:151], v[84:85], v[80:81] op_sel:[1,0,0]
	v_lshlrev_b32_e32 v84, 16, v28
	v_and_b32_e32 v85, 0xffff0000, v28
	v_pk_fma_f32 v[88:89], v[152:153], v[84:85], v[88:89] op_sel_hi:[0,1,1]
	v_pk_fma_f32 v[80:81], v[152:153], v[84:85], v[80:81] op_sel:[1,0,0]
	v_lshlrev_b32_e32 v84, 16, v24
	v_and_b32_e32 v85, 0xffff0000, v24
	v_pk_fma_f32 v[88:89], v[154:155], v[84:85], v[88:89] op_sel_hi:[0,1,1]
	v_pk_fma_f32 v[80:81], v[154:155], v[84:85], v[80:81] op_sel:[1,0,0]
	v_lshlrev_b32_e32 v84, 16, v20
	v_and_b32_e32 v85, 0xffff0000, v20
	v_pk_fma_f32 v[88:89], v[156:157], v[84:85], v[88:89] op_sel_hi:[0,1,1]
	v_pk_fma_f32 v[80:81], v[156:157], v[84:85], v[80:81] op_sel:[1,0,0]
	v_lshlrev_b32_e32 v84, 16, v16
	v_and_b32_e32 v85, 0xffff0000, v16
	v_pk_fma_f32 v[80:81], v[158:159], v[84:85], v[80:81] op_sel:[1,0,0]
	v_lshlrev_b32_e32 v68, 16, v69
	v_and_b32_e32 v69, 0xffff0000, v69
	v_pk_fma_f32 v[88:89], v[158:159], v[84:85], v[88:89] op_sel_hi:[0,1,1]
	v_pk_mul_f32 v[84:85], v[10:11], v[80:81]
	v_pk_mul_f32 v[80:81], v[160:161], v[80:81]
	v_lshlrev_b32_e32 v64, 16, v65
	v_and_b32_e32 v65, 0xffff0000, v65
	v_pk_fma_f32 v[84:85], v[160:161], v[88:89], v[84:85] neg_lo:[0,0,1] neg_hi:[0,0,1]
	v_pk_fma_f32 v[80:81], v[10:11], v[88:89], v[80:81]
; #define BU_LOAD(buf, ib) do { _Pragma("unroll") for (int h = 0; h < 2; ++h) { const int it = (2 * (ib) + h + k2) & 7, l = 16 * w + 2 * it + rp; \
;             _Pragma("unroll") for (int s2 = 0; s2 < 8; ++s2) c4[buf][h][s2] = *(const GAS u32x4*)(z0 + (size_t)l * 2048 + 256 * s2); } } while (0)
; __device__ __forceinline__ void b_unit(Frame& F, int u, bool dry) {
;     ...
;         BU_LOAD(0, 0);
;         BU_LOAD(1, 1); BU_RED(0, 0);
	v_pk_fma_f32 v[88:89], v[144:145], v[68:69], 0 op_sel_hi:[0,1,0]
	v_pk_fma_f32 v[68:69], v[144:145], v[68:69], 0 op_sel:[1,0,0] op_sel_hi:[1,1,0]
	v_pk_fma_f32 v[88:89], v[146:147], v[64:65], v[88:89] op_sel_hi:[0,1,1]
	v_pk_fma_f32 v[64:65], v[146:147], v[64:65], v[68:69] op_sel:[1,0,0]
	v_lshlrev_b32_e32 v36, 16, v37
	v_and_b32_e32 v37, 0xffff0000, v37
	v_pk_fma_f32 v[68:69], v[148:149], v[36:37], v[88:89] op_sel_hi:[0,1,1]
	v_pk_fma_f32 v[36:37], v[148:149], v[36:37], v[64:65] op_sel:[1,0,0]
	v_lshlrev_b32_e32 v32, 16, v33
	v_and_b32_e32 v33, 0xffff0000, v33
	v_pk_fma_f32 v[64:65], v[150:151], v[32:33], v[68:69] op_sel_hi:[0,1,1]
	v_pk_fma_f32 v[32:33], v[150:151], v[32:33], v[36:37] op_sel:[1,0,0]
	v_lshlrev_b32_e32 v28, 16, v29
	v_and_b32_e32 v29, 0xffff0000, v29
	v_pk_fma_f32 v[36:37], v[152:153], v[28:29], v[64:65] op_sel_hi:[0,1,1]
	v_pk_fma_f32 v[28:29], v[152:153], v[28:29], v[32:33] op_sel:[1,0,0]
	v_lshlrev_b32_e32 v24, 16, v25
	v_and_b32_e32 v25, 0xffff0000, v25
	v_pk_fma_f32 v[32:33], v[154:155], v[24:25], v[36:37] op_sel_hi:[0,1,1]
	v_pk_fma_f32 v[24:25], v[154:155], v[24:25], v[28:29] op_sel:[1,0,0]
	v_lshlrev_b32_e32 v20, 16, v21
	v_and_b32_e32 v21, 0xffff0000, v21
	v_pk_fma_f32 v[28:29], v[156:157], v[20:21], v[32:33] op_sel_hi:[0,1,1]
	v_pk_fma_f32 v[20:21], v[156:157], v[20:21], v[24:25] op_sel:[1,0,0]
	v_lshlrev_b32_e32 v16, 16, v17
	v_and_b32_e32 v17, 0xffff0000, v17
	v_pk_fma_f32 v[24:25], v[158:159], v[16:17], v[28:29] op_sel_hi:[0,1,1]
	v_pk_fma_f32 v[16:17], v[158:159], v[16:17], v[20:21] op_sel:[1,0,0]
	v_lshlrev_b32_e32 v82, 16, v70
	v_and_b32_e32 v83, 0xffff0000, v70
	v_pk_mul_f32 v[20:21], v[14:15], v[16:17]
	v_pk_mul_f32 v[16:17], v[8:9], v[16:17]
	v_lshlrev_b32_e32 v86, 16, v66
	v_and_b32_e32 v87, 0xffff0000, v66
	v_pk_fma_f32 v[20:21], v[8:9], v[24:25], v[20:21] neg_lo:[0,0,1] neg_hi:[0,0,1]
	v_pk_fma_f32 v[24:25], v[14:15], v[24:25], v[16:17]
	v_pk_fma_f32 v[16:17], v[144:145], v[82:83], 0 op_sel_hi:[0,1,0]
	v_pk_fma_f32 v[28:29], v[144:145], v[82:83], 0 op_sel:[1,0,0] op_sel_hi:[1,1,0]
	v_pk_fma_f32 v[16:17], v[146:147], v[86:87], v[16:17] op_sel_hi:[0,1,1]
	v_pk_fma_f32 v[28:29], v[146:147], v[86:87], v[28:29] op_sel:[1,0,0]
	v_lshlrev_b32_e32 v32, 16, v38
	v_and_b32_e32 v33, 0xffff0000, v38
	v_pk_fma_f32 v[16:17], v[148:149], v[32:33], v[16:17] op_sel_hi:[0,1,1]
	v_pk_fma_f32 v[28:29], v[148:149], v[32:33], v[28:29] op_sel:[1,0,0]
	v_lshlrev_b32_e32 v32, 16, v34
	v_and_b32_e32 v33, 0xffff0000, v34
	v_pk_fma_f32 v[16:17], v[150:151], v[32:33], v[16:17] op_sel_hi:[0,1,1]
	v_pk_fma_f32 v[28:29], v[150:151], v[32:33], v[28:29] op_sel:[1,0,0]
	v_lshlrev_b32_e32 v32, 16, v30
	v_and_b32_e32 v33, 0xffff0000, v30
	v_pk_fma_f32 v[16:17], v[152:153], v[32:33], v[16:17] op_sel_hi:[0,1,1]
	v_pk_fma_f32 v[28:29], v[152:153], v[32:33], v[28:29] op_sel:[1,0,0]
	v_lshlrev_b32_e32 v32, 16, v26
	v_and_b32_e32 v33, 0xffff0000, v26
	v_pk_fma_f32 v[16:17], v[154:155], v[32:33], v[16:17] op_sel_hi:[0,1,1]
	v_pk_fma_f32 v[28:29], v[154:155], v[32:33], v[28:29] op_sel:[1,0,0]
	v_lshlrev_b32_e32 v32, 16, v22
	v_and_b32_e32 v33, 0xffff0000, v22
	v_pk_fma_f32 v[16:17], v[156:157], v[32:33], v[16:17] op_sel_hi:[0,1,1]
	v_pk_fma_f32 v[28:29], v[156:157], v[32:33], v[28:29] op_sel:[1,0,0]
	v_lshlrev_b32_e32 v32, 16, v18
	v_and_b32_e32 v33, 0xffff0000, v18
	v_pk_fma_f32 v[28:29], v[158:159], v[32:33], v[28:29] op_sel:[1,0,0]
	v_lshlrev_b32_e32 v70, 16, v71
	v_and_b32_e32 v71, 0xffff0000, v71
	v_pk_fma_f32 v[16:17], v[158:159], v[32:33], v[16:17] op_sel_hi:[0,1,1]
	v_pk_mul_f32 v[32:33], v[6:7], v[28:29]
	v_pk_mul_f32 v[28:29], v[12:13], v[28:29]
	v_lshlrev_b32_e32 v66, 16, v67
	v_and_b32_e32 v67, 0xffff0000, v67
	v_pk_fma_f32 v[32:33], v[12:13], v[16:17], v[32:33] neg_lo:[0,0,1] neg_hi:[0,0,1]
	v_pk_fma_f32 v[28:29], v[6:7], v[16:17], v[28:29]
	v_pk_fma_f32 v[16:17], v[144:145], v[70:71], 0 op_sel_hi:[0,1,0]
	v_pk_fma_f32 v[36:37], v[144:145], v[70:71], 0 op_sel:[1,0,0] op_sel_hi:[1,1,0]
	v_pk_fma_f32 v[16:17], v[146:147], v[66:67], v[16:17] op_sel_hi:[0,1,1]
	v_pk_fma_f32 v[36:37], v[146:147], v[66:67], v[36:37] op_sel:[1,0,0]
	v_lshlrev_b32_e32 v38, 16, v39
	v_and_b32_e32 v39, 0xffff0000, v39
	v_pk_fma_f32 v[16:17], v[148:149], v[38:39], v[16:17] op_sel_hi:[0,1,1]
	v_pk_fma_f32 v[36:37], v[148:149], v[38:39], v[36:37] op_sel:[1,0,0]
	v_lshlrev_b32_e32 v34, 16, v35
	v_and_b32_e32 v35, 0xffff0000, v35
	v_pk_fma_f32 v[16:17], v[150:151], v[34:35], v[16:17] op_sel_hi:[0,1,1]
	v_pk_fma_f32 v[34:35], v[150:151], v[34:35], v[36:37] op_sel:[1,0,0]
	v_lshlrev_b32_e32 v30, 16, v31
	v_and_b32_e32 v31, 0xffff0000, v31
	v_pk_fma_f32 v[16:17], v[152:153], v[30:31], v[16:17] op_sel_hi:[0,1,1]
	v_pk_fma_f32 v[30:31], v[152:153], v[30:31], v[34:35] op_sel:[1,0,0]
	v_lshlrev_b32_e32 v26, 16, v27
	v_and_b32_e32 v27, 0xffff0000, v27
	v_pk_fma_f32 v[16:17], v[154:155], v[26:27], v[16:17] op_sel_hi:[0,1,1]
	v_pk_fma_f32 v[26:27], v[154:155], v[26:27], v[30:31] op_sel:[1,0,0]
	v_lshlrev_b32_e32 v22, 16, v23
	v_and_b32_e32 v23, 0xffff0000, v23
	v_pk_fma_f32 v[16:17], v[156:157], v[22:23], v[16:17] op_sel_hi:[0,1,1]
	v_pk_fma_f32 v[22:23], v[156:157], v[22:23], v[26:27] op_sel:[1,0,0]
	v_lshlrev_b32_e32 v18, 16, v19
	v_and_b32_e32 v19, 0xffff0000, v19
	v_pk_fma_f32 v[16:17], v[158:159], v[18:19], v[16:17] op_sel_hi:[0,1,1]
	v_pk_fma_f32 v[18:19], v[158:159], v[18:19], v[22:23] op_sel:[1,0,0]
	v_mul_lo_u32 v1, v164, s6
	v_pk_mul_f32 v[22:23], v[2:3], v[18:19]
	v_pk_mul_f32 v[18:19], v[4:5], v[18:19]
	v_pk_fma_f32 v[22:23], v[4:5], v[16:17], v[22:23] neg_lo:[0,0,1] neg_hi:[0,0,1]
	v_pk_fma_f32 v[26:27], v[2:3], v[16:17], v[18:19]
	v_cvt_pk_bf16_f32 v16, v84, v85
	v_cvt_pk_bf16_f32 v17, v20, v21
	v_cvt_pk_bf16_f32 v18, v32, v33
	v_cvt_pk_bf16_f32 v19, v22, v23
	v_add3_u32 v1, 0, v1, v192
	v_readlane_b32 s0, v253, 50
	ds_write_b128 v1, v[16:19]
	v_cvt_pk_bf16_f32 v16, v80, v81
	v_cvt_pk_bf16_f32 v17, v24, v25
	v_cvt_pk_bf16_f32 v18, v28, v29
	v_cvt_pk_bf16_f32 v19, v26, v27
	v_or_b32_e32 v166, s0, v172
	ds_write_b128 v1, v[16:19] offset:512
	v_lshlrev_b64 v[16:17], 12, v[166:167]
	v_readlane_b32 s0, v253, 52
	v_lshl_add_u64 v[16:17], v[162:163], 0, v[16:17]
	global_load_dwordx4 v[132:135], v[16:17], off sc1
	global_load_dwordx4 v[128:131], v[16:17], off offset:512 sc1
	global_load_dwordx4 v[100:103], v[16:17], off offset:1024 sc1
	global_load_dwordx4 v[96:99], v[16:17], off offset:1536 sc1
	global_load_dwordx4 v[92:95], v[16:17], off offset:2048 sc1
	global_load_dwordx4 v[88:91], v[16:17], off offset:2560 sc1
	global_load_dwordx4 v[84:87], v[16:17], off offset:3072 sc1
	global_load_dwordx4 v[80:83], v[16:17], off offset:3584 sc1
	v_or_b32_e32 v164, s0, v172
	v_lshlrev_b64 v[16:17], 12, v[164:165]
	v_lshl_add_u64 v[16:17], v[162:163], 0, v[16:17]
	s_waitcnt vmcnt(23)
; #define BU_LOAD(buf, ib) do { _Pragma("unroll") for (int h = 0; h < 2; ++h) { const int it = (2 * (ib) + h + k2) & 7, l = 16 * w + 2 * it + rp; \
;             _Pragma("unroll") for (int s2 = 0; s2 < 8; ++s2) c4[buf][h][s2] = *(const GAS u32x4*)(z0 + (size_t)l * 2048 + 256 * s2); } } while (0)
; __device__ __forceinline__ void b_unit(Frame& F, int u, bool dry) {
;     ...
;         BU_LOAD(0, 0);
;         BU_LOAD(1, 1); BU_RED(0, 0);
;         BU_LOAD(0, 2); BU_RED(1, 1);
;         BU_LOAD(1, 3); BU_RED(0, 2);
	v_lshlrev_b32_e32 v162, 16, v140
	v_and_b32_e32 v163, 0xffff0000, v140
	s_waitcnt vmcnt(22)
	v_lshlrev_b32_e32 v174, 16, v136
	v_and_b32_e32 v175, 0xffff0000, v136
	v_pk_fma_f32 v[178:179], v[144:145], v[162:163], 0 op_sel_hi:[0,1,0]
	v_pk_fma_f32 v[162:163], v[144:145], v[162:163], 0 op_sel:[1,0,0] op_sel_hi:[1,1,0]
	v_pk_fma_f32 v[178:179], v[146:147], v[174:175], v[178:179] op_sel_hi:[0,1,1]
	v_pk_fma_f32 v[162:163], v[146:147], v[174:175], v[162:163] op_sel:[1,0,0]
	s_waitcnt vmcnt(21)
	v_lshlrev_b32_e32 v174, 16, v124
	v_and_b32_e32 v175, 0xffff0000, v124
	v_pk_fma_f32 v[178:179], v[148:149], v[174:175], v[178:179] op_sel_hi:[0,1,1]
	v_pk_fma_f32 v[162:163], v[148:149], v[174:175], v[162:163] op_sel:[1,0,0]
	s_waitcnt vmcnt(20)
	v_lshlrev_b32_e32 v174, 16, v120
	v_and_b32_e32 v175, 0xffff0000, v120
	v_pk_fma_f32 v[178:179], v[150:151], v[174:175], v[178:179] op_sel_hi:[0,1,1]
	v_pk_fma_f32 v[162:163], v[150:151], v[174:175], v[162:163] op_sel:[1,0,0]
	s_waitcnt vmcnt(19)
	v_lshlrev_b32_e32 v174, 16, v116
	v_and_b32_e32 v175, 0xffff0000, v116
	v_pk_fma_f32 v[178:179], v[152:153], v[174:175], v[178:179] op_sel_hi:[0,1,1]
	v_pk_fma_f32 v[162:163], v[152:153], v[174:175], v[162:163] op_sel:[1,0,0]
	s_waitcnt vmcnt(18)
	v_lshlrev_b32_e32 v174, 16, v112
	v_and_b32_e32 v175, 0xffff0000, v112
	v_pk_fma_f32 v[178:179], v[154:155], v[174:175], v[178:179] op_sel_hi:[0,1,1]
	v_pk_fma_f32 v[162:163], v[154:155], v[174:175], v[162:163] op_sel:[1,0,0]
	s_waitcnt vmcnt(17)
	v_lshlrev_b32_e32 v174, 16, v108
	v_and_b32_e32 v175, 0xffff0000, v108
	v_pk_fma_f32 v[178:179], v[156:157], v[174:175], v[178:179] op_sel_hi:[0,1,1]
	v_pk_fma_f32 v[162:163], v[156:157], v[174:175], v[162:163] op_sel:[1,0,0]
	s_waitcnt vmcnt(16)
	v_lshlrev_b32_e32 v174, 16, v104
	v_and_b32_e32 v175, 0xffff0000, v104
	v_pk_fma_f32 v[162:163], v[158:159], v[174:175], v[162:163] op_sel:[1,0,0]
	v_lshlrev_b32_e32 v140, 16, v141
	v_and_b32_e32 v141, 0xffff0000, v141
	v_pk_fma_f32 v[178:179], v[158:159], v[174:175], v[178:179] op_sel_hi:[0,1,1]
	v_pk_mul_f32 v[174:175], v[10:11], v[162:163]
	v_pk_mul_f32 v[162:163], v[160:161], v[162:163]
	v_lshlrev_b32_e32 v136, 16, v137
	v_and_b32_e32 v137, 0xffff0000, v137
	v_pk_fma_f32 v[174:175], v[160:161], v[178:179], v[174:175] neg_lo:[0,0,1] neg_hi:[0,0,1]
	v_pk_fma_f32 v[162:163], v[10:11], v[178:179], v[162:163]
	v_pk_fma_f32 v[178:179], v[144:145], v[140:141], 0 op_sel_hi:[0,1,0]
	v_pk_fma_f32 v[140:141], v[144:145], v[140:141], 0 op_sel:[1,0,0] op_sel_hi:[1,1,0]
	v_pk_fma_f32 v[178:179], v[146:147], v[136:137], v[178:179] op_sel_hi:[0,1,1]
	v_pk_fma_f32 v[136:137], v[146:147], v[136:137], v[140:141] op_sel:[1,0,0]
	v_lshlrev_b32_e32 v124, 16, v125
	v_and_b32_e32 v125, 0xffff0000, v125
	v_pk_fma_f32 v[140:141], v[148:149], v[124:125], v[178:179] op_sel_hi:[0,1,1]
	v_pk_fma_f32 v[124:125], v[148:149], v[124:125], v[136:137] op_sel:[1,0,0]
	v_lshlrev_b32_e32 v120, 16, v121
	v_and_b32_e32 v121, 0xffff0000, v121
	v_pk_fma_f32 v[136:137], v[150:151], v[120:121], v[140:141] op_sel_hi:[0,1,1]
	v_pk_fma_f32 v[120:121], v[150:151], v[120:121], v[124:125] op_sel:[1,0,0]
	v_lshlrev_b32_e32 v116, 16, v117
	v_and_b32_e32 v117, 0xffff0000, v117
	v_pk_fma_f32 v[124:125], v[152:153], v[116:117], v[136:137] op_sel_hi:[0,1,1]
	v_pk_fma_f32 v[116:117], v[152:153], v[116:117], v[120:121] op_sel:[1,0,0]
	v_lshlrev_b32_e32 v112, 16, v113
	v_and_b32_e32 v113, 0xffff0000, v113
	v_pk_fma_f32 v[120:121], v[154:155], v[112:113], v[124:125] op_sel_hi:[0,1,1]
	v_pk_fma_f32 v[112:113], v[154:155], v[112:113], v[116:117] op_sel:[1,0,0]
	v_lshlrev_b32_e32 v108, 16, v109
	v_and_b32_e32 v109, 0xffff0000, v109
	v_pk_fma_f32 v[116:117], v[156:157], v[108:109], v[120:121] op_sel_hi:[0,1,1]
	v_pk_fma_f32 v[108:109], v[156:157], v[108:109], v[112:113] op_sel:[1,0,0]
	v_lshlrev_b32_e32 v104, 16, v105
	v_and_b32_e32 v105, 0xffff0000, v105
	v_pk_fma_f32 v[112:113], v[158:159], v[104:105], v[116:117] op_sel_hi:[0,1,1]
	v_pk_fma_f32 v[104:105], v[158:159], v[104:105], v[108:109] op_sel:[1,0,0]
	v_lshlrev_b32_e32 v172, 16, v142
	v_and_b32_e32 v173, 0xffff0000, v142
	v_pk_mul_f32 v[108:109], v[14:15], v[104:105]
	v_pk_mul_f32 v[104:105], v[8:9], v[104:105]
	v_lshlrev_b32_e32 v176, 16, v138
	v_and_b32_e32 v177, 0xffff0000, v138
	v_pk_fma_f32 v[108:109], v[8:9], v[112:113], v[108:109] neg_lo:[0,0,1] neg_hi:[0,0,1]
	v_pk_fma_f32 v[112:113], v[14:15], v[112:113], v[104:105]
	v_pk_fma_f32 v[104:105], v[144:145], v[172:173], 0 op_sel_hi:[0,1,0]
	v_pk_fma_f32 v[116:117], v[144:145], v[172:173], 0 op_sel:[1,0,0] op_sel_hi:[1,1,0]
	v_pk_fma_f32 v[104:105], v[146:147], v[176:177], v[104:105] op_sel_hi:[0,1,1]
	v_pk_fma_f32 v[116:117], v[146:147], v[176:177], v[116:117] op_sel:[1,0,0]
	v_lshlrev_b32_e32 v120, 16, v126
	v_and_b32_e32 v121, 0xffff0000, v126
	v_pk_fma_f32 v[104:105], v[148:149], v[120:121], v[104:105] op_sel_hi:[0,1,1]
	v_pk_fma_f32 v[116:117], v[148:149], v[120:121], v[116:117] op_sel:[1,0,0]
	v_lshlrev_b32_e32 v120, 16, v122
	v_and_b32_e32 v121, 0xffff0000, v122
	v_pk_fma_f32 v[104:105], v[150:151], v[120:121], v[104:105] op_sel_hi:[0,1,1]
	v_pk_fma_f32 v[116:117], v[150:151], v[120:121], v[116:117] op_sel:[1,0,0]
	v_lshlrev_b32_e32 v120, 16, v118
	v_and_b32_e32 v121, 0xffff0000, v118
	v_pk_fma_f32 v[104:105], v[152:153], v[120:121], v[104:105] op_sel_hi:[0,1,1]
	v_pk_fma_f32 v[116:117], v[152:153], v[120:121], v[116:117] op_sel:[1,0,0]
	v_lshlrev_b32_e32 v120, 16, v114
	v_and_b32_e32 v121, 0xffff0000, v114
	v_pk_fma_f32 v[104:105], v[154:155], v[120:121], v[104:105] op_sel_hi:[0,1,1]
	v_pk_fma_f32 v[116:117], v[154:155], v[120:121], v[116:117] op_sel:[1,0,0]
; #define BU_LOAD(buf, ib) do { _Pragma("unroll") for (int h = 0; h < 2; ++h) { const int it = (2 * (ib) + h + k2) & 7, l = 16 * w + 2 * it + rp; \
;             _Pragma("unroll") for (int s2 = 0; s2 < 8; ++s2) c4[buf][h][s2] = *(const GAS u32x4*)(z0 + (size_t)l * 2048 + 256 * s2); } } while (0)
; __device__ __forceinline__ void b_unit(Frame& F, int u, bool dry) {
;     ...
;         BU_LOAD(0, 0);
;         BU_LOAD(1, 1); BU_RED(0, 0);
;         BU_LOAD(0, 2); BU_RED(1, 1);
;         BU_LOAD(1, 3); BU_RED(0, 2);
	v_lshlrev_b32_e32 v120, 16, v110
	v_and_b32_e32 v121, 0xffff0000, v110
	v_pk_fma_f32 v[104:105], v[156:157], v[120:121], v[104:105] op_sel_hi:[0,1,1]
	v_pk_fma_f32 v[116:117], v[156:157], v[120:121], v[116:117] op_sel:[1,0,0]
	v_lshlrev_b32_e32 v120, 16, v106
	v_and_b32_e32 v121, 0xffff0000, v106
	v_pk_fma_f32 v[116:117], v[158:159], v[120:121], v[116:117] op_sel:[1,0,0]
	v_lshlrev_b32_e32 v142, 16, v143
	v_and_b32_e32 v143, 0xffff0000, v143
	v_pk_fma_f32 v[104:105], v[158:159], v[120:121], v[104:105] op_sel_hi:[0,1,1]
	v_pk_mul_f32 v[120:121], v[6:7], v[116:117]
	v_pk_mul_f32 v[116:117], v[12:13], v[116:117]
	v_lshlrev_b32_e32 v138, 16, v139
	v_and_b32_e32 v139, 0xffff0000, v139
	v_pk_fma_f32 v[120:121], v[12:13], v[104:105], v[120:121] neg_lo:[0,0,1] neg_hi:[0,0,1]
	v_pk_fma_f32 v[116:117], v[6:7], v[104:105], v[116:117]
	v_pk_fma_f32 v[104:105], v[144:145], v[142:143], 0 op_sel_hi:[0,1,0]
	v_pk_fma_f32 v[124:125], v[144:145], v[142:143], 0 op_sel:[1,0,0] op_sel_hi:[1,1,0]
	v_pk_fma_f32 v[104:105], v[146:147], v[138:139], v[104:105] op_sel_hi:[0,1,1]
	v_pk_fma_f32 v[124:125], v[146:147], v[138:139], v[124:125] op_sel:[1,0,0]
	v_lshlrev_b32_e32 v126, 16, v127
	v_and_b32_e32 v127, 0xffff0000, v127
	v_pk_fma_f32 v[104:105], v[148:149], v[126:127], v[104:105] op_sel_hi:[0,1,1]
	v_pk_fma_f32 v[124:125], v[148:149], v[126:127], v[124:125] op_sel:[1,0,0]
	v_lshlrev_b32_e32 v122, 16, v123
	v_and_b32_e32 v123, 0xffff0000, v123
	v_pk_fma_f32 v[104:105], v[150:151], v[122:123], v[104:105] op_sel_hi:[0,1,1]
	v_pk_fma_f32 v[122:123], v[150:151], v[122:123], v[124:125] op_sel:[1,0,0]
	v_lshlrev_b32_e32 v118, 16, v119
	v_and_b32_e32 v119, 0xffff0000, v119
	v_pk_fma_f32 v[104:105], v[152:153], v[118:119], v[104:105] op_sel_hi:[0,1,1]
	v_pk_fma_f32 v[118:119], v[152:153], v[118:119], v[122:123] op_sel:[1,0,0]
	v_lshlrev_b32_e32 v114, 16, v115
	v_and_b32_e32 v115, 0xffff0000, v115
	v_pk_fma_f32 v[104:105], v[154:155], v[114:115], v[104:105] op_sel_hi:[0,1,1]
	v_pk_fma_f32 v[114:115], v[154:155], v[114:115], v[118:119] op_sel:[1,0,0]
	v_lshlrev_b32_e32 v110, 16, v111
	v_and_b32_e32 v111, 0xffff0000, v111
	v_pk_fma_f32 v[104:105], v[156:157], v[110:111], v[104:105] op_sel_hi:[0,1,1]
	v_pk_fma_f32 v[110:111], v[156:157], v[110:111], v[114:115] op_sel:[1,0,0]
	v_lshlrev_b32_e32 v106, 16, v107
	v_and_b32_e32 v107, 0xffff0000, v107
	v_pk_fma_f32 v[104:105], v[158:159], v[106:107], v[104:105] op_sel_hi:[0,1,1]
	v_pk_fma_f32 v[106:107], v[158:159], v[106:107], v[110:111] op_sel:[1,0,0]
	v_mul_lo_u32 v1, v168, s6
	v_pk_mul_f32 v[110:111], v[2:3], v[106:107]
	v_pk_mul_f32 v[106:107], v[4:5], v[106:107]
	v_pk_fma_f32 v[110:111], v[4:5], v[104:105], v[110:111] neg_lo:[0,0,1] neg_hi:[0,0,1]
	v_pk_fma_f32 v[114:115], v[2:3], v[104:105], v[106:107]
	v_cvt_pk_bf16_f32 v104, v174, v175
	v_cvt_pk_bf16_f32 v105, v108, v109
	v_cvt_pk_bf16_f32 v106, v120, v121
	v_cvt_pk_bf16_f32 v107, v110, v111
	v_add3_u32 v1, 0, v1, v192
	global_load_dwordx4 v[68:71], v[16:17], off sc1
	global_load_dwordx4 v[64:67], v[16:17], off offset:512 sc1
	global_load_dwordx4 v[36:39], v[16:17], off offset:1024 sc1
	global_load_dwordx4 v[32:35], v[16:17], off offset:1536 sc1
	global_load_dwordx4 v[28:31], v[16:17], off offset:2048 sc1
	global_load_dwordx4 v[24:27], v[16:17], off offset:2560 sc1
	global_load_dwordx4 v[20:23], v[16:17], off offset:3072 sc1
	s_nop 0
	global_load_dwordx4 v[16:19], v[16:17], off offset:3584 sc1
	ds_write_b128 v1, v[104:107]
	v_cvt_pk_bf16_f32 v104, v162, v163
	v_cvt_pk_bf16_f32 v105, v112, v113
	v_cvt_pk_bf16_f32 v106, v116, v117
	v_cvt_pk_bf16_f32 v107, v114, v115
	ds_write_b128 v1, v[104:107] offset:512
	s_waitcnt vmcnt(23)
	v_lshlrev_b32_e32 v104, 16, v76
	v_and_b32_e32 v105, 0xffff0000, v76
	s_waitcnt vmcnt(22)
	v_lshlrev_b32_e32 v108, 16, v72
	v_and_b32_e32 v109, 0xffff0000, v72
	v_pk_fma_f32 v[112:113], v[144:145], v[104:105], 0 op_sel_hi:[0,1,0]
	v_pk_fma_f32 v[104:105], v[144:145], v[104:105], 0 op_sel:[1,0,0] op_sel_hi:[1,1,0]
	v_pk_fma_f32 v[112:113], v[146:147], v[108:109], v[112:113] op_sel_hi:[0,1,1]
	v_pk_fma_f32 v[104:105], v[146:147], v[108:109], v[104:105] op_sel:[1,0,0]
	s_waitcnt vmcnt(21)
	v_lshlrev_b32_e32 v108, 16, v60
	v_and_b32_e32 v109, 0xffff0000, v60
	v_pk_fma_f32 v[112:113], v[148:149], v[108:109], v[112:113] op_sel_hi:[0,1,1]
	v_pk_fma_f32 v[104:105], v[148:149], v[108:109], v[104:105] op_sel:[1,0,0]
	s_waitcnt vmcnt(20)
	v_lshlrev_b32_e32 v108, 16, v56
	v_and_b32_e32 v109, 0xffff0000, v56
	v_pk_fma_f32 v[112:113], v[150:151], v[108:109], v[112:113] op_sel_hi:[0,1,1]
	v_pk_fma_f32 v[104:105], v[150:151], v[108:109], v[104:105] op_sel:[1,0,0]
	s_waitcnt vmcnt(19)
	v_lshlrev_b32_e32 v108, 16, v52
	v_and_b32_e32 v109, 0xffff0000, v52
	v_pk_fma_f32 v[112:113], v[152:153], v[108:109], v[112:113] op_sel_hi:[0,1,1]
	v_pk_fma_f32 v[104:105], v[152:153], v[108:109], v[104:105] op_sel:[1,0,0]
	s_waitcnt vmcnt(18)
	v_lshlrev_b32_e32 v108, 16, v48
	v_and_b32_e32 v109, 0xffff0000, v48
	v_pk_fma_f32 v[112:113], v[154:155], v[108:109], v[112:113] op_sel_hi:[0,1,1]
	v_pk_fma_f32 v[104:105], v[154:155], v[108:109], v[104:105] op_sel:[1,0,0]
	s_waitcnt vmcnt(17)
	v_lshlrev_b32_e32 v108, 16, v44
	v_and_b32_e32 v109, 0xffff0000, v44
	v_pk_fma_f32 v[112:113], v[156:157], v[108:109], v[112:113] op_sel_hi:[0,1,1]
	v_pk_fma_f32 v[104:105], v[156:157], v[108:109], v[104:105] op_sel:[1,0,0]
	s_waitcnt vmcnt(16)
; #define BU_LOAD(buf, ib) do { _Pragma("unroll") for (int h = 0; h < 2; ++h) { const int it = (2 * (ib) + h + k2) & 7, l = 16 * w + 2 * it + rp; \
;             _Pragma("unroll") for (int s2 = 0; s2 < 8; ++s2) c4[buf][h][s2] = *(const GAS u32x4*)(z0 + (size_t)l * 2048 + 256 * s2); } } while (0)
; __device__ __forceinline__ void b_unit(Frame& F, int u, bool dry) {
;     ...
;         BU_LOAD(0, 0);
;         BU_LOAD(1, 1); BU_RED(0, 0);
;         BU_LOAD(0, 2); BU_RED(1, 1);
;         BU_LOAD(1, 3); BU_RED(0, 2);
	v_lshlrev_b32_e32 v108, 16, v40
	v_and_b32_e32 v109, 0xffff0000, v40
	v_pk_fma_f32 v[104:105], v[158:159], v[108:109], v[104:105] op_sel:[1,0,0]
	v_lshlrev_b32_e32 v76, 16, v77
	v_and_b32_e32 v77, 0xffff0000, v77
	v_pk_fma_f32 v[112:113], v[158:159], v[108:109], v[112:113] op_sel_hi:[0,1,1]
	v_pk_mul_f32 v[108:109], v[10:11], v[104:105]
	v_pk_mul_f32 v[104:105], v[160:161], v[104:105]
	v_lshlrev_b32_e32 v72, 16, v73
	v_and_b32_e32 v73, 0xffff0000, v73
	v_pk_fma_f32 v[108:109], v[160:161], v[112:113], v[108:109] neg_lo:[0,0,1] neg_hi:[0,0,1]
	v_pk_fma_f32 v[104:105], v[10:11], v[112:113], v[104:105]
	v_pk_fma_f32 v[112:113], v[144:145], v[76:77], 0 op_sel_hi:[0,1,0]
	v_pk_fma_f32 v[76:77], v[144:145], v[76:77], 0 op_sel:[1,0,0] op_sel_hi:[1,1,0]
	v_pk_fma_f32 v[112:113], v[146:147], v[72:73], v[112:113] op_sel_hi:[0,1,1]
	v_pk_fma_f32 v[72:73], v[146:147], v[72:73], v[76:77] op_sel:[1,0,0]
	v_lshlrev_b32_e32 v60, 16, v61
	v_and_b32_e32 v61, 0xffff0000, v61
	v_pk_fma_f32 v[76:77], v[148:149], v[60:61], v[112:113] op_sel_hi:[0,1,1]
	v_pk_fma_f32 v[60:61], v[148:149], v[60:61], v[72:73] op_sel:[1,0,0]
	v_lshlrev_b32_e32 v56, 16, v57
	v_and_b32_e32 v57, 0xffff0000, v57
	v_pk_fma_f32 v[72:73], v[150:151], v[56:57], v[76:77] op_sel_hi:[0,1,1]
	v_pk_fma_f32 v[56:57], v[150:151], v[56:57], v[60:61] op_sel:[1,0,0]
	v_lshlrev_b32_e32 v52, 16, v53
	v_and_b32_e32 v53, 0xffff0000, v53
	v_pk_fma_f32 v[60:61], v[152:153], v[52:53], v[72:73] op_sel_hi:[0,1,1]
	v_pk_fma_f32 v[52:53], v[152:153], v[52:53], v[56:57] op_sel:[1,0,0]
	v_lshlrev_b32_e32 v48, 16, v49
	v_and_b32_e32 v49, 0xffff0000, v49
	v_pk_fma_f32 v[56:57], v[154:155], v[48:49], v[60:61] op_sel_hi:[0,1,1]
	v_pk_fma_f32 v[48:49], v[154:155], v[48:49], v[52:53] op_sel:[1,0,0]
	v_lshlrev_b32_e32 v44, 16, v45
	v_and_b32_e32 v45, 0xffff0000, v45
	v_pk_fma_f32 v[52:53], v[156:157], v[44:45], v[56:57] op_sel_hi:[0,1,1]
	v_pk_fma_f32 v[44:45], v[156:157], v[44:45], v[48:49] op_sel:[1,0,0]
	v_lshlrev_b32_e32 v40, 16, v41
	v_and_b32_e32 v41, 0xffff0000, v41
	v_pk_fma_f32 v[48:49], v[158:159], v[40:41], v[52:53] op_sel_hi:[0,1,1]
	v_pk_fma_f32 v[40:41], v[158:159], v[40:41], v[44:45] op_sel:[1,0,0]
	v_lshlrev_b32_e32 v106, 16, v78
	v_and_b32_e32 v107, 0xffff0000, v78
	v_pk_mul_f32 v[44:45], v[14:15], v[40:41]
	v_pk_mul_f32 v[40:41], v[8:9], v[40:41]
	v_lshlrev_b32_e32 v110, 16, v74
	v_and_b32_e32 v111, 0xffff0000, v74
	v_pk_fma_f32 v[44:45], v[8:9], v[48:49], v[44:45] neg_lo:[0,0,1] neg_hi:[0,0,1]
	v_pk_fma_f32 v[48:49], v[14:15], v[48:49], v[40:41]
	v_pk_fma_f32 v[40:41], v[144:145], v[106:107], 0 op_sel_hi:[0,1,0]
	v_pk_fma_f32 v[52:53], v[144:145], v[106:107], 0 op_sel:[1,0,0] op_sel_hi:[1,1,0]
	v_pk_fma_f32 v[40:41], v[146:147], v[110:111], v[40:41] op_sel_hi:[0,1,1]
	v_pk_fma_f32 v[52:53], v[146:147], v[110:111], v[52:53] op_sel:[1,0,0]
	v_lshlrev_b32_e32 v56, 16, v62
	v_and_b32_e32 v57, 0xffff0000, v62
	v_pk_fma_f32 v[40:41], v[148:149], v[56:57], v[40:41] op_sel_hi:[0,1,1]
	v_pk_fma_f32 v[52:53], v[148:149], v[56:57], v[52:53] op_sel:[1,0,0]
	v_lshlrev_b32_e32 v56, 16, v58
	v_and_b32_e32 v57, 0xffff0000, v58
	v_pk_fma_f32 v[40:41], v[150:151], v[56:57], v[40:41] op_sel_hi:[0,1,1]
	v_pk_fma_f32 v[52:53], v[150:151], v[56:57], v[52:53] op_sel:[1,0,0]
	v_lshlrev_b32_e32 v56, 16, v54
	v_and_b32_e32 v57, 0xffff0000, v54
	v_pk_fma_f32 v[40:41], v[152:153], v[56:57], v[40:41] op_sel_hi:[0,1,1]
	v_pk_fma_f32 v[52:53], v[152:153], v[56:57], v[52:53] op_sel:[1,0,0]
	v_lshlrev_b32_e32 v56, 16, v50
	v_and_b32_e32 v57, 0xffff0000, v50
	v_pk_fma_f32 v[40:41], v[154:155], v[56:57], v[40:41] op_sel_hi:[0,1,1]
	v_pk_fma_f32 v[52:53], v[154:155], v[56:57], v[52:53] op_sel:[1,0,0]
	v_lshlrev_b32_e32 v56, 16, v46
	v_and_b32_e32 v57, 0xffff0000, v46
	v_pk_fma_f32 v[40:41], v[156:157], v[56:57], v[40:41] op_sel_hi:[0,1,1]
	v_pk_fma_f32 v[52:53], v[156:157], v[56:57], v[52:53] op_sel:[1,0,0]
	v_lshlrev_b32_e32 v56, 16, v42
	v_and_b32_e32 v57, 0xffff0000, v42
	v_pk_fma_f32 v[52:53], v[158:159], v[56:57], v[52:53] op_sel:[1,0,0]
	v_lshlrev_b32_e32 v78, 16, v79
	v_and_b32_e32 v79, 0xffff0000, v79
	v_pk_fma_f32 v[40:41], v[158:159], v[56:57], v[40:41] op_sel_hi:[0,1,1]
	v_pk_mul_f32 v[56:57], v[6:7], v[52:53]
	v_pk_mul_f32 v[52:53], v[12:13], v[52:53]
	v_lshlrev_b32_e32 v74, 16, v75
	v_and_b32_e32 v75, 0xffff0000, v75
	v_pk_fma_f32 v[56:57], v[12:13], v[40:41], v[56:57] neg_lo:[0,0,1] neg_hi:[0,0,1]
	v_pk_fma_f32 v[52:53], v[6:7], v[40:41], v[52:53]
	v_pk_fma_f32 v[40:41], v[144:145], v[78:79], 0 op_sel_hi:[0,1,0]
	v_pk_fma_f32 v[60:61], v[144:145], v[78:79], 0 op_sel:[1,0,0] op_sel_hi:[1,1,0]
	v_pk_fma_f32 v[40:41], v[146:147], v[74:75], v[40:41] op_sel_hi:[0,1,1]
	v_pk_fma_f32 v[60:61], v[146:147], v[74:75], v[60:61] op_sel:[1,0,0]
	v_lshlrev_b32_e32 v62, 16, v63
	v_and_b32_e32 v63, 0xffff0000, v63
	v_pk_fma_f32 v[40:41], v[148:149], v[62:63], v[40:41] op_sel_hi:[0,1,1]
	v_pk_fma_f32 v[60:61], v[148:149], v[62:63], v[60:61] op_sel:[1,0,0]
	v_lshlrev_b32_e32 v58, 16, v59
	v_and_b32_e32 v59, 0xffff0000, v59
	v_pk_fma_f32 v[40:41], v[150:151], v[58:59], v[40:41] op_sel_hi:[0,1,1]
	v_pk_fma_f32 v[58:59], v[150:151], v[58:59], v[60:61] op_sel:[1,0,0]
	v_lshlrev_b32_e32 v54, 16, v55
	v_and_b32_e32 v55, 0xffff0000, v55
	v_pk_fma_f32 v[40:41], v[152:153], v[54:55], v[40:41] op_sel_hi:[0,1,1]
	v_pk_fma_f32 v[54:55], v[152:153], v[54:55], v[58:59] op_sel:[1,0,0]
	v_lshlrev_b32_e32 v50, 16, v51
	v_and_b32_e32 v51, 0xffff0000, v51
	v_pk_fma_f32 v[40:41], v[154:155], v[50:51], v[40:41] op_sel_hi:[0,1,1]
	v_pk_fma_f32 v[50:51], v[154:155], v[50:51], v[54:55] op_sel:[1,0,0]
	v_lshlrev_b32_e32 v46, 16, v47
	v_and_b32_e32 v47, 0xffff0000, v47
	v_pk_fma_f32 v[40:41], v[156:157], v[46:47], v[40:41] op_sel_hi:[0,1,1]
	v_pk_fma_f32 v[46:47], v[156:157], v[46:47], v[50:51] op_sel:[1,0,0]
	v_lshlrev_b32_e32 v42, 16, v43
	v_and_b32_e32 v43, 0xffff0000, v43
	v_pk_fma_f32 v[40:41], v[158:159], v[42:43], v[40:41] op_sel_hi:[0,1,1]
	v_pk_fma_f32 v[42:43], v[158:159], v[42:43], v[46:47] op_sel:[1,0,0]
	v_mul_lo_u32 v0, v0, s6
	v_pk_mul_f32 v[46:47], v[2:3], v[42:43]
	v_pk_mul_f32 v[42:43], v[4:5], v[42:43]
	v_pk_fma_f32 v[46:47], v[4:5], v[40:41], v[46:47] neg_lo:[0,0,1] neg_hi:[0,0,1]
	v_pk_fma_f32 v[50:51], v[2:3], v[40:41], v[42:43]
	v_cvt_pk_bf16_f32 v40, v108, v109
	v_cvt_pk_bf16_f32 v41, v44, v45
	v_cvt_pk_bf16_f32 v42, v56, v57
	v_cvt_pk_bf16_f32 v43, v46, v47
	v_add3_u32 v0, 0, v0, v192
	ds_write_b128 v0, v[40:43]
	v_cvt_pk_bf16_f32 v40, v104, v105
	v_cvt_pk_bf16_f32 v41, v48, v49
	v_cvt_pk_bf16_f32 v42, v52, v53
	v_cvt_pk_bf16_f32 v43, v50, v51
	ds_write_b128 v0, v[40:43] offset:512
	s_waitcnt vmcnt(15)
; #define BU_LOAD(buf, ib) do { _Pragma("unroll") for (int h = 0; h < 2; ++h) { const int it = (2 * (ib) + h + k2) & 7, l = 16 * w + 2 * it + rp; \
;             _Pragma("unroll") for (int s2 = 0; s2 < 8; ++s2) c4[buf][h][s2] = *(const GAS u32x4*)(z0 + (size_t)l * 2048 + 256 * s2); } } while (0)
; __device__ __forceinline__ void b_unit(Frame& F, int u, bool dry) {
;     ...
;         BU_LOAD(0, 0);
;         BU_LOAD(1, 1); BU_RED(0, 0);
;         BU_LOAD(0, 2); BU_RED(1, 1);
;         BU_LOAD(1, 3); BU_RED(0, 2);
	v_lshlrev_b32_e32 v0, 16, v132
	v_and_b32_e32 v1, 0xffff0000, v132
	s_waitcnt vmcnt(14)
	v_lshlrev_b32_e32 v46, 16, v128
	v_and_b32_e32 v47, 0xffff0000, v128
	v_pk_fma_f32 v[54:55], v[144:145], v[0:1], 0 op_sel_hi:[0,1,0]
	v_pk_fma_f32 v[0:1], v[144:145], v[0:1], 0 op_sel:[1,0,0] op_sel_hi:[1,1,0]
	v_pk_fma_f32 v[54:55], v[146:147], v[46:47], v[54:55] op_sel_hi:[0,1,1]
	v_pk_fma_f32 v[0:1], v[146:147], v[46:47], v[0:1] op_sel:[1,0,0]
	s_waitcnt vmcnt(13)
	v_lshlrev_b32_e32 v46, 16, v100
	v_and_b32_e32 v47, 0xffff0000, v100
	v_pk_fma_f32 v[54:55], v[148:149], v[46:47], v[54:55] op_sel_hi:[0,1,1]
	v_pk_fma_f32 v[0:1], v[148:149], v[46:47], v[0:1] op_sel:[1,0,0]
	s_waitcnt vmcnt(12)
	v_lshlrev_b32_e32 v46, 16, v96
	v_and_b32_e32 v47, 0xffff0000, v96
	v_pk_fma_f32 v[54:55], v[150:151], v[46:47], v[54:55] op_sel_hi:[0,1,1]
	v_pk_fma_f32 v[0:1], v[150:151], v[46:47], v[0:1] op_sel:[1,0,0]
	s_waitcnt vmcnt(11)
	v_lshlrev_b32_e32 v46, 16, v92
	v_and_b32_e32 v47, 0xffff0000, v92
	v_pk_fma_f32 v[54:55], v[152:153], v[46:47], v[54:55] op_sel_hi:[0,1,1]
	v_pk_fma_f32 v[0:1], v[152:153], v[46:47], v[0:1] op_sel:[1,0,0]
	s_waitcnt vmcnt(10)
	v_lshlrev_b32_e32 v46, 16, v88
	v_and_b32_e32 v47, 0xffff0000, v88
	v_pk_fma_f32 v[54:55], v[154:155], v[46:47], v[54:55] op_sel_hi:[0,1,1]
	v_pk_fma_f32 v[0:1], v[154:155], v[46:47], v[0:1] op_sel:[1,0,0]
	s_waitcnt vmcnt(9)
	v_lshlrev_b32_e32 v46, 16, v84
	v_and_b32_e32 v47, 0xffff0000, v84
	v_pk_fma_f32 v[54:55], v[156:157], v[46:47], v[54:55] op_sel_hi:[0,1,1]
	v_pk_fma_f32 v[0:1], v[156:157], v[46:47], v[0:1] op_sel:[1,0,0]
	s_waitcnt vmcnt(8)
	v_lshlrev_b32_e32 v46, 16, v80
	v_and_b32_e32 v47, 0xffff0000, v80
	v_pk_fma_f32 v[0:1], v[158:159], v[46:47], v[0:1] op_sel:[1,0,0]
	v_lshlrev_b32_e32 v40, 16, v133
	v_and_b32_e32 v41, 0xffff0000, v133
	v_pk_fma_f32 v[54:55], v[158:159], v[46:47], v[54:55] op_sel_hi:[0,1,1]
	v_pk_mul_f32 v[46:47], v[10:11], v[0:1]
	v_pk_mul_f32 v[0:1], v[160:161], v[0:1]
	v_lshlrev_b32_e32 v48, 16, v129
	v_and_b32_e32 v49, 0xffff0000, v129
	v_pk_fma_f32 v[46:47], v[160:161], v[54:55], v[46:47] neg_lo:[0,0,1] neg_hi:[0,0,1]
	v_pk_fma_f32 v[0:1], v[10:11], v[54:55], v[0:1]
	v_pk_fma_f32 v[54:55], v[144:145], v[40:41], 0 op_sel_hi:[0,1,0]
	v_pk_fma_f32 v[40:41], v[144:145], v[40:41], 0 op_sel:[1,0,0] op_sel_hi:[1,1,0]
	v_pk_fma_f32 v[54:55], v[146:147], v[48:49], v[54:55] op_sel_hi:[0,1,1]
	v_pk_fma_f32 v[40:41], v[146:147], v[48:49], v[40:41] op_sel:[1,0,0]
	v_lshlrev_b32_e32 v48, 16, v101
	v_and_b32_e32 v49, 0xffff0000, v101
	v_pk_fma_f32 v[54:55], v[148:149], v[48:49], v[54:55] op_sel_hi:[0,1,1]
	v_pk_fma_f32 v[40:41], v[148:149], v[48:49], v[40:41] op_sel:[1,0,0]
	v_lshlrev_b32_e32 v48, 16, v97
	v_and_b32_e32 v49, 0xffff0000, v97
	v_pk_fma_f32 v[54:55], v[150:151], v[48:49], v[54:55] op_sel_hi:[0,1,1]
	v_pk_fma_f32 v[40:41], v[150:151], v[48:49], v[40:41] op_sel:[1,0,0]
	v_lshlrev_b32_e32 v48, 16, v93
	v_and_b32_e32 v49, 0xffff0000, v93
	v_pk_fma_f32 v[54:55], v[152:153], v[48:49], v[54:55] op_sel_hi:[0,1,1]
	v_pk_fma_f32 v[40:41], v[152:153], v[48:49], v[40:41] op_sel:[1,0,0]
	v_lshlrev_b32_e32 v48, 16, v89
	v_and_b32_e32 v49, 0xffff0000, v89
	v_pk_fma_f32 v[54:55], v[154:155], v[48:49], v[54:55] op_sel_hi:[0,1,1]
	v_pk_fma_f32 v[40:41], v[154:155], v[48:49], v[40:41] op_sel:[1,0,0]
	v_lshlrev_b32_e32 v48, 16, v85
	v_and_b32_e32 v49, 0xffff0000, v85
	v_pk_fma_f32 v[54:55], v[156:157], v[48:49], v[54:55] op_sel_hi:[0,1,1]
	v_pk_fma_f32 v[40:41], v[156:157], v[48:49], v[40:41] op_sel:[1,0,0]
	v_lshlrev_b32_e32 v48, 16, v81
	v_and_b32_e32 v49, 0xffff0000, v81
	v_pk_fma_f32 v[40:41], v[158:159], v[48:49], v[40:41] op_sel:[1,0,0]
	v_lshlrev_b32_e32 v42, 16, v134
	v_and_b32_e32 v43, 0xffff0000, v134
	v_pk_fma_f32 v[54:55], v[158:159], v[48:49], v[54:55] op_sel_hi:[0,1,1]
	v_pk_mul_f32 v[48:49], v[14:15], v[40:41]
	v_pk_mul_f32 v[40:41], v[8:9], v[40:41]
	v_lshlrev_b32_e32 v50, 16, v130
	v_and_b32_e32 v51, 0xffff0000, v130
	v_pk_fma_f32 v[48:49], v[8:9], v[54:55], v[48:49] neg_lo:[0,0,1] neg_hi:[0,0,1]
	v_pk_fma_f32 v[54:55], v[14:15], v[54:55], v[40:41]
	v_pk_fma_f32 v[40:41], v[144:145], v[42:43], 0 op_sel_hi:[0,1,0]
	v_pk_fma_f32 v[42:43], v[144:145], v[42:43], 0 op_sel:[1,0,0] op_sel_hi:[1,1,0]
	v_pk_fma_f32 v[40:41], v[146:147], v[50:51], v[40:41] op_sel_hi:[0,1,1]
	v_pk_fma_f32 v[42:43], v[146:147], v[50:51], v[42:43] op_sel:[1,0,0]
	v_lshlrev_b32_e32 v50, 16, v102
	v_and_b32_e32 v51, 0xffff0000, v102
	v_pk_fma_f32 v[40:41], v[148:149], v[50:51], v[40:41] op_sel_hi:[0,1,1]
	v_pk_fma_f32 v[42:43], v[148:149], v[50:51], v[42:43] op_sel:[1,0,0]
	v_lshlrev_b32_e32 v50, 16, v98
	v_and_b32_e32 v51, 0xffff0000, v98
	v_pk_fma_f32 v[40:41], v[150:151], v[50:51], v[40:41] op_sel_hi:[0,1,1]
	v_pk_fma_f32 v[42:43], v[150:151], v[50:51], v[42:43] op_sel:[1,0,0]
	v_lshlrev_b32_e32 v50, 16, v94
	v_and_b32_e32 v51, 0xffff0000, v94
	v_pk_fma_f32 v[40:41], v[152:153], v[50:51], v[40:41] op_sel_hi:[0,1,1]
	v_pk_fma_f32 v[42:43], v[152:153], v[50:51], v[42:43] op_sel:[1,0,0]
	v_lshlrev_b32_e32 v50, 16, v90
	v_and_b32_e32 v51, 0xffff0000, v90
	v_pk_fma_f32 v[40:41], v[154:155], v[50:51], v[40:41] op_sel_hi:[0,1,1]
	v_pk_fma_f32 v[42:43], v[154:155], v[50:51], v[42:43] op_sel:[1,0,0]
	v_lshlrev_b32_e32 v50, 16, v86
	v_and_b32_e32 v51, 0xffff0000, v86
	v_pk_fma_f32 v[40:41], v[156:157], v[50:51], v[40:41] op_sel_hi:[0,1,1]
	v_pk_fma_f32 v[42:43], v[156:157], v[50:51], v[42:43] op_sel:[1,0,0]
	v_lshlrev_b32_e32 v50, 16, v82
	v_and_b32_e32 v51, 0xffff0000, v82
	v_pk_fma_f32 v[42:43], v[158:159], v[50:51], v[42:43] op_sel:[1,0,0]
	v_lshlrev_b32_e32 v44, 16, v135
	v_and_b32_e32 v45, 0xffff0000, v135
; #define BU_LOAD(buf, ib) do { _Pragma("unroll") for (int h = 0; h < 2; ++h) { const int it = (2 * (ib) + h + k2) & 7, l = 16 * w + 2 * it + rp; \
;             _Pragma("unroll") for (int s2 = 0; s2 < 8; ++s2) c4[buf][h][s2] = *(const GAS u32x4*)(z0 + (size_t)l * 2048 + 256 * s2); } } while (0)
; __device__ __forceinline__ void b_unit(Frame& F, int u, bool dry) {
;     ...
;         BU_LOAD(0, 0);
;         BU_LOAD(1, 1); BU_RED(0, 0);
;         BU_LOAD(0, 2); BU_RED(1, 1);
;         BU_LOAD(1, 3); BU_RED(0, 2);
	v_pk_fma_f32 v[40:41], v[158:159], v[50:51], v[40:41] op_sel_hi:[0,1,1]
	v_pk_mul_f32 v[50:51], v[6:7], v[42:43]
	v_pk_mul_f32 v[42:43], v[12:13], v[42:43]
	v_lshlrev_b32_e32 v52, 16, v131
	v_and_b32_e32 v53, 0xffff0000, v131
	v_pk_fma_f32 v[50:51], v[12:13], v[40:41], v[50:51] neg_lo:[0,0,1] neg_hi:[0,0,1]
	v_pk_fma_f32 v[56:57], v[6:7], v[40:41], v[42:43]
	v_pk_fma_f32 v[40:41], v[144:145], v[44:45], 0 op_sel_hi:[0,1,0]
	v_pk_fma_f32 v[42:43], v[144:145], v[44:45], 0 op_sel:[1,0,0] op_sel_hi:[1,1,0]
	v_pk_fma_f32 v[40:41], v[146:147], v[52:53], v[40:41] op_sel_hi:[0,1,1]
	v_pk_fma_f32 v[42:43], v[146:147], v[52:53], v[42:43] op_sel:[1,0,0]
	v_lshlrev_b32_e32 v44, 16, v103
	v_and_b32_e32 v45, 0xffff0000, v103
	v_pk_fma_f32 v[40:41], v[148:149], v[44:45], v[40:41] op_sel_hi:[0,1,1]
	v_pk_fma_f32 v[42:43], v[148:149], v[44:45], v[42:43] op_sel:[1,0,0]
	v_lshlrev_b32_e32 v44, 16, v99
	v_and_b32_e32 v45, 0xffff0000, v99
	v_pk_fma_f32 v[40:41], v[150:151], v[44:45], v[40:41] op_sel_hi:[0,1,1]
	v_pk_fma_f32 v[42:43], v[150:151], v[44:45], v[42:43] op_sel:[1,0,0]
	v_lshlrev_b32_e32 v44, 16, v95
	v_and_b32_e32 v45, 0xffff0000, v95
	v_pk_fma_f32 v[40:41], v[152:153], v[44:45], v[40:41] op_sel_hi:[0,1,1]
	v_pk_fma_f32 v[42:43], v[152:153], v[44:45], v[42:43] op_sel:[1,0,0]
	v_lshlrev_b32_e32 v44, 16, v91
	v_and_b32_e32 v45, 0xffff0000, v91
	v_pk_fma_f32 v[40:41], v[154:155], v[44:45], v[40:41] op_sel_hi:[0,1,1]
	v_pk_fma_f32 v[42:43], v[154:155], v[44:45], v[42:43] op_sel:[1,0,0]
	v_lshlrev_b32_e32 v44, 16, v87
	v_and_b32_e32 v45, 0xffff0000, v87
	v_pk_fma_f32 v[40:41], v[156:157], v[44:45], v[40:41] op_sel_hi:[0,1,1]
	v_pk_fma_f32 v[42:43], v[156:157], v[44:45], v[42:43] op_sel:[1,0,0]
	v_lshlrev_b32_e32 v44, 16, v83
	v_and_b32_e32 v45, 0xffff0000, v83
	v_pk_fma_f32 v[42:43], v[158:159], v[44:45], v[42:43] op_sel:[1,0,0]
	v_pk_fma_f32 v[40:41], v[158:159], v[44:45], v[40:41] op_sel_hi:[0,1,1]
	v_pk_mul_f32 v[44:45], v[2:3], v[42:43]
	v_pk_mul_f32 v[42:43], v[4:5], v[42:43]
	v_pk_fma_f32 v[44:45], v[4:5], v[40:41], v[44:45] neg_lo:[0,0,1] neg_hi:[0,0,1]
	v_pk_fma_f32 v[52:53], v[2:3], v[40:41], v[42:43]
	v_cvt_pk_bf16_f32 v43, v44, v45
	v_mul_lo_u32 v44, v166, s6
	v_cvt_pk_bf16_f32 v40, v46, v47
	v_cvt_pk_bf16_f32 v41, v48, v49
	v_cvt_pk_bf16_f32 v42, v50, v51
	v_add3_u32 v44, 0, v44, v192
	ds_write_b128 v44, v[40:43]
	v_cvt_pk_bf16_f32 v40, v0, v1
	s_waitcnt vmcnt(7)
	v_lshlrev_b32_e32 v0, 16, v68
	v_and_b32_e32 v1, 0xffff0000, v68
	v_cvt_pk_bf16_f32 v41, v54, v55
	s_waitcnt vmcnt(6)
	v_lshlrev_b32_e32 v46, 16, v64
	v_and_b32_e32 v47, 0xffff0000, v64
	v_pk_fma_f32 v[54:55], v[144:145], v[0:1], 0 op_sel_hi:[0,1,0]
	v_pk_fma_f32 v[0:1], v[144:145], v[0:1], 0 op_sel:[1,0,0] op_sel_hi:[1,1,0]
	v_pk_fma_f32 v[54:55], v[146:147], v[46:47], v[54:55] op_sel_hi:[0,1,1]
	v_pk_fma_f32 v[0:1], v[146:147], v[46:47], v[0:1] op_sel:[1,0,0]
	s_waitcnt vmcnt(5)
	v_lshlrev_b32_e32 v46, 16, v36
	v_and_b32_e32 v47, 0xffff0000, v36
	v_pk_fma_f32 v[54:55], v[148:149], v[46:47], v[54:55] op_sel_hi:[0,1,1]
	v_pk_fma_f32 v[0:1], v[148:149], v[46:47], v[0:1] op_sel:[1,0,0]
	s_waitcnt vmcnt(4)
	v_lshlrev_b32_e32 v46, 16, v32
	v_and_b32_e32 v47, 0xffff0000, v32
	v_pk_fma_f32 v[54:55], v[150:151], v[46:47], v[54:55] op_sel_hi:[0,1,1]
	v_pk_fma_f32 v[0:1], v[150:151], v[46:47], v[0:1] op_sel:[1,0,0]
	s_waitcnt vmcnt(3)
	v_lshlrev_b32_e32 v46, 16, v28
	v_and_b32_e32 v47, 0xffff0000, v28
	v_pk_fma_f32 v[54:55], v[152:153], v[46:47], v[54:55] op_sel_hi:[0,1,1]
	v_pk_fma_f32 v[0:1], v[152:153], v[46:47], v[0:1] op_sel:[1,0,0]
	s_waitcnt vmcnt(2)
	v_lshlrev_b32_e32 v46, 16, v24
	v_and_b32_e32 v47, 0xffff0000, v24
	v_pk_fma_f32 v[54:55], v[154:155], v[46:47], v[54:55] op_sel_hi:[0,1,1]
	v_pk_fma_f32 v[0:1], v[154:155], v[46:47], v[0:1] op_sel:[1,0,0]
	s_waitcnt vmcnt(1)
	v_lshlrev_b32_e32 v46, 16, v20
	v_and_b32_e32 v47, 0xffff0000, v20
	v_pk_fma_f32 v[54:55], v[156:157], v[46:47], v[54:55] op_sel_hi:[0,1,1]
	v_pk_fma_f32 v[0:1], v[156:157], v[46:47], v[0:1] op_sel:[1,0,0]
	s_waitcnt vmcnt(0)
	v_lshlrev_b32_e32 v46, 16, v16
	v_and_b32_e32 v47, 0xffff0000, v16
	v_cvt_pk_bf16_f32 v42, v56, v57
	v_cvt_pk_bf16_f32 v43, v52, v53
	v_pk_fma_f32 v[0:1], v[158:159], v[46:47], v[0:1] op_sel:[1,0,0]
	ds_write_b128 v44, v[40:43] offset:512
	v_lshlrev_b32_e32 v40, 16, v69
	v_and_b32_e32 v41, 0xffff0000, v69
	v_pk_fma_f32 v[54:55], v[158:159], v[46:47], v[54:55] op_sel_hi:[0,1,1]
	v_pk_mul_f32 v[46:47], v[10:11], v[0:1]
	v_pk_mul_f32 v[0:1], v[160:161], v[0:1]
	v_lshlrev_b32_e32 v48, 16, v65
	v_and_b32_e32 v49, 0xffff0000, v65
	v_pk_fma_f32 v[10:11], v[10:11], v[54:55], v[0:1]
	v_pk_fma_f32 v[0:1], v[144:145], v[40:41], 0 op_sel_hi:[0,1,0]
	v_pk_fma_f32 v[40:41], v[144:145], v[40:41], 0 op_sel:[1,0,0] op_sel_hi:[1,1,0]
	v_pk_fma_f32 v[0:1], v[146:147], v[48:49], v[0:1] op_sel_hi:[0,1,1]
	v_pk_fma_f32 v[40:41], v[146:147], v[48:49], v[40:41] op_sel:[1,0,0]
	v_lshlrev_b32_e32 v36, 16, v37
	v_and_b32_e32 v37, 0xffff0000, v37
	v_pk_fma_f32 v[0:1], v[148:149], v[36:37], v[0:1] op_sel_hi:[0,1,1]
	v_pk_fma_f32 v[36:37], v[148:149], v[36:37], v[40:41] op_sel:[1,0,0]
	v_lshlrev_b32_e32 v32, 16, v33
	v_and_b32_e32 v33, 0xffff0000, v33
	v_pk_fma_f32 v[0:1], v[150:151], v[32:33], v[0:1] op_sel_hi:[0,1,1]
	v_pk_fma_f32 v[32:33], v[150:151], v[32:33], v[36:37] op_sel:[1,0,0]
	v_lshlrev_b32_e32 v28, 16, v29
	v_and_b32_e32 v29, 0xffff0000, v29
	v_pk_fma_f32 v[0:1], v[152:153], v[28:29], v[0:1] op_sel_hi:[0,1,1]
	v_pk_fma_f32 v[28:29], v[152:153], v[28:29], v[32:33] op_sel:[1,0,0]
	v_lshlrev_b32_e32 v24, 16, v25
	v_and_b32_e32 v25, 0xffff0000, v25
	v_pk_fma_f32 v[0:1], v[154:155], v[24:25], v[0:1] op_sel_hi:[0,1,1]
; #define BU_LOAD(buf, ib) do { _Pragma("unroll") for (int h = 0; h < 2; ++h) { const int it = (2 * (ib) + h + k2) & 7, l = 16 * w + 2 * it + rp; \
;             _Pragma("unroll") for (int s2 = 0; s2 < 8; ++s2) c4[buf][h][s2] = *(const GAS u32x4*)(z0 + (size_t)l * 2048 + 256 * s2); } } while (0)
; __device__ __forceinline__ void b_unit(Frame& F, int u, bool dry) {
;     ...
;         BU_LOAD(0, 0);
;         BU_LOAD(1, 1); BU_RED(0, 0);
;         BU_LOAD(0, 2); BU_RED(1, 1);
;         BU_LOAD(1, 3); BU_RED(0, 2);
;         BU_RED(1, 3);
;     ...
;     }
;     __syncthreads();
	v_pk_fma_f32 v[24:25], v[154:155], v[24:25], v[28:29] op_sel:[1,0,0]
	v_lshlrev_b32_e32 v20, 16, v21
	v_and_b32_e32 v21, 0xffff0000, v21
	v_pk_fma_f32 v[0:1], v[156:157], v[20:21], v[0:1] op_sel_hi:[0,1,1]
	v_pk_fma_f32 v[20:21], v[156:157], v[20:21], v[24:25] op_sel:[1,0,0]
	v_lshlrev_b32_e32 v16, 16, v17
	v_and_b32_e32 v17, 0xffff0000, v17
	v_pk_fma_f32 v[0:1], v[158:159], v[16:17], v[0:1] op_sel_hi:[0,1,1]
	v_pk_fma_f32 v[16:17], v[158:159], v[16:17], v[20:21] op_sel:[1,0,0]
	v_lshlrev_b32_e32 v42, 16, v70
	v_pk_mul_f32 v[20:21], v[14:15], v[16:17]
	v_and_b32_e32 v43, 0xffff0000, v70
	v_pk_fma_f32 v[20:21], v[8:9], v[0:1], v[20:21] neg_lo:[0,0,1] neg_hi:[0,0,1]
	v_pk_mul_f32 v[8:9], v[8:9], v[16:17]
	v_lshlrev_b32_e32 v50, 16, v66
	v_and_b32_e32 v51, 0xffff0000, v66
	v_pk_fma_f32 v[8:9], v[14:15], v[0:1], v[8:9]
	v_pk_fma_f32 v[0:1], v[144:145], v[42:43], 0 op_sel_hi:[0,1,0]
	v_pk_fma_f32 v[14:15], v[144:145], v[42:43], 0 op_sel:[1,0,0] op_sel_hi:[1,1,0]
	v_pk_fma_f32 v[0:1], v[146:147], v[50:51], v[0:1] op_sel_hi:[0,1,1]
	v_pk_fma_f32 v[14:15], v[146:147], v[50:51], v[14:15] op_sel:[1,0,0]
	v_lshlrev_b32_e32 v16, 16, v38
	v_and_b32_e32 v17, 0xffff0000, v38
	v_pk_fma_f32 v[0:1], v[148:149], v[16:17], v[0:1] op_sel_hi:[0,1,1]
	v_pk_fma_f32 v[14:15], v[148:149], v[16:17], v[14:15] op_sel:[1,0,0]
	v_lshlrev_b32_e32 v16, 16, v34
	v_and_b32_e32 v17, 0xffff0000, v34
	v_pk_fma_f32 v[0:1], v[150:151], v[16:17], v[0:1] op_sel_hi:[0,1,1]
	v_pk_fma_f32 v[14:15], v[150:151], v[16:17], v[14:15] op_sel:[1,0,0]
	v_lshlrev_b32_e32 v16, 16, v30
	v_and_b32_e32 v17, 0xffff0000, v30
	v_pk_fma_f32 v[0:1], v[152:153], v[16:17], v[0:1] op_sel_hi:[0,1,1]
	v_pk_fma_f32 v[14:15], v[152:153], v[16:17], v[14:15] op_sel:[1,0,0]
	v_lshlrev_b32_e32 v16, 16, v26
	v_and_b32_e32 v17, 0xffff0000, v26
	v_pk_fma_f32 v[0:1], v[154:155], v[16:17], v[0:1] op_sel_hi:[0,1,1]
	v_pk_fma_f32 v[14:15], v[154:155], v[16:17], v[14:15] op_sel:[1,0,0]
	v_lshlrev_b32_e32 v16, 16, v22
	v_and_b32_e32 v17, 0xffff0000, v22
	v_pk_fma_f32 v[0:1], v[156:157], v[16:17], v[0:1] op_sel_hi:[0,1,1]
	v_pk_fma_f32 v[14:15], v[156:157], v[16:17], v[14:15] op_sel:[1,0,0]
	v_lshlrev_b32_e32 v16, 16, v18
	v_and_b32_e32 v17, 0xffff0000, v18
	v_pk_fma_f32 v[14:15], v[158:159], v[16:17], v[14:15] op_sel:[1,0,0]
	v_pk_fma_f32 v[0:1], v[158:159], v[16:17], v[0:1] op_sel_hi:[0,1,1]
	v_pk_mul_f32 v[16:17], v[6:7], v[14:15]
	v_lshlrev_b32_e32 v44, 16, v71
	v_and_b32_e32 v45, 0xffff0000, v71
	v_pk_fma_f32 v[16:17], v[12:13], v[0:1], v[16:17] neg_lo:[0,0,1] neg_hi:[0,0,1]
	v_pk_mul_f32 v[12:13], v[12:13], v[14:15]
	v_lshlrev_b32_e32 v52, 16, v67
	v_and_b32_e32 v53, 0xffff0000, v67
	v_pk_fma_f32 v[6:7], v[6:7], v[0:1], v[12:13]
	v_pk_fma_f32 v[0:1], v[144:145], v[44:45], 0 op_sel_hi:[0,1,0]
	v_pk_fma_f32 v[12:13], v[144:145], v[44:45], 0 op_sel:[1,0,0] op_sel_hi:[1,1,0]
	v_pk_fma_f32 v[0:1], v[146:147], v[52:53], v[0:1] op_sel_hi:[0,1,1]
	v_pk_fma_f32 v[12:13], v[146:147], v[52:53], v[12:13] op_sel:[1,0,0]
	v_lshlrev_b32_e32 v14, 16, v39
	v_and_b32_e32 v15, 0xffff0000, v39
	v_pk_fma_f32 v[0:1], v[148:149], v[14:15], v[0:1] op_sel_hi:[0,1,1]
	v_pk_fma_f32 v[12:13], v[148:149], v[14:15], v[12:13] op_sel:[1,0,0]
	v_lshlrev_b32_e32 v14, 16, v35
	v_and_b32_e32 v15, 0xffff0000, v35
	v_pk_fma_f32 v[0:1], v[150:151], v[14:15], v[0:1] op_sel_hi:[0,1,1]
	v_pk_fma_f32 v[12:13], v[150:151], v[14:15], v[12:13] op_sel:[1,0,0]
	v_lshlrev_b32_e32 v14, 16, v31
	v_and_b32_e32 v15, 0xffff0000, v31
	v_pk_fma_f32 v[0:1], v[152:153], v[14:15], v[0:1] op_sel_hi:[0,1,1]
	v_pk_fma_f32 v[12:13], v[152:153], v[14:15], v[12:13] op_sel:[1,0,0]
	v_lshlrev_b32_e32 v14, 16, v27
	v_and_b32_e32 v15, 0xffff0000, v27
	v_pk_fma_f32 v[0:1], v[154:155], v[14:15], v[0:1] op_sel_hi:[0,1,1]
	v_pk_fma_f32 v[12:13], v[154:155], v[14:15], v[12:13] op_sel:[1,0,0]
	v_lshlrev_b32_e32 v14, 16, v23
	v_and_b32_e32 v15, 0xffff0000, v23
	v_pk_fma_f32 v[0:1], v[156:157], v[14:15], v[0:1] op_sel_hi:[0,1,1]
	v_pk_fma_f32 v[12:13], v[156:157], v[14:15], v[12:13] op_sel:[1,0,0]
	v_lshlrev_b32_e32 v14, 16, v19
	v_and_b32_e32 v15, 0xffff0000, v19
	v_pk_fma_f32 v[12:13], v[158:159], v[14:15], v[12:13] op_sel:[1,0,0]
	v_pk_fma_f32 v[0:1], v[158:159], v[14:15], v[0:1] op_sel_hi:[0,1,1]
	v_pk_mul_f32 v[14:15], v[2:3], v[12:13]
	v_pk_fma_f32 v[46:47], v[160:161], v[54:55], v[46:47] neg_lo:[0,0,1] neg_hi:[0,0,1]
	v_pk_fma_f32 v[14:15], v[4:5], v[0:1], v[14:15] neg_lo:[0,0,1] neg_hi:[0,0,1]
	v_pk_mul_f32 v[4:5], v[4:5], v[12:13]
	v_mul_lo_u32 v12, v164, s6
	v_pk_fma_f32 v[4:5], v[2:3], v[0:1], v[4:5]
	v_cvt_pk_bf16_f32 v0, v46, v47
	v_cvt_pk_bf16_f32 v1, v20, v21
	v_cvt_pk_bf16_f32 v2, v16, v17
	v_cvt_pk_bf16_f32 v3, v14, v15
	v_add3_u32 v12, 0, v12, v192
	ds_write_b128 v12, v[0:3]
	v_cvt_pk_bf16_f32 v0, v10, v11
	v_cvt_pk_bf16_f32 v1, v8, v9
	v_cvt_pk_bf16_f32 v2, v6, v7
	v_cvt_pk_bf16_f32 v3, v4, v5
	v_lshlrev_b32_e32 v192, 4, v171
	ds_write_b128 v12, v[0:3] offset:512
	v_lshl_add_u64 v[0:1], s[2:3], 0, v[192:193]
	v_add_co_u32_e32 v4, vcc, s7, v0
	s_waitcnt lgkmcnt(0)
	s_nop 0
	v_addc_co_u32_e32 v5, vcc, 0, v1, vcc
	s_barrier
; #define LAS __attribute__((address_space(3)))
; #define GAS __attribute__((address_space(1)))
; __device__ __forceinline__ unsigned cvtpk(float lo, float hi) { f32x2 v = {lo, hi}; bf16x2_t b = __builtin_convertvector(v, bf16x2_t); return __builtin_bit_cast(unsigned, b); }
; __device__ __forceinline__ void b_unit(Frame& F, int u, bool dry) {
;     ...
;         const bf16x8 Wr = *(const GAS bf16x8*)(ws_ + WS_W16F + (size_t)lane * 16), Wi = *(const GAS bf16x8*)(ws_ + WS_W16F + 1024 + (size_t)lane * 16);
;         f32x2 t2[4];
; #pragma unroll
;         for (int j = 0; j < 4; ++j) t2[j] = *(const GAS f32x2*)(ws_ + WS_TW2 + (size_t)(lane * 4 + j) * 8);
;         const f32x4 zero4 = (f32x4){0.f, 0.f, 0.f, 0.f};
;         const unsigned rbase = (unsigned)(size_t)Bt + (unsigned)(16 * w) * 1040u + (unsigned)(fq >> 1) * 512u + (unsigned)(16 * (8 * (fq & 1) + (fr >> 2)) + 4 * (fr & 3)) * 2u;
;         u32x2 q0[16], q1[16];
;     ...
;         BU_TR8(0); BU_TR8(8);
;     ...
;         LAS unsigned char* vrow = Bt + (size_t)(16 * w) * 1040 + 64 * fr + 8 * fq;
; #pragma unroll
;         for (int i = 0; i < 16; ++i) {
;             u32x4 f4; f4.x = q0[i].x; f4.y = q0[i].y; f4.z = q1[i].x; f4.w = q1[i].y;
;             const bf16x8 frag = __builtin_bit_cast(bf16x8, f4);
;             const f32x4 dr = __builtin_amdgcn_mfma_f32_16x16x32_bf16(frag, Wr, zero4, 0, 0, 0), di = __builtin_amdgcn_mfma_f32_16x16x32_bf16(frag, Wi, zero4, 0, 0, 0);
;             float vr[4], vi[4];
; #pragma unroll
;             for (int j = 0; j < 4; ++j) { vr[j] = dr[j] * t2[j].x + di[j] * t2[j].y; vi[j] = di[j] * t2[j].x - dr[j] * t2[j].y; }
;             u32x2 o; o.x = cvtpk(vr[0], vr[1]); o.y = cvtpk(vr[2], vr[3]); *(LAS u32x2*)(vrow + i * 1040) = o;
;             o.x = cvtpk(vi[0], vi[1]); o.y = cvtpk(vi[2], vi[3]); *(LAS u32x2*)(vrow + i * 1040 + 32) = o;
;         }
	global_load_dwordx4 v[0:3], v[4:5], off
	s_nop 0
	global_load_dwordx4 v[4:7], v[4:5], off offset:1024
	v_lshlrev_b32_e32 v8, 5, v171
	v_mov_b32_e32 v9, v193
	v_lshl_add_u64 v[8:9], s[2:3], 0, v[8:9]
	s_mov_b64 s[0:1], 0x1d90800
	v_lshl_add_u64 v[10:11], v[8:9], 0, s[0:1]
	v_add_co_u32_e32 v8, vcc, s7, v8
	v_lshrrev_b32_e32 v17, 1, v170
	s_nop 0
	v_addc_co_u32_e32 v9, vcc, 0, v9, vcc
	global_load_dwordx4 v[12:15], v[8:9], off offset:2048
	s_nop 0
	global_load_dwordx4 v[8:11], v[10:11], off offset:16
	v_bfe_u32 v18, v170, 2, 2
	v_and_b32_e32 v76, 24, v17
	v_and_or_b32 v17, v17, 8, v18
	v_lshlrev_b32_e32 v18, 3, v170
	v_and_b32_e32 v18, 24, v18
	v_readlane_b32 s0, v253, 54
	v_and_b32_e32 v16, 0x200, v192
	v_lshlrev_b32_e32 v17, 5, v17
	v_add_u32_e32 v18, s0, v18
	v_add3_u32 v64, v18, v16, v17
	ds_read_b64_tr_b16 v[82:83], v64 offset:0
	ds_read_b64_tr_b16 v[84:85], v64 offset:0+128
	ds_read_b64_tr_b16 v[78:79], v64 offset:0+1040
	ds_read_b64_tr_b16 v[80:81], v64 offset:0+1040+128
	ds_read_b64_tr_b16 v[72:73], v64 offset:0+2080
	ds_read_b64_tr_b16 v[74:75], v64 offset:0+2080+128
	ds_read_b64_tr_b16 v[68:69], v64 offset:0+3120
	ds_read_b64_tr_b16 v[70:71], v64 offset:0+3120+128
	ds_read_b64_tr_b16 v[60:61], v64 offset:0+4160
	ds_read_b64_tr_b16 v[62:63], v64 offset:0+4160+128
	ds_read_b64_tr_b16 v[56:57], v64 offset:0+5200
	ds_read_b64_tr_b16 v[58:59], v64 offset:0+5200+128
	ds_read_b64_tr_b16 v[52:53], v64 offset:0+6240
	ds_read_b64_tr_b16 v[54:55], v64 offset:0+6240+128
	ds_read_b64_tr_b16 v[48:49], v64 offset:0+7280
	ds_read_b64_tr_b16 v[50:51], v64 offset:0+7280+128
	s_waitcnt lgkmcnt(0)
	v_and_b32_e32 v77, 15, v170
	s_waitcnt vmcnt(3)
	v_mfma_f32_16x16x32_bf16 v[86:89], v[82:85], v[0:3], 0
	ds_read_b64_tr_b16 v[44:45], v64 offset:0x2080
	ds_read_b64_tr_b16 v[46:47], v64 offset:0x2080+128
	ds_read_b64_tr_b16 v[40:41], v64 offset:0x2080+1040
	ds_read_b64_tr_b16 v[42:43], v64 offset:0x2080+1040+128
	ds_read_b64_tr_b16 v[36:37], v64 offset:0x2080+2080
	ds_read_b64_tr_b16 v[38:39], v64 offset:0x2080+2080+128
	ds_read_b64_tr_b16 v[32:33], v64 offset:0x2080+3120
	ds_read_b64_tr_b16 v[34:35], v64 offset:0x2080+3120+128
	ds_read_b64_tr_b16 v[28:29], v64 offset:0x2080+4160
	ds_read_b64_tr_b16 v[30:31], v64 offset:0x2080+4160+128
	ds_read_b64_tr_b16 v[24:25], v64 offset:0x2080+5200
	ds_read_b64_tr_b16 v[26:27], v64 offset:0x2080+5200+128
	ds_read_b64_tr_b16 v[20:21], v64 offset:0x2080+6240
	ds_read_b64_tr_b16 v[22:23], v64 offset:0x2080+6240+128
	ds_read_b64_tr_b16 v[16:17], v64 offset:0x2080+7280
	ds_read_b64_tr_b16 v[18:19], v64 offset:0x2080+7280+128
	s_waitcnt lgkmcnt(0)
	v_lshlrev_b32_e32 v64, 6, v77
	v_add3_u32 v66, s0, v64, v76
	s_waitcnt vmcnt(2)
	v_mfma_f32_16x16x32_bf16 v[82:85], v[82:85], v[4:7], 0
	v_add_u32_e32 v67, 0x800, v66
	v_readlane_b32 s0, v253, 60
	v_lshlrev_b32_e32 v192, 1, v76
	s_waitcnt vmcnt(1)
	v_mov_b32_e32 v65, v14
	v_mov_b32_e32 v14, v13
	v_mov_b32_e32 v64, v12
	s_nop 0
	v_pk_mul_f32 v[12:13], v[14:15], v[82:83]
	s_nop 0
	v_pk_fma_f32 v[90:91], v[64:65], v[86:87], v[12:13]
	v_pk_mul_f32 v[12:13], v[14:15], v[86:87]
	s_nop 0
	v_pk_fma_f32 v[82:83], v[64:65], v[82:83], v[12:13] neg_lo:[0,0,1] neg_hi:[0,0,1]
	s_waitcnt vmcnt(0)
	v_mov_b32_e32 v13, v10
	v_mov_b32_e32 v10, v9
	v_mov_b32_e32 v12, v8
	v_pk_mul_f32 v[8:9], v[10:11], v[84:85]
	v_pk_mul_f32 v[86:87], v[10:11], v[88:89]
	v_pk_fma_f32 v[8:9], v[12:13], v[88:89], v[8:9]
	v_pk_fma_f32 v[84:85], v[12:13], v[84:85], v[86:87] neg_lo:[0,0,1] neg_hi:[0,0,1]
	v_cvt_pk_bf16_f32 v87, v8, v9
	v_cvt_pk_bf16_f32 v8, v82, v83
	v_cvt_pk_bf16_f32 v9, v84, v85
	v_mfma_f32_16x16x32_bf16 v[82:85], v[78:81], v[0:3], 0
	v_cvt_pk_bf16_f32 v86, v90, v91
	ds_write2_b64 v66, v[86:87], v[8:9] offset1:4
	v_mfma_f32_16x16x32_bf16 v[78:81], v[78:81], v[4:7], 0
	s_nop 7
	v_pk_mul_f32 v[8:9], v[14:15], v[78:79]
	s_nop 0
	v_pk_fma_f32 v[8:9], v[64:65], v[82:83], v[8:9]
	v_pk_mul_f32 v[82:83], v[14:15], v[82:83]
	v_cvt_pk_bf16_f32 v8, v8, v9
	v_pk_fma_f32 v[78:79], v[64:65], v[78:79], v[82:83] neg_lo:[0,0,1] neg_hi:[0,0,1]
	v_pk_mul_f32 v[82:83], v[10:11], v[80:81]
	v_cvt_pk_bf16_f32 v78, v78, v79
	v_pk_fma_f32 v[82:83], v[12:13], v[84:85], v[82:83]
	v_pk_mul_f32 v[84:85], v[10:11], v[84:85]
	v_cvt_pk_bf16_f32 v9, v82, v83
	v_pk_fma_f32 v[80:81], v[12:13], v[80:81], v[84:85] neg_lo:[0,0,1] neg_hi:[0,0,1]
	s_nop 0
	v_cvt_pk_bf16_f32 v79, v80, v81
	ds_write2_b64 v66, v[8:9], v[78:79] offset0:130 offset1:134
	v_mfma_f32_16x16x32_bf16 v[78:81], v[72:75], v[0:3], 0
	v_mfma_f32_16x16x32_bf16 v[72:75], v[72:75], v[4:7], 0
	s_nop 7
	v_pk_mul_f32 v[8:9], v[14:15], v[72:73]
	s_nop 0
	v_pk_fma_f32 v[8:9], v[64:65], v[78:79], v[8:9]
	v_pk_mul_f32 v[78:79], v[14:15], v[78:79]
	v_cvt_pk_bf16_f32 v8, v8, v9
	v_pk_fma_f32 v[72:73], v[64:65], v[72:73], v[78:79] neg_lo:[0,0,1] neg_hi:[0,0,1]
	v_pk_mul_f32 v[78:79], v[10:11], v[74:75]
	v_cvt_pk_bf16_f32 v72, v72, v73
	v_pk_fma_f32 v[78:79], v[12:13], v[80:81], v[78:79]
	v_pk_mul_f32 v[80:81], v[10:11], v[80:81]
	v_cvt_pk_bf16_f32 v9, v78, v79
	v_pk_fma_f32 v[74:75], v[12:13], v[74:75], v[80:81] neg_lo:[0,0,1] neg_hi:[0,0,1]
	s_nop 0
	v_cvt_pk_bf16_f32 v73, v74, v75
	ds_write2_b64 v67, v[8:9], v[72:73] offset0:4 offset1:8
	v_mfma_f32_16x16x32_bf16 v[72:75], v[68:71], v[0:3], 0
	v_mfma_f32_16x16x32_bf16 v[68:71], v[68:71], v[4:7], 0
	s_nop 7
	v_pk_mul_f32 v[8:9], v[14:15], v[68:69]
	s_nop 0
	v_pk_fma_f32 v[8:9], v[64:65], v[72:73], v[8:9]
	v_pk_mul_f32 v[72:73], v[14:15], v[72:73]
	v_cvt_pk_bf16_f32 v8, v8, v9
	v_pk_fma_f32 v[68:69], v[64:65], v[68:69], v[72:73] neg_lo:[0,0,1] neg_hi:[0,0,1]
	v_pk_mul_f32 v[72:73], v[10:11], v[70:71]
	v_cvt_pk_bf16_f32 v68, v68, v69
; #define LAS __attribute__((address_space(3)))
; __device__ __forceinline__ unsigned cvtpk(float lo, float hi) { f32x2 v = {lo, hi}; bf16x2_t b = __builtin_convertvector(v, bf16x2_t); return __builtin_bit_cast(unsigned, b); }
; __device__ __forceinline__ void b_unit(Frame& F, int u, bool dry) {
;     ...
; #pragma unroll
;         for (int i = 0; i < 16; ++i) {
;             u32x4 f4; f4.x = q0[i].x; f4.y = q0[i].y; f4.z = q1[i].x; f4.w = q1[i].y;
;             const bf16x8 frag = __builtin_bit_cast(bf16x8, f4);
;             const f32x4 dr = __builtin_amdgcn_mfma_f32_16x16x32_bf16(frag, Wr, zero4, 0, 0, 0), di = __builtin_amdgcn_mfma_f32_16x16x32_bf16(frag, Wi, zero4, 0, 0, 0);
;             float vr[4], vi[4];
; #pragma unroll
;             for (int j = 0; j < 4; ++j) { vr[j] = dr[j] * t2[j].x + di[j] * t2[j].y; vi[j] = di[j] * t2[j].x - dr[j] * t2[j].y; }
;             u32x2 o; o.x = cvtpk(vr[0], vr[1]); o.y = cvtpk(vr[2], vr[3]); *(LAS u32x2*)(vrow + i * 1040) = o;
;             o.x = cvtpk(vi[0], vi[1]); o.y = cvtpk(vi[2], vi[3]); *(LAS u32x2*)(vrow + i * 1040 + 32) = o;
;         }
	v_pk_fma_f32 v[72:73], v[12:13], v[74:75], v[72:73]
	v_pk_mul_f32 v[74:75], v[10:11], v[74:75]
	v_cvt_pk_bf16_f32 v9, v72, v73
	v_pk_fma_f32 v[70:71], v[12:13], v[70:71], v[74:75] neg_lo:[0,0,1] neg_hi:[0,0,1]
	s_nop 0
	v_cvt_pk_bf16_f32 v69, v70, v71
	ds_write2_b64 v67, v[8:9], v[68:69] offset0:134 offset1:138
	v_mfma_f32_16x16x32_bf16 v[68:71], v[60:63], v[0:3], 0
	v_add_u32_e32 v67, 0x1000, v66
	v_mfma_f32_16x16x32_bf16 v[60:63], v[60:63], v[4:7], 0
	s_nop 7
	v_pk_mul_f32 v[8:9], v[14:15], v[60:61]
	s_nop 0
	v_pk_fma_f32 v[8:9], v[64:65], v[68:69], v[8:9]
	v_pk_mul_f32 v[68:69], v[14:15], v[68:69]
	v_cvt_pk_bf16_f32 v8, v8, v9
	v_pk_fma_f32 v[60:61], v[64:65], v[60:61], v[68:69] neg_lo:[0,0,1] neg_hi:[0,0,1]
	v_pk_mul_f32 v[68:69], v[10:11], v[62:63]
	v_cvt_pk_bf16_f32 v60, v60, v61
	v_pk_fma_f32 v[68:69], v[12:13], v[70:71], v[68:69]
	v_pk_mul_f32 v[70:71], v[10:11], v[70:71]
	v_cvt_pk_bf16_f32 v9, v68, v69
	v_pk_fma_f32 v[62:63], v[12:13], v[62:63], v[70:71] neg_lo:[0,0,1] neg_hi:[0,0,1]
	s_nop 0
	v_cvt_pk_bf16_f32 v61, v62, v63
	ds_write2_b64 v67, v[8:9], v[60:61] offset0:8 offset1:12
	v_mfma_f32_16x16x32_bf16 v[60:63], v[56:59], v[0:3], 0
	v_mfma_f32_16x16x32_bf16 v[56:59], v[56:59], v[4:7], 0
	s_nop 7
	v_pk_mul_f32 v[8:9], v[14:15], v[56:57]
	s_nop 0
	v_pk_fma_f32 v[8:9], v[64:65], v[60:61], v[8:9]
	v_pk_mul_f32 v[60:61], v[14:15], v[60:61]
	v_cvt_pk_bf16_f32 v8, v8, v9
	v_pk_fma_f32 v[56:57], v[64:65], v[56:57], v[60:61] neg_lo:[0,0,1] neg_hi:[0,0,1]
	v_pk_mul_f32 v[60:61], v[10:11], v[58:59]
	v_cvt_pk_bf16_f32 v56, v56, v57
	v_pk_fma_f32 v[60:61], v[12:13], v[62:63], v[60:61]
	v_pk_mul_f32 v[62:63], v[10:11], v[62:63]
	v_cvt_pk_bf16_f32 v9, v60, v61
	v_pk_fma_f32 v[58:59], v[12:13], v[58:59], v[62:63] neg_lo:[0,0,1] neg_hi:[0,0,1]
	s_nop 0
	v_cvt_pk_bf16_f32 v57, v58, v59
	ds_write2_b64 v67, v[8:9], v[56:57] offset0:138 offset1:142
	v_mfma_f32_16x16x32_bf16 v[56:59], v[52:55], v[0:3], 0
	v_mfma_f32_16x16x32_bf16 v[52:55], v[52:55], v[4:7], 0
	s_nop 7
	v_pk_mul_f32 v[8:9], v[14:15], v[52:53]
	s_nop 0
	v_pk_fma_f32 v[8:9], v[64:65], v[56:57], v[8:9]
	v_pk_mul_f32 v[56:57], v[14:15], v[56:57]
	v_cvt_pk_bf16_f32 v8, v8, v9
	v_pk_fma_f32 v[52:53], v[64:65], v[52:53], v[56:57] neg_lo:[0,0,1] neg_hi:[0,0,1]
	v_pk_mul_f32 v[56:57], v[10:11], v[54:55]
	v_cvt_pk_bf16_f32 v52, v52, v53
	v_pk_fma_f32 v[56:57], v[12:13], v[58:59], v[56:57]
	v_pk_mul_f32 v[58:59], v[10:11], v[58:59]
	v_cvt_pk_bf16_f32 v9, v56, v57
	v_pk_fma_f32 v[54:55], v[12:13], v[54:55], v[58:59] neg_lo:[0,0,1] neg_hi:[0,0,1]
	v_add_u32_e32 v56, 0x1800, v66
	v_cvt_pk_bf16_f32 v53, v54, v55
	ds_write2_b64 v56, v[8:9], v[52:53] offset0:12 offset1:16
	v_mfma_f32_16x16x32_bf16 v[52:55], v[48:51], v[0:3], 0
	v_mfma_f32_16x16x32_bf16 v[48:51], v[48:51], v[4:7], 0
	s_nop 7
	v_pk_mul_f32 v[8:9], v[14:15], v[48:49]
	s_nop 0
	v_pk_fma_f32 v[8:9], v[64:65], v[52:53], v[8:9]
	v_pk_mul_f32 v[52:53], v[14:15], v[52:53]
	v_cvt_pk_bf16_f32 v8, v8, v9
	v_pk_fma_f32 v[48:49], v[64:65], v[48:49], v[52:53] neg_lo:[0,0,1] neg_hi:[0,0,1]
	v_pk_mul_f32 v[52:53], v[10:11], v[50:51]
	v_cvt_pk_bf16_f32 v48, v48, v49
	v_pk_fma_f32 v[52:53], v[12:13], v[54:55], v[52:53]
	v_pk_mul_f32 v[54:55], v[10:11], v[54:55]
	v_cvt_pk_bf16_f32 v9, v52, v53
	v_pk_fma_f32 v[50:51], v[12:13], v[50:51], v[54:55] neg_lo:[0,0,1] neg_hi:[0,0,1]
	v_mov_b32_e32 v52, 0x1c700
	v_cvt_pk_bf16_f32 v49, v50, v51
	ds_write2_b64 v56, v[8:9], v[48:49] offset0:142 offset1:146
	v_mfma_f32_16x16x32_bf16 v[48:51], v[44:47], v[0:3], 0
	v_mad_u32_u24 v134, v77, s6, v52
	v_mfma_f32_16x16x32_bf16 v[44:47], v[44:47], v[4:7], 0
	s_nop 7
	v_pk_mul_f32 v[8:9], v[14:15], v[44:45]
	s_nop 0
	v_pk_fma_f32 v[8:9], v[64:65], v[48:49], v[8:9]
	v_pk_mul_f32 v[48:49], v[14:15], v[48:49]
	v_cvt_pk_bf16_f32 v8, v8, v9
	v_pk_fma_f32 v[44:45], v[64:65], v[44:45], v[48:49] neg_lo:[0,0,1] neg_hi:[0,0,1]
	v_pk_mul_f32 v[48:49], v[10:11], v[46:47]
	v_cvt_pk_bf16_f32 v44, v44, v45
	v_pk_fma_f32 v[48:49], v[12:13], v[50:51], v[48:49]
	v_pk_mul_f32 v[50:51], v[10:11], v[50:51]
	v_cvt_pk_bf16_f32 v9, v48, v49
	v_pk_fma_f32 v[46:47], v[12:13], v[46:47], v[50:51] neg_lo:[0,0,1] neg_hi:[0,0,1]
	v_add_u32_e32 v48, 0x2000, v66
	v_cvt_pk_bf16_f32 v45, v46, v47
	ds_write2_b64 v48, v[8:9], v[44:45] offset0:16 offset1:20
	v_mfma_f32_16x16x32_bf16 v[44:47], v[40:43], v[0:3], 0
	v_mfma_f32_16x16x32_bf16 v[40:43], v[40:43], v[4:7], 0
	s_nop 7
	v_pk_mul_f32 v[8:9], v[14:15], v[40:41]
	s_nop 0
	v_pk_fma_f32 v[8:9], v[64:65], v[44:45], v[8:9]
	v_pk_mul_f32 v[44:45], v[14:15], v[44:45]
	v_cvt_pk_bf16_f32 v8, v8, v9
	v_pk_fma_f32 v[40:41], v[64:65], v[40:41], v[44:45] neg_lo:[0,0,1] neg_hi:[0,0,1]
	v_pk_mul_f32 v[44:45], v[10:11], v[42:43]
	v_cvt_pk_bf16_f32 v40, v40, v41
	v_pk_fma_f32 v[44:45], v[12:13], v[46:47], v[44:45]
	v_pk_mul_f32 v[46:47], v[10:11], v[46:47]
	v_cvt_pk_bf16_f32 v9, v44, v45
	v_pk_fma_f32 v[42:43], v[12:13], v[42:43], v[46:47] neg_lo:[0,0,1] neg_hi:[0,0,1]
	s_nop 0
	v_cvt_pk_bf16_f32 v41, v42, v43
	ds_write2_b64 v48, v[8:9], v[40:41] offset0:146 offset1:150
	v_mfma_f32_16x16x32_bf16 v[40:43], v[36:39], v[0:3], 0
	v_mfma_f32_16x16x32_bf16 v[36:39], v[36:39], v[4:7], 0
	s_nop 7
	v_pk_mul_f32 v[8:9], v[14:15], v[36:37]
	s_nop 0
	v_pk_fma_f32 v[8:9], v[64:65], v[40:41], v[8:9]
	v_pk_mul_f32 v[40:41], v[14:15], v[40:41]
	v_cvt_pk_bf16_f32 v8, v8, v9
	v_pk_fma_f32 v[36:37], v[64:65], v[36:37], v[40:41] neg_lo:[0,0,1] neg_hi:[0,0,1]
	v_pk_mul_f32 v[40:41], v[10:11], v[38:39]
	v_cvt_pk_bf16_f32 v36, v36, v37
	v_pk_fma_f32 v[40:41], v[12:13], v[42:43], v[40:41]
	v_pk_mul_f32 v[42:43], v[10:11], v[42:43]
	v_cvt_pk_bf16_f32 v9, v40, v41
; #define LAS __attribute__((address_space(3)))
; __device__ __forceinline__ unsigned cvtpk(float lo, float hi) { f32x2 v = {lo, hi}; bf16x2_t b = __builtin_convertvector(v, bf16x2_t); return __builtin_bit_cast(unsigned, b); }
; __device__ __forceinline__ void b_unit(Frame& F, int u, bool dry) {
;     ...
;         for (int i = 0; i < 16; ++i) {
;             u32x4 f4; f4.x = q0[i].x; f4.y = q0[i].y; f4.z = q1[i].x; f4.w = q1[i].y;
;             const bf16x8 frag = __builtin_bit_cast(bf16x8, f4);
;             const f32x4 dr = __builtin_amdgcn_mfma_f32_16x16x32_bf16(frag, Wr, zero4, 0, 0, 0), di = __builtin_amdgcn_mfma_f32_16x16x32_bf16(frag, Wi, zero4, 0, 0, 0);
;             float vr[4], vi[4];
; #pragma unroll
;             for (int j = 0; j < 4; ++j) { vr[j] = dr[j] * t2[j].x + di[j] * t2[j].y; vi[j] = di[j] * t2[j].x - dr[j] * t2[j].y; }
;             u32x2 o; o.x = cvtpk(vr[0], vr[1]); o.y = cvtpk(vr[2], vr[3]); *(LAS u32x2*)(vrow + i * 1040) = o;
;             o.x = cvtpk(vi[0], vi[1]); o.y = cvtpk(vi[2], vi[3]); *(LAS u32x2*)(vrow + i * 1040 + 32) = o;
;         }
;         __syncthreads();
; #pragma unroll
;         for (int cc = 0; cc < 2; ++cc)
; #pragma unroll
;             for (int lb = 0; lb < 8; ++lb) {
;                 const bf16x8 frag = *(const LAS bf16x8*)(Bt + (size_t)(16 * lb + fr) * 1040 + 64 * (2 * w + cc) + 16 * fq);
;                 ur[cc][lb] = __builtin_amdgcn_mfma_f32_16x16x32_bf16(frag, Wr, zero4, 0, 0, 0);
;                 ui[cc][lb] = __builtin_amdgcn_mfma_f32_16x16x32_bf16(frag, Wi, zero4, 0, 0, 0);
;             }
	v_pk_fma_f32 v[38:39], v[12:13], v[38:39], v[42:43] neg_lo:[0,0,1] neg_hi:[0,0,1]
	v_add_u32_e32 v40, 0x2800, v66
	v_cvt_pk_bf16_f32 v37, v38, v39
	ds_write2_b64 v40, v[8:9], v[36:37] offset0:20 offset1:24
	v_mfma_f32_16x16x32_bf16 v[36:39], v[32:35], v[0:3], 0
	v_mfma_f32_16x16x32_bf16 v[32:35], v[32:35], v[4:7], 0
	s_nop 7
	v_pk_mul_f32 v[8:9], v[14:15], v[32:33]
	s_nop 0
	v_pk_fma_f32 v[8:9], v[64:65], v[36:37], v[8:9]
	v_pk_mul_f32 v[36:37], v[14:15], v[36:37]
	v_cvt_pk_bf16_f32 v8, v8, v9
	v_pk_fma_f32 v[32:33], v[64:65], v[32:33], v[36:37] neg_lo:[0,0,1] neg_hi:[0,0,1]
	v_pk_mul_f32 v[36:37], v[10:11], v[34:35]
	v_cvt_pk_bf16_f32 v32, v32, v33
	v_pk_fma_f32 v[36:37], v[12:13], v[38:39], v[36:37]
	v_pk_mul_f32 v[38:39], v[10:11], v[38:39]
	v_cvt_pk_bf16_f32 v9, v36, v37
	v_pk_fma_f32 v[34:35], v[12:13], v[34:35], v[38:39] neg_lo:[0,0,1] neg_hi:[0,0,1]
	s_nop 0
	v_cvt_pk_bf16_f32 v33, v34, v35
	ds_write2_b64 v40, v[8:9], v[32:33] offset0:150 offset1:154
	v_mfma_f32_16x16x32_bf16 v[32:35], v[28:31], v[0:3], 0
	v_mov_b32_e32 v40, 0x14500
	v_mad_u32_u24 v118, v77, s6, v40
	v_mfma_f32_16x16x32_bf16 v[28:31], v[28:31], v[4:7], 0
	s_nop 7
	v_pk_mul_f32 v[8:9], v[14:15], v[28:29]
	s_nop 0
	v_pk_fma_f32 v[8:9], v[64:65], v[32:33], v[8:9]
	v_pk_mul_f32 v[32:33], v[14:15], v[32:33]
	v_cvt_pk_bf16_f32 v8, v8, v9
	v_pk_fma_f32 v[28:29], v[64:65], v[28:29], v[32:33] neg_lo:[0,0,1] neg_hi:[0,0,1]
	v_pk_mul_f32 v[32:33], v[10:11], v[30:31]
	v_cvt_pk_bf16_f32 v28, v28, v29
	v_pk_fma_f32 v[32:33], v[12:13], v[34:35], v[32:33]
	v_pk_mul_f32 v[34:35], v[10:11], v[34:35]
	v_cvt_pk_bf16_f32 v9, v32, v33
	v_pk_fma_f32 v[30:31], v[12:13], v[30:31], v[34:35] neg_lo:[0,0,1] neg_hi:[0,0,1]
	v_add_u32_e32 v32, 0x3000, v66
	v_cvt_pk_bf16_f32 v29, v30, v31
	ds_write2_b64 v32, v[8:9], v[28:29] offset0:24 offset1:28
	v_mfma_f32_16x16x32_bf16 v[28:31], v[24:27], v[0:3], 0
	v_mfma_f32_16x16x32_bf16 v[24:27], v[24:27], v[4:7], 0
	s_nop 7
	v_pk_mul_f32 v[8:9], v[14:15], v[24:25]
	s_nop 0
	v_pk_fma_f32 v[8:9], v[64:65], v[28:29], v[8:9]
	v_pk_mul_f32 v[28:29], v[14:15], v[28:29]
	v_cvt_pk_bf16_f32 v8, v8, v9
	v_pk_fma_f32 v[24:25], v[64:65], v[24:25], v[28:29] neg_lo:[0,0,1] neg_hi:[0,0,1]
	v_pk_mul_f32 v[28:29], v[10:11], v[26:27]
	v_cvt_pk_bf16_f32 v24, v24, v25
	v_pk_fma_f32 v[28:29], v[12:13], v[30:31], v[28:29]
	v_pk_mul_f32 v[30:31], v[10:11], v[30:31]
	v_cvt_pk_bf16_f32 v9, v28, v29
	v_pk_fma_f32 v[26:27], v[12:13], v[26:27], v[30:31] neg_lo:[0,0,1] neg_hi:[0,0,1]
	s_nop 0
	v_cvt_pk_bf16_f32 v25, v26, v27
	ds_write2_b64 v32, v[8:9], v[24:25] offset0:154 offset1:158
	v_mfma_f32_16x16x32_bf16 v[24:27], v[20:23], v[0:3], 0
	v_mfma_f32_16x16x32_bf16 v[20:23], v[20:23], v[4:7], 0
	s_nop 7
	v_pk_mul_f32 v[8:9], v[14:15], v[20:21]
	s_nop 0
	v_pk_fma_f32 v[8:9], v[64:65], v[24:25], v[8:9]
	v_pk_mul_f32 v[24:25], v[14:15], v[24:25]
	v_cvt_pk_bf16_f32 v8, v8, v9
	v_pk_fma_f32 v[20:21], v[64:65], v[20:21], v[24:25] neg_lo:[0,0,1] neg_hi:[0,0,1]
	v_pk_mul_f32 v[24:25], v[10:11], v[22:23]
	v_cvt_pk_bf16_f32 v20, v20, v21
	v_pk_fma_f32 v[24:25], v[12:13], v[26:27], v[24:25]
	v_pk_mul_f32 v[26:27], v[10:11], v[26:27]
	v_cvt_pk_bf16_f32 v9, v24, v25
	v_pk_fma_f32 v[22:23], v[12:13], v[22:23], v[26:27] neg_lo:[0,0,1] neg_hi:[0,0,1]
	v_add_u32_e32 v24, 0x3800, v66
	v_cvt_pk_bf16_f32 v21, v22, v23
	ds_write2_b64 v24, v[8:9], v[20:21] offset0:28 offset1:32
	v_mfma_f32_16x16x32_bf16 v[20:23], v[16:19], v[0:3], 0
	v_mfma_f32_16x16x32_bf16 v[16:19], v[16:19], v[4:7], 0
	s_nop 7
	v_pk_mul_f32 v[8:9], v[14:15], v[16:17]
	v_pk_mul_f32 v[14:15], v[14:15], v[20:21]
	v_pk_fma_f32 v[8:9], v[64:65], v[20:21], v[8:9]
	v_pk_fma_f32 v[14:15], v[64:65], v[16:17], v[14:15] neg_lo:[0,0,1] neg_hi:[0,0,1]
	v_pk_mul_f32 v[16:17], v[10:11], v[18:19]
	v_pk_mul_f32 v[10:11], v[10:11], v[22:23]
	v_pk_fma_f32 v[16:17], v[12:13], v[22:23], v[16:17]
	v_pk_fma_f32 v[10:11], v[12:13], v[18:19], v[10:11] neg_lo:[0,0,1] neg_hi:[0,0,1]
	v_cvt_pk_bf16_f32 v8, v8, v9
	v_cvt_pk_bf16_f32 v9, v16, v17
	v_cvt_pk_bf16_f32 v12, v14, v15
	v_cvt_pk_bf16_f32 v13, v10, v11
	ds_write2_b64 v24, v[8:9], v[12:13] offset0:158 offset1:162
	v_and_b32_e32 v8, 48, v170
	v_mov_b32_e32 v16, 0x10400
	v_add_u32_e32 v78, s0, v8
	v_mad_u32_u24 v110, v77, s6, v16
	v_add_u32_e32 v16, v78, v110
	v_add_u32_e32 v40, v78, v118
	s_waitcnt lgkmcnt(0)
	s_barrier
	ds_read_b128 v[16:19], v16
	ds_read_b128 v[40:43], v40
	s_waitcnt lgkmcnt(0)
	v_mfma_f32_16x16x32_bf16 v[64:67], v[40:43], v[0:3], 0
	v_add_u32_e32 v52, v78, v134
	ds_read_b128 v[52:55], v52
	v_mad_u32_u24 v102, v77, s6, v78
	v_mfma_f32_16x16x32_bf16 v[56:59], v[40:43], v[4:7], 0
	v_mov_b32_e32 v40, 0x18600
	v_mad_u32_u24 v126, v77, s6, v40
	v_add_u32_e32 v40, v78, v126
	ds_read_b128 v[40:43], v40
	ds_read_b128 v[8:11], v102
	s_waitcnt lgkmcnt(2)
	v_mfma_f32_16x16x32_bf16 v[72:75], v[52:55], v[0:3], 0
	v_add_u32_e32 v135, 64, v78
	ds_read_b128 v[12:15], v102 offset:49920
	s_mov_b32 s0, 0x1dd6000
	v_mfma_f32_16x16x32_bf16 v[68:71], v[52:55], v[4:7], 0
	ds_read_b128 v[52:55], v102 offset:64
	s_waitcnt lgkmcnt(2)
	v_mfma_f32_16x16x32_bf16 v[36:39], v[8:11], v[0:3], 0
	v_mfma_f32_16x16x32_bf16 v[20:23], v[8:11], v[4:7], 0
	ds_read_b128 v[8:11], v102 offset:16640
	s_waitcnt lgkmcnt(1)
	v_mfma_f32_16x16x32_bf16 v[78:81], v[52:55], v[0:3], 0
	v_mfma_f32_16x16x32_bf16 v[82:85], v[52:55], v[4:7], 0
	ds_read_b128 v[52:55], v102 offset:16704
	s_waitcnt lgkmcnt(1)
	v_mfma_f32_16x16x32_bf16 v[48:51], v[8:11], v[0:3], 0
	v_mfma_f32_16x16x32_bf16 v[24:27], v[8:11], v[4:7], 0
	ds_read_b128 v[8:11], v102 offset:33280
	s_waitcnt lgkmcnt(1)
	v_mfma_f32_16x16x32_bf16 v[86:89], v[52:55], v[0:3], 0
	v_mfma_f32_16x16x32_bf16 v[90:93], v[52:55], v[4:7], 0
	ds_read_b128 v[52:55], v102 offset:33344
	s_waitcnt lgkmcnt(0)
	v_mfma_f32_16x16x32_bf16 v[94:97], v[52:55], v[0:3], 0
	v_mfma_f32_16x16x32_bf16 v[98:101], v[52:55], v[4:7], 0
	ds_read_b128 v[52:55], v102 offset:49984
	s_waitcnt lgkmcnt(0)
	v_mfma_f32_16x16x32_bf16 v[102:105], v[52:55], v[0:3], 0
	v_mfma_f32_16x16x32_bf16 v[106:109], v[52:55], v[4:7], 0
	v_add_u32_e32 v52, v135, v110
	ds_read_b128 v[52:55], v52
	s_waitcnt lgkmcnt(0)
	v_mfma_f32_16x16x32_bf16 v[110:113], v[52:55], v[0:3], 0
	v_mfma_f32_16x16x32_bf16 v[114:117], v[52:55], v[4:7], 0
	v_add_u32_e32 v52, v135, v118
	ds_read_b128 v[52:55], v52
	s_waitcnt lgkmcnt(0)
	v_mfma_f32_16x16x32_bf16 v[118:121], v[52:55], v[0:3], 0
	v_mfma_f32_16x16x32_bf16 v[122:125], v[52:55], v[4:7], 0
	v_add_u32_e32 v52, v135, v126
	ds_read_b128 v[52:55], v52
	s_waitcnt lgkmcnt(0)
	v_mfma_f32_16x16x32_bf16 v[126:129], v[52:55], v[0:3], 0
	v_mfma_f32_16x16x32_bf16 v[130:133], v[52:55], v[4:7], 0
	v_add_u32_e32 v52, v135, v134
	ds_read_b128 v[52:55], v52
	s_waitcnt lgkmcnt(0)
	v_mfma_f32_16x16x32_bf16 v[44:47], v[16:19], v[0:3], 0
	s_barrier
; #define LAS __attribute__((address_space(3)))
; #define GAS __attribute__((address_space(1)))
; __device__ __forceinline__ unsigned cvtpk(float lo, float hi) { f32x2 v = {lo, hi}; bf16x2_t b = __builtin_convertvector(v, bf16x2_t); return __builtin_bit_cast(unsigned, b); }
; __device__ __forceinline__ void b_unit(Frame& F, int u, bool dry) {
;     ...
;     bf16x8 yr[2][4], yi[2][4];
; #pragma unroll
;     for (int mb = 0; mb < 2; ++mb)
; #pragma unroll
;         for (int t = 0; t < 4; ++t) {
;             u32x4 p; p.x = cvtpk(ur[mb][2 * t][0], ur[mb][2 * t][1]); p.y = cvtpk(ur[mb][2 * t][2], ur[mb][2 * t][3]); p.z = cvtpk(ur[mb][2 * t + 1][0], ur[mb][2 * t + 1][1]); p.w = cvtpk(ur[mb][2 * t + 1][2], ur[mb][2 * t + 1][3]);
;             yr[mb][t] = __builtin_bit_cast(bf16x8, p);
;             p.x = cvtpk(ui[mb][2 * t][0], ui[mb][2 * t][1]); p.y = cvtpk(ui[mb][2 * t][2], ui[mb][2 * t][3]); p.z = cvtpk(ui[mb][2 * t + 1][0], ui[mb][2 * t + 1][1]); p.w = cvtpk(ui[mb][2 * t + 1][2], ui[mb][2 * t + 1][3]);
;             yi[mb][t] = __builtin_bit_cast(bf16x8, p);
;         }
;     bf16_t* SBG = (bf16_t*)(ws_ + WS_SBG);
;     __syncthreads();
;     {   const GAS u32x4* src = (const GAS u32x4*)(ws_ + WS_GT) + (w * 64 + lane); u32x4 tv[8];
; #pragma unroll
;         for (int i = 0; i < 8; ++i) tv[i] = src[i * 512];
; #pragma unroll
;         for (int i = 0; i < 8; ++i) *(LAS u32x4*)(Bt + (size_t)(i * 512 + w * 64 + lane) * 16) = tv[i]; }
;     u32x4 sbq[4][2];
; #pragma unroll
;     for (int p = 0; p < 4; ++p)
; #pragma unroll
;         for (int mb = 0; mb < 2; ++mb) { const int k1 = 2 * w + mb + 16 * fr; const size_t tok = (size_t)b * SEQ + 8 * k1 + k2; sbq[p][mb] = *(const GAS u32x4*)(SBG + tok * 512 + g * 128 + 32 * p + 8 * fq); }
;     __syncthreads();
	v_mfma_f32_16x16x32_bf16 v[60:63], v[40:43], v[0:3], 0
	v_mfma_f32_16x16x32_bf16 v[40:43], v[40:43], v[4:7], 0
	v_mfma_f32_16x16x32_bf16 v[134:137], v[52:55], v[0:3], 0
	v_mfma_f32_16x16x32_bf16 v[138:141], v[52:55], v[4:7], 0
	v_cvt_pk_bf16_f32 v54, v48, v49
	v_cvt_pk_bf16_f32 v48, v20, v21
	s_nop 0
	v_cvt_pk_bf16_f32 v20, v44, v45
	v_cvt_pk_bf16_f32 v44, v98, v99
	v_or_b32_e32 v98, s70, v171
	v_ashrrev_i32_e32 v99, 31, v98
	v_mfma_f32_16x16x32_bf16 v[28:31], v[8:11], v[0:3], 0
	v_cvt_pk_bf16_f32 v49, v22, v23
	v_cvt_pk_bf16_f32 v22, v64, v65
	v_cvt_pk_bf16_f32 v53, v38, v39
	v_mfma_f32_16x16x32_bf16 v[32:35], v[12:15], v[0:3], 0
	v_cvt_pk_bf16_f32 v0, v40, v41
	v_cvt_pk_bf16_f32 v40, v94, v95
	v_lshl_add_u64 v[94:95], v[98:99], 4, s[2:3]
	v_mfma_f32_16x16x32_bf16 v[8:11], v[8:11], v[4:7], 0
	v_add_co_u32_e32 v64, vcc, s8, v94
	v_cvt_pk_bf16_f32 v2, v68, v69
	s_nop 0
	v_addc_co_u32_e32 v65, vcc, 0, v95, vcc
	v_mfma_f32_16x16x32_bf16 v[16:19], v[16:19], v[4:7], 0
	v_add_co_u32_e32 v68, vcc, s0, v94
	s_mov_b32 s0, 0x1dd8000
	s_nop 0
	v_addc_co_u32_e32 v69, vcc, 0, v95, vcc
	v_cvt_pk_bf16_f32 v38, v32, v33
	v_cvt_pk_bf16_f32 v33, v10, v11
	v_cvt_pk_bf16_f32 v10, v72, v73
	v_add_co_u32_e32 v72, vcc, s0, v94
	s_mov_b32 s0, 0x1dda000
	s_nop 0
	v_addc_co_u32_e32 v73, vcc, 0, v95, vcc
	v_cvt_pk_bf16_f32 v16, v16, v17
	v_cvt_pk_bf16_f32 v17, v18, v19
	v_cvt_pk_bf16_f32 v18, v56, v57
	v_cvt_pk_bf16_f32 v56, v78, v79
	v_add_co_u32_e32 v78, vcc, s0, v94
	s_mov_b32 s0, 0x1ddc000
	s_nop 0
	v_addc_co_u32_e32 v79, vcc, 0, v95, vcc
	v_cvt_pk_bf16_f32 v32, v8, v9
	v_cvt_pk_bf16_f32 v8, v60, v61
	v_cvt_pk_bf16_f32 v60, v82, v83
	v_add_co_u32_e32 v82, vcc, s0, v94
	v_cvt_pk_bf16_f32 v23, v66, v67
	global_load_dwordx4 v[64:67], v[64:65], off offset:64
	v_addc_co_u32_e32 v83, vcc, 0, v95, vcc
	s_mov_b32 s0, 0x1dde000
	v_cvt_pk_bf16_f32 v19, v58, v59
	v_cvt_pk_bf16_f32 v3, v70, v71
	v_cvt_pk_bf16_f32 v58, v86, v87
	global_load_dwordx4 v[68:71], v[68:69], off offset:64
	v_add_co_u32_e32 v86, vcc, s0, v94
	v_cvt_pk_bf16_f32 v11, v74, v75
	global_load_dwordx4 v[72:75], v[72:73], off offset:64
	v_addc_co_u32_e32 v87, vcc, 0, v95, vcc
	s_mov_b32 s0, 0x1de0000
	v_cvt_pk_bf16_f32 v9, v62, v63
	v_cvt_pk_bf16_f32 v57, v80, v81
	v_cvt_pk_bf16_f32 v62, v90, v91
	global_load_dwordx4 v[78:81], v[78:79], off offset:64
	v_add_co_u32_e32 v90, vcc, s0, v94
	v_cvt_pk_bf16_f32 v61, v84, v85
	global_load_dwordx4 v[82:85], v[82:83], off offset:64
	v_addc_co_u32_e32 v91, vcc, 0, v95, vcc
	s_mov_b32 s0, 0x1de2000
	v_cvt_pk_bf16_f32 v59, v88, v89
	global_load_dwordx4 v[86:89], v[86:87], off offset:64
	v_add_co_u32_e32 v94, vcc, s0, v94
	v_cvt_pk_bf16_f32 v63, v92, v93
	global_load_dwordx4 v[90:93], v[90:91], off offset:64
	v_addc_co_u32_e32 v95, vcc, 0, v95, vcc
	v_cvt_pk_bf16_f32 v41, v96, v97
	global_load_dwordx4 v[94:97], v[94:95], off offset:64
	v_lshl_add_u32 v98, v98, 4, 0
	v_readlane_b32 s0, v253, 51
	s_waitcnt vmcnt(7)
	ds_write_b128 v98, v[64:67]
	s_waitcnt vmcnt(6)
	ds_write_b128 v98, v[68:71] offset:8192
	s_waitcnt vmcnt(5)
	ds_write_b128 v98, v[72:75] offset:16384
	s_waitcnt vmcnt(4)
	ds_write_b128 v98, v[78:81] offset:24576
	s_waitcnt vmcnt(3)
	ds_write_b128 v98, v[82:85] offset:32768
	s_waitcnt vmcnt(2)
	ds_write_b128 v98, v[86:89] offset:40960
	s_waitcnt vmcnt(1)
	ds_write_b128 v98, v[90:93] offset:49152
	s_waitcnt vmcnt(0)
	ds_write_b128 v98, v[94:97] offset:57344
	v_lshl_add_u32 v64, v77, 7, s0
	v_readlane_b32 s0, v254, 31
	s_add_u32 s0, s2, s0
	s_addc_u32 s1, s3, 0
	v_lshl_add_u64 v[66:67], s[0:1], 0, v[192:193]
	s_mov_b64 s[0:1], 0xa000000
	v_lshl_add_u64 v[66:67], v[66:67], 0, s[0:1]
	v_readlane_b32 s0, v254, 21
	v_mov_b32_e32 v65, v193
	v_readlane_b32 s1, v254, 22
	v_or_b32_e32 v192, 8, v64
	v_cvt_pk_bf16_f32 v45, v100, v101
	v_lshl_add_u64 v[68:69], s[0:1], 0, v[64:65]
	v_lshlrev_b64 v[68:69], 10, v[68:69]
	v_lshl_add_u64 v[98:99], v[66:67], 0, v[68:69]
	global_load_dwordx4 v[92:95], v[98:99], off sc1
	v_lshl_add_u64 v[64:65], s[0:1], 0, v[192:193]
	v_lshlrev_b32_e32 v100, 4, v170
	v_lshlrev_b64 v[64:65], 10, v[64:65]
	v_and_b32_e32 v100, 0x3f0, v100
	v_lshl_add_u64 v[96:97], v[66:67], 0, v[64:65]
	v_add_u32_e32 v100, 0, v100
	v_cvt_pk_bf16_f32 v21, v46, v47
	v_cvt_pk_bf16_f32 v1, v42, v43
	v_cvt_pk_bf16_f32 v42, v102, v103
	v_cvt_pk_bf16_f32 v43, v104, v105
	v_cvt_pk_bf16_f32 v46, v106, v107
	v_cvt_pk_bf16_f32 v47, v108, v109
	global_load_dwordx4 v[88:91], v[96:97], off sc1
	global_load_dwordx4 v[84:87], v[98:99], off offset:64 sc1
	global_load_dwordx4 v[80:83], v[96:97], off offset:64 sc1
	global_load_dwordx4 v[76:79], v[98:99], off offset:128 sc1
	global_load_dwordx4 v[72:75], v[96:97], off offset:128 sc1
	global_load_dwordx4 v[68:71], v[98:99], off offset:192 sc1
	global_load_dwordx4 v[64:67], v[96:97], off offset:192 sc1
	s_waitcnt lgkmcnt(0)
	s_barrier
; #define LAS __attribute__((address_space(3)))
; #define GAS __attribute__((address_space(1)))
; __device__ __forceinline__ unsigned cvtpk(float lo, float hi) { f32x2 v = {lo, hi}; bf16x2_t b = __builtin_convertvector(v, bf16x2_t); return __builtin_bit_cast(unsigned, b); }
; __device__ __forceinline__ float bflo(unsigned w) { return __uint_as_float(w << 16); }
; __device__ __forceinline__ float bfhi(unsigned w) { return __uint_as_float(w & 0xffff0000u); }
; __device__ __forceinline__ void b_unit(Frame& F, int u, bool dry) {
;     ...
;     const LAS unsigned char* XF = Bt + (size_t)(fq * 16 + fr) * 16;
; #pragma unroll
;     for (int p = 0; p < 4; ++p) {
;         f32x4 o3[2][2];
; #pragma unroll
;         for (int h = 0; h < 2; ++h) { const int lb = 2 * p + h;
;             o3[h][0] = (f32x4){0.f, 0.f, 0.f, 0.f}; o3[h][1] = (f32x4){0.f, 0.f, 0.f, 0.f};
; #pragma unroll
;             for (int t = 0; t < 4; ++t) {
;                 const bf16x8 xc = *(const LAS bf16x8*)(XF + (size_t)((lb * 4 + t) * 2 + 0) * 1024), xs = *(const LAS bf16x8*)(XF + (size_t)((lb * 4 + t) * 2 + 1) * 1024);
; #pragma unroll
;                 for (int mb = 0; mb < 2; ++mb) { o3[h][mb] = __builtin_amdgcn_mfma_f32_16x16x32_bf16(xc, yr[mb][t], o3[h][mb], 0, 0, 0); o3[h][mb] = __builtin_amdgcn_mfma_f32_16x16x32_bf16(xs, yi[mb][t], o3[h][mb], 0, 0, 0); }
;             }
;         }
; #pragma unroll
;         for (int mb = 0; mb < 2; ++mb) { const int k1 = 2 * w + mb + 16 * fr; const size_t tok = (size_t)b * SEQ + 8 * k1 + k2; const u32x4 sb = sbq[p][mb]; const f32x4 a0 = o3[0][mb] * 0.001953125f, a1 = o3[1][mb] * 0.001953125f;
;             u32x4 o; o.x = cvtpk(bflo(sb.x) * a0[0], bfhi(sb.x) * a0[1]); o.y = cvtpk(bflo(sb.y) * a0[2], bfhi(sb.y) * a0[3]); o.z = cvtpk(bflo(sb.z) * a1[0], bfhi(sb.z) * a1[1]); o.w = cvtpk(bflo(sb.w) * a1[2], bfhi(sb.w) * a1[3]);
;             if (!dry) *(GAS u32x4*)(SBG + tok * 512 + g * 128 + 32 * p + 8 * fq) = o; }
;     }
	ds_read_b128 v[102:105], v100
	ds_read_b128 v[106:109], v100 offset:1024
	v_cvt_pk_bf16_f32 v52, v36, v37
	v_cvt_pk_bf16_f32 v55, v50, v51
	v_cvt_pk_bf16_f32 v50, v24, v25
	v_cvt_pk_bf16_f32 v24, v110, v111
	v_cvt_pk_bf16_f32 v25, v112, v113
	s_waitcnt lgkmcnt(1)
	v_mfma_f32_16x16x32_bf16 v[110:113], v[102:105], v[52:55], 0
	v_cvt_pk_bf16_f32 v51, v26, v27
	v_cvt_pk_bf16_f32 v36, v28, v29
	v_cvt_pk_bf16_f32 v28, v114, v115
	v_mfma_f32_16x16x32_bf16 v[102:105], v[102:105], v[56:59], 0
	v_cvt_pk_bf16_f32 v29, v116, v117
	v_cvt_pk_bf16_f32 v37, v30, v31
	v_cvt_pk_bf16_f32 v39, v34, v35
	s_waitcnt lgkmcnt(0)
	v_mfma_f32_16x16x32_bf16 v[110:113], v[106:109], v[48:51], v[110:113]
	v_cvt_pk_bf16_f32 v26, v118, v119
	v_cvt_pk_bf16_f32 v27, v120, v121
	v_cvt_pk_bf16_f32 v30, v122, v123
	v_mfma_f32_16x16x32_bf16 v[102:105], v[106:109], v[60:63], v[102:105]
	ds_read_b128 v[106:109], v100 offset:2048
	ds_read_b128 v[114:117], v100 offset:3072
	v_cvt_pk_bf16_f32 v31, v124, v125
	s_mov_b32 s0, 0x3b000000
	v_mfma_f32_16x16x32_bf16 v[12:15], v[12:15], v[4:7], 0
	v_cvt_pk_bf16_f32 v4, v130, v131
	v_cvt_pk_bf16_f32 v5, v132, v133
	v_cvt_pk_bf16_f32 v6, v138, v139
	s_waitcnt lgkmcnt(1)
	v_mfma_f32_16x16x32_bf16 v[110:113], v[106:109], v[36:39], v[110:113]
	v_cvt_pk_bf16_f32 v7, v140, v141
	s_nop 1
	v_cvt_pk_bf16_f32 v34, v12, v13
	v_cvt_pk_bf16_f32 v35, v14, v15
	v_mfma_f32_16x16x32_bf16 v[102:105], v[106:109], v[40:43], v[102:105]
	v_cvt_pk_bf16_f32 v12, v126, v127
	v_cvt_pk_bf16_f32 v13, v128, v129
	v_cvt_pk_bf16_f32 v14, v134, v135
	s_waitcnt lgkmcnt(0)
	v_mfma_f32_16x16x32_bf16 v[110:113], v[114:117], v[32:35], v[110:113]
	v_cvt_pk_bf16_f32 v15, v136, v137
	v_mfma_f32_16x16x32_bf16 v[102:105], v[114:117], v[44:47], v[102:105]
	ds_read_b128 v[106:109], v100 offset:4096
	ds_read_b128 v[114:117], v100 offset:5120
	s_waitcnt lgkmcnt(1)
	v_mfma_f32_16x16x32_bf16 v[110:113], v[106:109], v[20:23], v[110:113]
	v_mfma_f32_16x16x32_bf16 v[102:105], v[106:109], v[24:27], v[102:105]
	s_waitcnt lgkmcnt(0)
	v_mfma_f32_16x16x32_bf16 v[110:113], v[114:117], v[16:19], v[110:113]
	v_mfma_f32_16x16x32_bf16 v[102:105], v[114:117], v[28:31], v[102:105]
	ds_read_b128 v[106:109], v100 offset:6144
	ds_read_b128 v[114:117], v100 offset:7168
	s_waitcnt lgkmcnt(1)
	v_mfma_f32_16x16x32_bf16 v[110:113], v[106:109], v[8:11], v[110:113]
	v_mfma_f32_16x16x32_bf16 v[102:105], v[106:109], v[12:15], v[102:105]
	s_waitcnt lgkmcnt(0)
	v_mfma_f32_16x16x32_bf16 v[110:113], v[114:117], v[0:3], v[110:113]
	v_mfma_f32_16x16x32_bf16 v[102:105], v[114:117], v[4:7], v[102:105]
	ds_read_b128 v[106:109], v100 offset:8192
	ds_read_b128 v[114:117], v100 offset:9216
	s_nop 4
	v_pk_mul_f32 v[110:111], v[110:111], s[0:1] op_sel_hi:[1,0]
	v_pk_mul_f32 v[112:113], v[112:113], s[0:1] op_sel_hi:[1,0]
	s_waitcnt lgkmcnt(1)
	v_mfma_f32_16x16x32_bf16 v[118:121], v[106:109], v[52:55], 0
	v_mfma_f32_16x16x32_bf16 v[106:109], v[106:109], v[56:59], 0
	s_waitcnt lgkmcnt(0)
	v_mfma_f32_16x16x32_bf16 v[118:121], v[114:117], v[48:51], v[118:121]
	v_mfma_f32_16x16x32_bf16 v[106:109], v[114:117], v[60:63], v[106:109]
	ds_read_b128 v[114:117], v100 offset:10240
	ds_read_b128 v[122:125], v100 offset:11264
	s_waitcnt lgkmcnt(1)
	v_mfma_f32_16x16x32_bf16 v[118:121], v[114:117], v[36:39], v[118:121]
	v_mfma_f32_16x16x32_bf16 v[106:109], v[114:117], v[40:43], v[106:109]
	s_waitcnt lgkmcnt(0)
	v_mfma_f32_16x16x32_bf16 v[118:121], v[122:125], v[32:35], v[118:121]
	v_mfma_f32_16x16x32_bf16 v[106:109], v[122:125], v[44:47], v[106:109]
	ds_read_b128 v[114:117], v100 offset:12288
	ds_read_b128 v[122:125], v100 offset:13312
	s_waitcnt lgkmcnt(1)
	v_mfma_f32_16x16x32_bf16 v[118:121], v[114:117], v[20:23], v[118:121]
	v_mfma_f32_16x16x32_bf16 v[106:109], v[114:117], v[24:27], v[106:109]
	s_waitcnt lgkmcnt(0)
	v_mfma_f32_16x16x32_bf16 v[118:121], v[122:125], v[16:19], v[118:121]
	v_mfma_f32_16x16x32_bf16 v[106:109], v[122:125], v[28:31], v[106:109]
	ds_read_b128 v[114:117], v100 offset:14336
	ds_read_b128 v[122:125], v100 offset:15360
	s_waitcnt lgkmcnt(1)
	v_mfma_f32_16x16x32_bf16 v[118:121], v[114:117], v[8:11], v[118:121]
	s_waitcnt lgkmcnt(0)
	v_mfma_f32_16x16x32_bf16 v[118:121], v[122:125], v[0:3], v[118:121]
	v_mfma_f32_16x16x32_bf16 v[106:109], v[114:117], v[12:15], v[106:109]
	v_mfma_f32_16x16x32_bf16 v[106:109], v[122:125], v[4:7], v[106:109]
	s_nop 5
	v_mul_f32_e64 v116, v118, s0
	v_mul_f32_e64 v117, v119, s0
	s_waitcnt vmcnt(7)
	v_lshlrev_b32_e32 v118, 16, v92
	v_and_b32_e32 v119, 0xffff0000, v92
	v_pk_mul_f32 v[110:111], v[110:111], v[118:119]
	v_pk_mul_f32 v[114:115], v[120:121], s[0:1] op_sel_hi:[1,0]
	v_cvt_pk_bf16_f32 v92, v110, v111
	v_lshlrev_b32_e32 v110, 16, v93
	v_and_b32_e32 v111, 0xffff0000, v93
	v_pk_mul_f32 v[110:111], v[112:113], v[110:111]
	s_nop 0
	v_cvt_pk_bf16_f32 v93, v110, v111
	v_lshlrev_b32_e32 v110, 16, v94
	v_and_b32_e32 v111, 0xffff0000, v94
	v_pk_mul_f32 v[110:111], v[116:117], v[110:111]
	s_nop 0
	v_cvt_pk_bf16_f32 v94, v110, v111
	v_lshlrev_b32_e32 v110, 16, v95
	v_and_b32_e32 v111, 0xffff0000, v95
	v_pk_mul_f32 v[110:111], v[114:115], v[110:111]
	s_nop 0
	v_cvt_pk_bf16_f32 v95, v110, v111
	global_store_dwordx4 v[98:99], v[92:95], off
	s_nop 1
	v_pk_mul_f32 v[92:93], v[104:105], s[0:1] op_sel_hi:[1,0]
	v_pk_mul_f32 v[94:95], v[102:103], s[0:1] op_sel_hi:[1,0]
	v_pk_mul_f32 v[104:105], v[106:107], s[0:1] op_sel_hi:[1,0]
	s_waitcnt vmcnt(7)
; #define LAS __attribute__((address_space(3)))
; #define GAS __attribute__((address_space(1)))
; __device__ __forceinline__ unsigned cvtpk(float lo, float hi) { f32x2 v = {lo, hi}; bf16x2_t b = __builtin_convertvector(v, bf16x2_t); return __builtin_bit_cast(unsigned, b); }
; __device__ __forceinline__ float bflo(unsigned w) { return __uint_as_float(w << 16); }
; __device__ __forceinline__ float bfhi(unsigned w) { return __uint_as_float(w & 0xffff0000u); }
; __device__ __forceinline__ void b_unit(Frame& F, int u, bool dry) {
;     ...
;     const LAS unsigned char* XF = Bt + (size_t)(fq * 16 + fr) * 16;
; #pragma unroll
;     for (int p = 0; p < 4; ++p) {
;         f32x4 o3[2][2];
; #pragma unroll
;         for (int h = 0; h < 2; ++h) { const int lb = 2 * p + h;
;             o3[h][0] = (f32x4){0.f, 0.f, 0.f, 0.f}; o3[h][1] = (f32x4){0.f, 0.f, 0.f, 0.f};
; #pragma unroll
;             for (int t = 0; t < 4; ++t) {
;                 const bf16x8 xc = *(const LAS bf16x8*)(XF + (size_t)((lb * 4 + t) * 2 + 0) * 1024), xs = *(const LAS bf16x8*)(XF + (size_t)((lb * 4 + t) * 2 + 1) * 1024);
; #pragma unroll
;                 for (int mb = 0; mb < 2; ++mb) { o3[h][mb] = __builtin_amdgcn_mfma_f32_16x16x32_bf16(xc, yr[mb][t], o3[h][mb], 0, 0, 0); o3[h][mb] = __builtin_amdgcn_mfma_f32_16x16x32_bf16(xs, yi[mb][t], o3[h][mb], 0, 0, 0); }
;             }
;         }
; #pragma unroll
;         for (int mb = 0; mb < 2; ++mb) { const int k1 = 2 * w + mb + 16 * fr; const size_t tok = (size_t)b * SEQ + 8 * k1 + k2; const u32x4 sb = sbq[p][mb]; const f32x4 a0 = o3[0][mb] * 0.001953125f, a1 = o3[1][mb] * 0.001953125f;
;             u32x4 o; o.x = cvtpk(bflo(sb.x) * a0[0], bfhi(sb.x) * a0[1]); o.y = cvtpk(bflo(sb.y) * a0[2], bfhi(sb.y) * a0[3]); o.z = cvtpk(bflo(sb.z) * a1[0], bfhi(sb.z) * a1[1]); o.w = cvtpk(bflo(sb.w) * a1[2], bfhi(sb.w) * a1[3]);
;             if (!dry) *(GAS u32x4*)(SBG + tok * 512 + g * 128 + 32 * p + 8 * fq) = o; }
;     }
	v_lshlrev_b32_e32 v106, 16, v88
	v_and_b32_e32 v107, 0xffff0000, v88
	v_pk_mul_f32 v[94:95], v[94:95], v[106:107]
	v_pk_mul_f32 v[102:103], v[108:109], s[0:1] op_sel_hi:[1,0]
	v_cvt_pk_bf16_f32 v88, v94, v95
	v_lshlrev_b32_e32 v94, 16, v89
	v_and_b32_e32 v95, 0xffff0000, v89
	v_pk_mul_f32 v[92:93], v[92:93], v[94:95]
	s_nop 0
	v_cvt_pk_bf16_f32 v89, v92, v93
	v_lshlrev_b32_e32 v92, 16, v90
	v_and_b32_e32 v93, 0xffff0000, v90
	v_pk_mul_f32 v[92:93], v[104:105], v[92:93]
	s_nop 0
	v_cvt_pk_bf16_f32 v90, v92, v93
	v_lshlrev_b32_e32 v92, 16, v91
	v_and_b32_e32 v93, 0xffff0000, v91
	v_pk_mul_f32 v[92:93], v[102:103], v[92:93]
	s_nop 0
	v_cvt_pk_bf16_f32 v91, v92, v93
	global_store_dwordx4 v[96:97], v[88:91], off
	ds_read_b128 v[88:91], v100 offset:16384
	ds_read_b128 v[92:95], v100 offset:17408
	s_waitcnt lgkmcnt(1)
	v_mfma_f32_16x16x32_bf16 v[102:105], v[88:91], v[52:55], 0
	v_mfma_f32_16x16x32_bf16 v[88:91], v[88:91], v[56:59], 0
	s_waitcnt lgkmcnt(0)
	v_mfma_f32_16x16x32_bf16 v[102:105], v[92:95], v[48:51], v[102:105]
	v_mfma_f32_16x16x32_bf16 v[88:91], v[92:95], v[60:63], v[88:91]
	ds_read_b128 v[92:95], v100 offset:18432
	ds_read_b128 v[106:109], v100 offset:19456
	s_waitcnt lgkmcnt(1)
	v_mfma_f32_16x16x32_bf16 v[102:105], v[92:95], v[36:39], v[102:105]
	v_mfma_f32_16x16x32_bf16 v[88:91], v[92:95], v[40:43], v[88:91]
	s_waitcnt lgkmcnt(0)
	v_mfma_f32_16x16x32_bf16 v[102:105], v[106:109], v[32:35], v[102:105]
	v_mfma_f32_16x16x32_bf16 v[88:91], v[106:109], v[44:47], v[88:91]
	ds_read_b128 v[92:95], v100 offset:20480
	ds_read_b128 v[106:109], v100 offset:21504
	s_waitcnt lgkmcnt(1)
	v_mfma_f32_16x16x32_bf16 v[102:105], v[92:95], v[20:23], v[102:105]
	v_mfma_f32_16x16x32_bf16 v[88:91], v[92:95], v[24:27], v[88:91]
	s_waitcnt lgkmcnt(0)
	v_mfma_f32_16x16x32_bf16 v[102:105], v[106:109], v[16:19], v[102:105]
	v_mfma_f32_16x16x32_bf16 v[88:91], v[106:109], v[28:31], v[88:91]
	ds_read_b128 v[92:95], v100 offset:22528
	ds_read_b128 v[106:109], v100 offset:23552
	s_waitcnt lgkmcnt(1)
	v_mfma_f32_16x16x32_bf16 v[102:105], v[92:95], v[8:11], v[102:105]
	v_mfma_f32_16x16x32_bf16 v[88:91], v[92:95], v[12:15], v[88:91]
	s_waitcnt lgkmcnt(0)
	v_mfma_f32_16x16x32_bf16 v[102:105], v[106:109], v[0:3], v[102:105]
	v_mfma_f32_16x16x32_bf16 v[88:91], v[106:109], v[4:7], v[88:91]
	ds_read_b128 v[92:95], v100 offset:24576
	ds_read_b128 v[106:109], v100 offset:25600
	s_nop 4
	v_pk_mul_f32 v[102:103], v[102:103], s[0:1] op_sel_hi:[1,0]
	v_pk_mul_f32 v[104:105], v[104:105], s[0:1] op_sel_hi:[1,0]
	s_waitcnt lgkmcnt(1)
	v_mfma_f32_16x16x32_bf16 v[110:113], v[92:95], v[52:55], 0
	v_mfma_f32_16x16x32_bf16 v[92:95], v[92:95], v[56:59], 0
	s_waitcnt lgkmcnt(0)
	v_mfma_f32_16x16x32_bf16 v[110:113], v[106:109], v[48:51], v[110:113]
	v_mfma_f32_16x16x32_bf16 v[92:95], v[106:109], v[60:63], v[92:95]
	ds_read_b128 v[106:109], v100 offset:26624
	ds_read_b128 v[114:117], v100 offset:27648
	s_waitcnt lgkmcnt(1)
	v_mfma_f32_16x16x32_bf16 v[110:113], v[106:109], v[36:39], v[110:113]
	v_mfma_f32_16x16x32_bf16 v[92:95], v[106:109], v[40:43], v[92:95]
	s_waitcnt lgkmcnt(0)
	v_mfma_f32_16x16x32_bf16 v[110:113], v[114:117], v[32:35], v[110:113]
	v_mfma_f32_16x16x32_bf16 v[92:95], v[114:117], v[44:47], v[92:95]
	ds_read_b128 v[106:109], v100 offset:28672
	ds_read_b128 v[114:117], v100 offset:29696
	s_waitcnt lgkmcnt(1)
	v_mfma_f32_16x16x32_bf16 v[110:113], v[106:109], v[20:23], v[110:113]
	v_mfma_f32_16x16x32_bf16 v[92:95], v[106:109], v[24:27], v[92:95]
	s_waitcnt lgkmcnt(0)
	v_mfma_f32_16x16x32_bf16 v[110:113], v[114:117], v[16:19], v[110:113]
	v_mfma_f32_16x16x32_bf16 v[92:95], v[114:117], v[28:31], v[92:95]
	ds_read_b128 v[106:109], v100 offset:30720
	ds_read_b128 v[114:117], v100 offset:31744
	s_waitcnt lgkmcnt(1)
	v_mfma_f32_16x16x32_bf16 v[110:113], v[106:109], v[8:11], v[110:113]
	s_waitcnt lgkmcnt(0)
	v_mfma_f32_16x16x32_bf16 v[110:113], v[114:117], v[0:3], v[110:113]
	v_mfma_f32_16x16x32_bf16 v[92:95], v[106:109], v[12:15], v[92:95]
	v_mfma_f32_16x16x32_bf16 v[92:95], v[114:117], v[4:7], v[92:95]
	s_nop 5
	v_mul_f32_e64 v108, v110, s0
	v_mul_f32_e64 v109, v111, s0
	s_waitcnt vmcnt(7)
	v_lshlrev_b32_e32 v110, 16, v84
	v_and_b32_e32 v111, 0xffff0000, v84
	v_pk_mul_f32 v[102:103], v[102:103], v[110:111]
	v_pk_mul_f32 v[106:107], v[112:113], s[0:1] op_sel_hi:[1,0]
	v_cvt_pk_bf16_f32 v84, v102, v103
	v_lshlrev_b32_e32 v102, 16, v85
	v_and_b32_e32 v103, 0xffff0000, v85
	v_pk_mul_f32 v[102:103], v[104:105], v[102:103]
	s_nop 0
	v_cvt_pk_bf16_f32 v85, v102, v103
	v_lshlrev_b32_e32 v102, 16, v86
	v_and_b32_e32 v103, 0xffff0000, v86
	v_pk_mul_f32 v[102:103], v[108:109], v[102:103]
	s_nop 0
	v_cvt_pk_bf16_f32 v86, v102, v103
	v_lshlrev_b32_e32 v102, 16, v87
	v_and_b32_e32 v103, 0xffff0000, v87
	v_pk_mul_f32 v[102:103], v[106:107], v[102:103]
	s_nop 0
	v_cvt_pk_bf16_f32 v87, v102, v103
	global_store_dwordx4 v[98:99], v[84:87], off offset:64
	s_nop 1
	v_pk_mul_f32 v[84:85], v[90:91], s[0:1] op_sel_hi:[1,0]
	v_pk_mul_f32 v[86:87], v[88:89], s[0:1] op_sel_hi:[1,0]
	v_pk_mul_f32 v[90:91], v[92:93], s[0:1] op_sel_hi:[1,0]
	s_waitcnt vmcnt(7)
	v_lshlrev_b32_e32 v92, 16, v80
	v_and_b32_e32 v93, 0xffff0000, v80
	v_pk_mul_f32 v[86:87], v[86:87], v[92:93]
	v_pk_mul_f32 v[88:89], v[94:95], s[0:1] op_sel_hi:[1,0]
	v_cvt_pk_bf16_f32 v80, v86, v87
	v_lshlrev_b32_e32 v86, 16, v81
	v_and_b32_e32 v87, 0xffff0000, v81
	v_pk_mul_f32 v[84:85], v[84:85], v[86:87]
	s_nop 0
	v_cvt_pk_bf16_f32 v81, v84, v85
	v_lshlrev_b32_e32 v84, 16, v82
	v_and_b32_e32 v85, 0xffff0000, v82
	v_pk_mul_f32 v[84:85], v[90:91], v[84:85]
	s_nop 0
	v_cvt_pk_bf16_f32 v82, v84, v85
	v_lshlrev_b32_e32 v84, 16, v83
	v_and_b32_e32 v85, 0xffff0000, v83
	v_pk_mul_f32 v[84:85], v[88:89], v[84:85]
	s_nop 0
	v_cvt_pk_bf16_f32 v83, v84, v85
	global_store_dwordx4 v[96:97], v[80:83], off offset:64
	ds_read_b128 v[80:83], v100 offset:32768
	ds_read_b128 v[84:87], v100 offset:33792
	s_waitcnt lgkmcnt(1)
; #define LAS __attribute__((address_space(3)))
; #define GAS __attribute__((address_space(1)))
; __device__ __forceinline__ unsigned cvtpk(float lo, float hi) { f32x2 v = {lo, hi}; bf16x2_t b = __builtin_convertvector(v, bf16x2_t); return __builtin_bit_cast(unsigned, b); }
; __device__ __forceinline__ float bflo(unsigned w) { return __uint_as_float(w << 16); }
; __device__ __forceinline__ float bfhi(unsigned w) { return __uint_as_float(w & 0xffff0000u); }
; __device__ __forceinline__ void b_unit(Frame& F, int u, bool dry) {
;     ...
;     const LAS unsigned char* XF = Bt + (size_t)(fq * 16 + fr) * 16;
; #pragma unroll
;     for (int p = 0; p < 4; ++p) {
;         f32x4 o3[2][2];
; #pragma unroll
;         for (int h = 0; h < 2; ++h) { const int lb = 2 * p + h;
;             o3[h][0] = (f32x4){0.f, 0.f, 0.f, 0.f}; o3[h][1] = (f32x4){0.f, 0.f, 0.f, 0.f};
; #pragma unroll
;             for (int t = 0; t < 4; ++t) {
;                 const bf16x8 xc = *(const LAS bf16x8*)(XF + (size_t)((lb * 4 + t) * 2 + 0) * 1024), xs = *(const LAS bf16x8*)(XF + (size_t)((lb * 4 + t) * 2 + 1) * 1024);
; #pragma unroll
;                 for (int mb = 0; mb < 2; ++mb) { o3[h][mb] = __builtin_amdgcn_mfma_f32_16x16x32_bf16(xc, yr[mb][t], o3[h][mb], 0, 0, 0); o3[h][mb] = __builtin_amdgcn_mfma_f32_16x16x32_bf16(xs, yi[mb][t], o3[h][mb], 0, 0, 0); }
;             }
;         }
; #pragma unroll
;         for (int mb = 0; mb < 2; ++mb) { const int k1 = 2 * w + mb + 16 * fr; const size_t tok = (size_t)b * SEQ + 8 * k1 + k2; const u32x4 sb = sbq[p][mb]; const f32x4 a0 = o3[0][mb] * 0.001953125f, a1 = o3[1][mb] * 0.001953125f;
;             u32x4 o; o.x = cvtpk(bflo(sb.x) * a0[0], bfhi(sb.x) * a0[1]); o.y = cvtpk(bflo(sb.y) * a0[2], bfhi(sb.y) * a0[3]); o.z = cvtpk(bflo(sb.z) * a1[0], bfhi(sb.z) * a1[1]); o.w = cvtpk(bflo(sb.w) * a1[2], bfhi(sb.w) * a1[3]);
;             if (!dry) *(GAS u32x4*)(SBG + tok * 512 + g * 128 + 32 * p + 8 * fq) = o; }
;     }
	v_mfma_f32_16x16x32_bf16 v[88:91], v[80:83], v[52:55], 0
	v_mfma_f32_16x16x32_bf16 v[80:83], v[80:83], v[56:59], 0
	s_waitcnt lgkmcnt(0)
	v_mfma_f32_16x16x32_bf16 v[88:91], v[84:87], v[48:51], v[88:91]
	v_mfma_f32_16x16x32_bf16 v[80:83], v[84:87], v[60:63], v[80:83]
	ds_read_b128 v[84:87], v100 offset:34816
	ds_read_b128 v[92:95], v100 offset:35840
	s_waitcnt lgkmcnt(1)
	v_mfma_f32_16x16x32_bf16 v[88:91], v[84:87], v[36:39], v[88:91]
	v_mfma_f32_16x16x32_bf16 v[80:83], v[84:87], v[40:43], v[80:83]
	s_waitcnt lgkmcnt(0)
	v_mfma_f32_16x16x32_bf16 v[88:91], v[92:95], v[32:35], v[88:91]
	v_mfma_f32_16x16x32_bf16 v[80:83], v[92:95], v[44:47], v[80:83]
	ds_read_b128 v[84:87], v100 offset:36864
	ds_read_b128 v[92:95], v100 offset:37888
	s_waitcnt lgkmcnt(1)
	v_mfma_f32_16x16x32_bf16 v[88:91], v[84:87], v[20:23], v[88:91]
	v_mfma_f32_16x16x32_bf16 v[80:83], v[84:87], v[24:27], v[80:83]
	s_waitcnt lgkmcnt(0)
	v_mfma_f32_16x16x32_bf16 v[88:91], v[92:95], v[16:19], v[88:91]
	v_mfma_f32_16x16x32_bf16 v[80:83], v[92:95], v[28:31], v[80:83]
	ds_read_b128 v[92:95], v100 offset:38912
	ds_read_b128 v[102:105], v100 offset:39936
	s_waitcnt lgkmcnt(1)
	v_mfma_f32_16x16x32_bf16 v[84:87], v[92:95], v[8:11], v[88:91]
	v_mfma_f32_16x16x32_bf16 v[80:83], v[92:95], v[12:15], v[80:83]
	s_nop 1
	ds_read_b128 v[88:91], v100 offset:40960
	ds_read_b128 v[92:95], v100 offset:41984
	s_waitcnt lgkmcnt(2)
	v_mfma_f32_16x16x32_bf16 v[84:87], v[102:105], v[0:3], v[84:87]
	v_mfma_f32_16x16x32_bf16 v[80:83], v[102:105], v[4:7], v[80:83]
	s_waitcnt lgkmcnt(1)
	v_mfma_f32_16x16x32_bf16 v[102:105], v[88:91], v[52:55], 0
	s_nop 4
	v_mul_f32_e64 v84, v84, s0
	v_mul_f32_e64 v85, v85, s0
	v_pk_mul_f32 v[86:87], v[86:87], s[0:1] op_sel_hi:[1,0]
	v_mfma_f32_16x16x32_bf16 v[88:91], v[88:91], v[56:59], 0
	s_waitcnt lgkmcnt(0)
	v_mfma_f32_16x16x32_bf16 v[102:105], v[92:95], v[48:51], v[102:105]
	v_mfma_f32_16x16x32_bf16 v[88:91], v[92:95], v[60:63], v[88:91]
	ds_read_b128 v[92:95], v100 offset:43008
	ds_read_b128 v[106:109], v100 offset:44032
	s_waitcnt lgkmcnt(1)
	v_mfma_f32_16x16x32_bf16 v[102:105], v[92:95], v[36:39], v[102:105]
	v_mfma_f32_16x16x32_bf16 v[88:91], v[92:95], v[40:43], v[88:91]
	s_waitcnt lgkmcnt(0)
	v_mfma_f32_16x16x32_bf16 v[102:105], v[106:109], v[32:35], v[102:105]
	v_mfma_f32_16x16x32_bf16 v[88:91], v[106:109], v[44:47], v[88:91]
	ds_read_b128 v[92:95], v100 offset:45056
	ds_read_b128 v[106:109], v100 offset:46080
	s_waitcnt lgkmcnt(1)
	v_mfma_f32_16x16x32_bf16 v[102:105], v[92:95], v[20:23], v[102:105]
	v_mfma_f32_16x16x32_bf16 v[88:91], v[92:95], v[24:27], v[88:91]
	s_waitcnt lgkmcnt(0)
	v_mfma_f32_16x16x32_bf16 v[102:105], v[106:109], v[16:19], v[102:105]
	v_mfma_f32_16x16x32_bf16 v[88:91], v[106:109], v[28:31], v[88:91]
	ds_read_b128 v[92:95], v100 offset:47104
	ds_read_b128 v[106:109], v100 offset:48128
	s_waitcnt lgkmcnt(1)
	v_mfma_f32_16x16x32_bf16 v[102:105], v[92:95], v[8:11], v[102:105]
	s_waitcnt lgkmcnt(0)
	v_mfma_f32_16x16x32_bf16 v[102:105], v[106:109], v[0:3], v[102:105]
	v_mfma_f32_16x16x32_bf16 v[88:91], v[92:95], v[12:15], v[88:91]
	v_mfma_f32_16x16x32_bf16 v[88:91], v[106:109], v[4:7], v[88:91]
	s_nop 5
	v_mul_f32_e64 v94, v102, s0
	v_mul_f32_e64 v95, v103, s0
	s_waitcnt vmcnt(7)
	v_lshlrev_b32_e32 v102, 16, v76
	v_and_b32_e32 v103, 0xffff0000, v76
	v_pk_mul_f32 v[84:85], v[84:85], v[102:103]
	v_pk_mul_f32 v[92:93], v[104:105], s[0:1] op_sel_hi:[1,0]
	v_cvt_pk_bf16_f32 v76, v84, v85
	v_lshlrev_b32_e32 v84, 16, v77
	v_and_b32_e32 v85, 0xffff0000, v77
	v_pk_mul_f32 v[84:85], v[86:87], v[84:85]
	s_nop 0
	v_cvt_pk_bf16_f32 v77, v84, v85
	v_lshlrev_b32_e32 v84, 16, v78
	v_and_b32_e32 v85, 0xffff0000, v78
	v_pk_mul_f32 v[84:85], v[94:95], v[84:85]
	s_nop 0
	v_cvt_pk_bf16_f32 v78, v84, v85
	v_lshlrev_b32_e32 v84, 16, v79
	v_and_b32_e32 v85, 0xffff0000, v79
	v_pk_mul_f32 v[84:85], v[92:93], v[84:85]
	s_nop 0
	v_cvt_pk_bf16_f32 v79, v84, v85
	global_store_dwordx4 v[98:99], v[76:79], off offset:128
	s_waitcnt vmcnt(7)
	v_lshlrev_b32_e32 v84, 16, v72
	v_and_b32_e32 v85, 0xffff0000, v72
	v_pk_mul_f32 v[78:79], v[80:81], s[0:1] op_sel_hi:[1,0]
	v_pk_mul_f32 v[76:77], v[82:83], s[0:1] op_sel_hi:[1,0]
	v_pk_mul_f32 v[78:79], v[78:79], v[84:85]
	v_pk_mul_f32 v[82:83], v[88:89], s[0:1] op_sel_hi:[1,0]
	v_cvt_pk_bf16_f32 v72, v78, v79
	v_lshlrev_b32_e32 v78, 16, v73
	v_and_b32_e32 v79, 0xffff0000, v73
	v_pk_mul_f32 v[76:77], v[76:77], v[78:79]
	v_pk_mul_f32 v[80:81], v[90:91], s[0:1] op_sel_hi:[1,0]
	v_cvt_pk_bf16_f32 v73, v76, v77
	v_lshlrev_b32_e32 v76, 16, v74
	v_and_b32_e32 v77, 0xffff0000, v74
	v_pk_mul_f32 v[76:77], v[82:83], v[76:77]
	s_nop 0
	v_cvt_pk_bf16_f32 v74, v76, v77
	v_lshlrev_b32_e32 v76, 16, v75
	v_and_b32_e32 v77, 0xffff0000, v75
	v_pk_mul_f32 v[76:77], v[80:81], v[76:77]
	s_nop 0
	v_cvt_pk_bf16_f32 v75, v76, v77
	global_store_dwordx4 v[96:97], v[72:75], off offset:128
	ds_read_b128 v[72:75], v100 offset:49152
	ds_read_b128 v[76:79], v100 offset:50176
	s_waitcnt lgkmcnt(1)
	v_mfma_f32_16x16x32_bf16 v[80:83], v[72:75], v[52:55], 0
	v_mfma_f32_16x16x32_bf16 v[72:75], v[72:75], v[56:59], 0
	s_waitcnt lgkmcnt(0)
; #define LAS __attribute__((address_space(3)))
; #define GAS __attribute__((address_space(1)))
; __device__ __forceinline__ unsigned cvtpk(float lo, float hi) { f32x2 v = {lo, hi}; bf16x2_t b = __builtin_convertvector(v, bf16x2_t); return __builtin_bit_cast(unsigned, b); }
; __device__ __forceinline__ float bflo(unsigned w) { return __uint_as_float(w << 16); }
; __device__ __forceinline__ float bfhi(unsigned w) { return __uint_as_float(w & 0xffff0000u); }
; __device__ __forceinline__ void xcdl_wait_t0(const XcdBarrier& b) {
;     if (is_t0(b.wave)) {
;         unsigned* bar = b.bar; asm volatile("" : "+s"(bar));
;         const unsigned gen = b.st[5];
;         XB_SPIN(xb_ld(&bar[XB_LGEN(b.x)]) == gen, bar);
;         __builtin_amdgcn_fence(__ATOMIC_ACQUIRE, "agent");
;         asm volatile("s_waitcnt vmcnt(0)" ::: "memory");
;     }
; }
; __device__ __forceinline__ void b_unit(Frame& F, int u, bool dry) {
;     ...
;     const LAS unsigned char* XF = Bt + (size_t)(fq * 16 + fr) * 16;
; #pragma unroll
;     for (int p = 0; p < 4; ++p) {
;         f32x4 o3[2][2];
; #pragma unroll
;         for (int h = 0; h < 2; ++h) { const int lb = 2 * p + h;
;             o3[h][0] = (f32x4){0.f, 0.f, 0.f, 0.f}; o3[h][1] = (f32x4){0.f, 0.f, 0.f, 0.f};
; #pragma unroll
;             for (int t = 0; t < 4; ++t) {
;                 const bf16x8 xc = *(const LAS bf16x8*)(XF + (size_t)((lb * 4 + t) * 2 + 0) * 1024), xs = *(const LAS bf16x8*)(XF + (size_t)((lb * 4 + t) * 2 + 1) * 1024);
; #pragma unroll
;                 for (int mb = 0; mb < 2; ++mb) { o3[h][mb] = __builtin_amdgcn_mfma_f32_16x16x32_bf16(xc, yr[mb][t], o3[h][mb], 0, 0, 0); o3[h][mb] = __builtin_amdgcn_mfma_f32_16x16x32_bf16(xs, yi[mb][t], o3[h][mb], 0, 0, 0); }
;             }
;         }
; #pragma unroll
;         for (int mb = 0; mb < 2; ++mb) { const int k1 = 2 * w + mb + 16 * fr; const size_t tok = (size_t)b * SEQ + 8 * k1 + k2; const u32x4 sb = sbq[p][mb]; const f32x4 a0 = o3[0][mb] * 0.001953125f, a1 = o3[1][mb] * 0.001953125f;
;             u32x4 o; o.x = cvtpk(bflo(sb.x) * a0[0], bfhi(sb.x) * a0[1]); o.y = cvtpk(bflo(sb.y) * a0[2], bfhi(sb.y) * a0[3]); o.z = cvtpk(bflo(sb.z) * a1[0], bfhi(sb.z) * a1[1]); o.w = cvtpk(bflo(sb.w) * a1[2], bfhi(sb.w) * a1[3]);
;             if (!dry) *(GAS u32x4*)(SBG + tok * 512 + g * 128 + 32 * p + 8 * fq) = o; }
;     }
;     __syncthreads();
	v_mfma_f32_16x16x32_bf16 v[80:83], v[76:79], v[48:51], v[80:83]
	v_mfma_f32_16x16x32_bf16 v[72:75], v[76:79], v[60:63], v[72:75]
	ds_read_b128 v[76:79], v100 offset:51200
	ds_read_b128 v[84:87], v100 offset:52224
	s_waitcnt lgkmcnt(1)
	v_mfma_f32_16x16x32_bf16 v[80:83], v[76:79], v[36:39], v[80:83]
	v_mfma_f32_16x16x32_bf16 v[72:75], v[76:79], v[40:43], v[72:75]
	s_waitcnt lgkmcnt(0)
	v_mfma_f32_16x16x32_bf16 v[80:83], v[84:87], v[32:35], v[80:83]
	v_mfma_f32_16x16x32_bf16 v[72:75], v[84:87], v[44:47], v[72:75]
	ds_read_b128 v[76:79], v100 offset:53248
	ds_read_b128 v[84:87], v100 offset:54272
	s_waitcnt lgkmcnt(1)
	v_mfma_f32_16x16x32_bf16 v[80:83], v[76:79], v[20:23], v[80:83]
	v_mfma_f32_16x16x32_bf16 v[72:75], v[76:79], v[24:27], v[72:75]
	s_waitcnt lgkmcnt(0)
	v_mfma_f32_16x16x32_bf16 v[80:83], v[84:87], v[16:19], v[80:83]
	v_mfma_f32_16x16x32_bf16 v[72:75], v[84:87], v[28:31], v[72:75]
	ds_read_b128 v[84:87], v100 offset:55296
	ds_read_b128 v[88:91], v100 offset:56320
	s_waitcnt lgkmcnt(1)
	v_mfma_f32_16x16x32_bf16 v[76:79], v[84:87], v[8:11], v[80:83]
	v_mfma_f32_16x16x32_bf16 v[72:75], v[84:87], v[12:15], v[72:75]
	s_nop 1
	ds_read_b128 v[80:83], v100 offset:57344
	ds_read_b128 v[84:87], v100 offset:58368
	s_waitcnt lgkmcnt(1)
	v_mfma_f32_16x16x32_bf16 v[52:55], v[80:83], v[52:55], 0
	s_waitcnt lgkmcnt(0)
	v_mfma_f32_16x16x32_bf16 v[48:51], v[84:87], v[48:51], v[52:55]
	v_mfma_f32_16x16x32_bf16 v[52:55], v[80:83], v[56:59], 0
	v_mfma_f32_16x16x32_bf16 v[52:55], v[84:87], v[60:63], v[52:55]
	ds_read_b128 v[56:59], v100 offset:59392
	ds_read_b128 v[60:63], v100 offset:60416
	s_waitcnt lgkmcnt(1)
	v_mfma_f32_16x16x32_bf16 v[36:39], v[56:59], v[36:39], v[48:51]
	s_waitcnt lgkmcnt(0)
	v_mfma_f32_16x16x32_bf16 v[32:35], v[60:63], v[32:35], v[36:39]
	v_mfma_f32_16x16x32_bf16 v[36:39], v[56:59], v[40:43], v[52:55]
	v_mfma_f32_16x16x32_bf16 v[36:39], v[60:63], v[44:47], v[36:39]
	ds_read_b128 v[40:43], v100 offset:61440
	ds_read_b128 v[44:47], v100 offset:62464
	v_mov_b32_e32 v53, v193
	s_waitcnt lgkmcnt(1)
	v_mfma_f32_16x16x32_bf16 v[20:23], v[40:43], v[20:23], v[32:35]
	s_waitcnt lgkmcnt(0)
	v_mfma_f32_16x16x32_bf16 v[16:19], v[44:47], v[16:19], v[20:23]
	v_mfma_f32_16x16x32_bf16 v[20:23], v[40:43], v[24:27], v[36:39]
	v_mfma_f32_16x16x32_bf16 v[20:23], v[44:47], v[28:31], v[20:23]
	ds_read_b128 v[24:27], v100 offset:63488
	ds_read_b128 v[28:31], v100 offset:64512
	s_waitcnt lgkmcnt(1)
	v_mfma_f32_16x16x32_bf16 v[8:11], v[24:27], v[8:11], v[16:19]
	v_mfma_f32_16x16x32_bf16 v[76:79], v[88:91], v[0:3], v[76:79]
	s_waitcnt lgkmcnt(0)
	v_mfma_f32_16x16x32_bf16 v[0:3], v[28:31], v[0:3], v[8:11]
	v_mfma_f32_16x16x32_bf16 v[8:11], v[24:27], v[12:15], v[20:23]
	v_mfma_f32_16x16x32_bf16 v[72:75], v[88:91], v[4:7], v[72:75]
	s_nop 5
	v_mul_f32_e64 v12, v2, s0
	v_mul_f32_e64 v13, v3, s0
	v_pk_mul_f32 v[2:3], v[0:1], s[0:1] op_sel_hi:[1,0]
	s_waitcnt vmcnt(7)
	v_lshlrev_b32_e32 v0, 16, v68
	v_mfma_f32_16x16x32_bf16 v[4:7], v[28:31], v[4:7], v[8:11]
	v_and_b32_e32 v1, 0xffff0000, v68
	s_nop 1
	v_pk_mul_f32 v[10:11], v[76:77], s[0:1] op_sel_hi:[1,0]
	v_pk_mul_f32 v[8:9], v[78:79], s[0:1] op_sel_hi:[1,0]
	v_pk_mul_f32 v[0:1], v[10:11], v[0:1]
	v_lshlrev_b32_e32 v10, 16, v69
	v_and_b32_e32 v11, 0xffff0000, v69
	v_pk_mul_f32 v[8:9], v[8:9], v[10:11]
	v_cvt_pk_bf16_f32 v0, v0, v1
	v_cvt_pk_bf16_f32 v1, v8, v9
	v_lshlrev_b32_e32 v8, 16, v70
	v_and_b32_e32 v9, 0xffff0000, v70
	v_pk_mul_f32 v[2:3], v[2:3], v[8:9]
	v_lshlrev_b32_e32 v8, 16, v71
	v_and_b32_e32 v9, 0xffff0000, v71
	v_pk_mul_f32 v[8:9], v[12:13], v[8:9]
	v_cvt_pk_bf16_f32 v2, v2, v3
	v_cvt_pk_bf16_f32 v3, v8, v9
	global_store_dwordx4 v[98:99], v[0:3], off offset:192
	s_waitcnt vmcnt(7)
	v_lshlrev_b32_e32 v8, 16, v64
	v_and_b32_e32 v9, 0xffff0000, v64
	v_pk_mul_f32 v[0:1], v[72:73], s[0:1] op_sel_hi:[1,0]
	v_pk_mul_f32 v[2:3], v[74:75], s[0:1] op_sel_hi:[1,0]
	v_pk_mul_f32 v[0:1], v[0:1], v[8:9]
	v_lshlrev_b32_e32 v8, 16, v65
	v_and_b32_e32 v9, 0xffff0000, v65
	v_pk_mul_f32 v[2:3], v[2:3], v[8:9]
	v_pk_mul_f32 v[4:5], v[4:5], s[0:1] op_sel_hi:[1,0]
	v_cvt_pk_bf16_f32 v0, v0, v1
	v_cvt_pk_bf16_f32 v1, v2, v3
	v_lshlrev_b32_e32 v2, 16, v66
	v_and_b32_e32 v3, 0xffff0000, v66
	v_pk_mul_f32 v[6:7], v[6:7], s[0:1] op_sel_hi:[1,0]
	v_pk_mul_f32 v[2:3], v[4:5], v[2:3]
	v_lshlrev_b32_e32 v4, 16, v67
	v_and_b32_e32 v5, 0xffff0000, v67
	v_pk_mul_f32 v[4:5], v[6:7], v[4:5]
	v_cvt_pk_bf16_f32 v2, v2, v3
	v_cvt_pk_bf16_f32 v3, v4, v5
	v_readlane_b32 s0, v253, 55
	global_store_dwordx4 v[96:97], v[0:3], off offset:192
	s_nop 0
	s_nop 0
	s_nop 0
	s_and_b64 vcc, exec, s[46:47]
	s_cbranch_vccnz .Lsd_w_done
	v_readlane_b32 s2, v253, 3
	v_readlane_b32 s3, v253, 4
	s_cmp_lg_u64 s[2:3], 0
	s_cbranch_scc1 .Lsd_w_done
	s_mov_b64 s[16:17], exec
	s_lshl_b32 s2, s23, 1
	s_add_u32 s6, s26, 0x6000
	s_addc_u32 s7, s27, 0
	s_add_u32 s6, s6, s2
	s_addc_u32 s7, s7, 0
	s_add_i32 s2, s34, 1
	s_mov_b32 exec_lo, -1
	s_mov_b32 exec_hi, 0
	v_mbcnt_lo_u32_b32 v8, -1, 0
	v_lshlrev_b32_e32 v8, 2, v8
	v_mov_b32_e32 v9, s2
	s_mov_b32 s3, 0
	v_cmp_lt_u32_e32 vcc, v248, v9
	s_nop 1
	s_cmp_eq_u64 vcc, 0
	s_cbranch_scc1 .Lsd_w_ok2

; __device__ __forceinline__ unsigned xb_ld(unsigned* p)              { return __hip_atomic_load(p, __ATOMIC_RELAXED, __HIP_MEMORY_SCOPE_AGENT); }
; #define XB_SPIN(cond, bar) do { unsigned _sp = 0; while (cond) { __builtin_amdgcn_s_sleep(1); \
;     if ((++_sp & 255u) == 0u) { if (xb_ld(&(bar)[XB_TMO])) break; if (_sp > XB_SPIN_CAP) { atomicAdd(&(bar)[XB_TMO], 1u); break; } } } } while (0)
; __device__ __forceinline__ bool is_t0(int wave) { return wave == 0 && olane() == 0; }
; __device__ __forceinline__ void xcdl_wait_t0(const XcdBarrier& b) {
;     if (is_t0(b.wave)) {
;         unsigned* bar = b.bar; asm volatile("" : "+s"(bar));
;         const unsigned gen = b.st[5];
;         XB_SPIN(xb_ld(&bar[XB_LGEN(b.x)]) == gen, bar);
;         __builtin_amdgcn_fence(__ATOMIC_ACQUIRE, "agent");
;         asm volatile("s_waitcnt vmcnt(0)" ::: "memory");
;     }
; }
.Lsd_w_ok2:
	s_nop 0
	s_nop 0
	s_nop 0
	s_nop 0
	s_nop 0
	s_nop 0
	s_nop 0
	s_nop 0
	s_nop 0
	s_nop 0
	s_mov_b64 exec, s[16:17]

; __device__ __forceinline__ unsigned xb_ld(unsigned* p)              { return __hip_atomic_load(p, __ATOMIC_RELAXED, __HIP_MEMORY_SCOPE_AGENT); }
; __device__ __forceinline__ unsigned xb_add(unsigned* p, unsigned v) { return __hip_atomic_fetch_add(p, v, __ATOMIC_RELAXED, __HIP_MEMORY_SCOPE_AGENT); }
; #define XB_SPIN(cond, bar) do { unsigned _sp = 0; while (cond) { __builtin_amdgcn_s_sleep(1); \
;     if ((++_sp & 255u) == 0u) { if (xb_ld(&(bar)[XB_TMO])) break; if (_sp > XB_SPIN_CAP) { atomicAdd(&(bar)[XB_TMO], 1u); break; } } } } while (0)
; __device__ __forceinline__ bool is_t0(int wave) { return wave == 0 && olane() == 0; }
; __device__ __forceinline__ void xcdl_barrier(const XcdBarrier& b) {
;     asm volatile("s_waitcnt vmcnt(0)" ::: "memory");
;     __syncthreads();
;     if (is_t0(b.wave)) {
;         unsigned* bar = b.bar; asm volatile("" : "+s"(bar));
;         __builtin_amdgcn_s_waitcnt(0);
;         const unsigned old = xb_add(&bar[XB_LSUB(b.x)], 1u);
;         const unsigned gen = old >> 5;
;         if ((old & 31u) == 31u) xb_add(&bar[XB_LGEN(b.x)], 1u);
;         else XB_SPIN(xb_ld(&bar[XB_LGEN(b.x)]) == gen, bar);
;         __builtin_amdgcn_fence(__ATOMIC_ACQUIRE, "agent");
;         asm volatile("s_waitcnt vmcnt(0)" ::: "memory");
;     }
;     __syncthreads();
; }
; __device__ __forceinline__ void xcdl_arrive(const XcdBarrier& b) {
;     if (is_t0(b.wave)) {
;         unsigned* bar = b.bar; asm volatile("" : "+s"(bar));
;         const unsigned old = xb_add(&bar[XB_LSUB(b.x)], 1u);
;         if ((old & 31u) == 31u) xb_add(&bar[XB_LGEN(b.x)], 1u);
;         b.st[5] = old >> 5;
;     }
; }
.LBB0_611:
	s_and_b64 vcc, exec, s[0:1]
	s_cbranch_vccz .LBB0_631
	s_waitcnt vmcnt(0)
	s_and_b64 vcc, exec, s[46:47]
	s_waitcnt vmcnt(0)
	s_barrier
	s_cbranch_vccnz .LBB0_630
	v_mbcnt_lo_u32_b32 v0, -1, 0
	v_mbcnt_hi_u32_b32 v0, -1, v0
	s_nop 0
	v_cmp_eq_u32_e32 vcc, 0, v0
	s_and_saveexec_b64 s[4:5], vcc
	s_cbranch_execz .LBB0_629
	s_lshl_b32 s6, s23, 1
	s_add_u32 s0, s26, 0x6000
	s_addc_u32 s1, s27, 0
	s_add_u32 s0, s0, s6
	s_addc_u32 s1, s1, 0
	v_readlane_b32 s6, v254, 49
	s_add_i32 s7, s34, 2
	s_lshr_b32 s6, s6, 3
	s_lshl_b32 s6, s6, 2
	v_mov_b32_e32 v0, s6
	v_mov_b32_e32 v1, s7
	s_waitcnt vmcnt(0) lgkmcnt(0)
	global_store_dword v0, v1, s[0:1]
	s_mov_b64 s[10:11], exec
	s_and_b32 s6, s6, 28
	s_lshl_b32 s6, 15, s6
	s_mov_b32 exec_lo, -1
	s_mov_b32 exec_hi, 0
	v_mbcnt_lo_u32_b32 v2, -1, 0
	v_lshlrev_b32_e32 v2, 2, v2
	v_mov_b32_e32 v1, s7
	s_mov_b32 s8, 0
.Lxbf_poll_S2:
	global_load_dword v3, v2, s[0:1] sc1
	s_waitcnt vmcnt(0)
	v_cmp_lt_u32_e32 vcc, v3, v1
	s_nop 1
	s_and_b32 vcc_lo, vcc_lo, s6
	s_cmp_eq_u64 vcc, 0
	s_cbranch_scc1 .Lxbf_done_S2
	s_sleep 1
	s_add_u32 s8, s8, 1
	s_cmp_lt_u32 s8, 0x4000
	s_cbranch_scc1 .Lxbf_poll_S2
	v_mov_b32_e32 v3, 1
	v_mov_b32_e32 v2, 0x200
	global_store_dword v2, v3, s[26:27] sc1
.Lxbf_done_S2:
	v_mov_b32_e32 v249, v3
	buffer_inv sc1
	s_waitcnt vmcnt(0)
	s_mov_b64 exec, s[10:11]
	s_branch .Lxbf_end_S2
	s_nop 0
	s_nop 0
	s_nop 0
	s_nop 0
	s_nop 0
	s_nop 0
	s_nop 0
	s_nop 0
	s_nop 0
	s_nop 0
	s_nop 0
	s_nop 0
	s_nop 0
	s_nop 0
	s_nop 0
	s_nop 0
	s_nop 0
	s_nop 0
	s_nop 0
	s_nop 0
	s_nop 0
	s_nop 0
	s_nop 0
	s_nop 0
	s_nop 0
	s_nop 0
	s_nop 0
	s_nop 0
	s_nop 0
	s_nop 0
	s_nop 0
	s_nop 0
	s_nop 0
	s_nop 0
	s_nop 0
	s_nop 0
	s_nop 0
	s_nop 0
	s_nop 0
	s_nop 0
	s_nop 0
	s_nop 0
	s_nop 0
	s_nop 0
	s_nop 0
	s_nop 0
	s_nop 0
	s_nop 0
	s_nop 0
	s_nop 0
	s_nop 0
	s_nop 0
	s_nop 0
	s_nop 0
	s_nop 0
	s_nop 0
	s_nop 0
	s_nop 0
	s_nop 0
	s_nop 0
	s_nop 0
	s_nop 0
	s_nop 0
	s_nop 0
	s_nop 0
	s_nop 0
	s_nop 0
	s_nop 0
	s_nop 0
	s_nop 0
	s_nop 0
	s_nop 0
	s_nop 0
	s_nop 0
	s_nop 0
	s_nop 0
	s_nop 0
	s_nop 0
	s_nop 0
	s_nop 0
	s_nop 0
	s_nop 0
	s_nop 0
	s_nop 0
	s_nop 0
	s_nop 0
	s_nop 0
	s_nop 0
	s_nop 0
	s_nop 0
	s_nop 0
	s_nop 0
	s_nop 0
	s_nop 0
	s_nop 0
	s_nop 0
	s_nop 0
	s_nop 0
	s_nop 0
	s_nop 0
	s_nop 0
	s_nop 0
	s_nop 0
	s_nop 0
	s_nop 0

; __device__ __forceinline__ unsigned xb_ld(unsigned* p)              { return __hip_atomic_load(p, __ATOMIC_RELAXED, __HIP_MEMORY_SCOPE_AGENT); }
; #define XB_SPIN(cond, bar) do { unsigned _sp = 0; while (cond) { __builtin_amdgcn_s_sleep(1); \
;     if ((++_sp & 255u) == 0u) { if (xb_ld(&(bar)[XB_TMO])) break; if (_sp > XB_SPIN_CAP) { atomicAdd(&(bar)[XB_TMO], 1u); break; } } } } while (0)
; __device__ __forceinline__ bool is_t0(int wave) { return wave == 0 && olane() == 0; }
; __device__ __forceinline__ void xcdl_wait_t0(const XcdBarrier& b) {
;     if (is_t0(b.wave)) {
;         unsigned* bar = b.bar; asm volatile("" : "+s"(bar));
;         const unsigned gen = b.st[5];
;         XB_SPIN(xb_ld(&bar[XB_LGEN(b.x)]) == gen, bar);
;         __builtin_amdgcn_fence(__ATOMIC_ACQUIRE, "agent");
;         asm volatile("s_waitcnt vmcnt(0)" ::: "memory");
;     }
; }
;     __device__ __forceinline__ void mid(Acc& acc, const GUnit& u, int wr, int wc, int fr, int fq) const {
;         const int wl = ((wr * 4 + wc) * 64 + fq * 16 + fr) * 32;
;         const int bra = (u.kind == 0) ? 2 : u.kind - 1, brb = u.kind;
;         const unsigned char* Ga = MG8 + ((size_t)u.pm * 12 + bra * 4 + u.pn) * 65536 + wl; const unsigned char* Gb = MG8 + ((size_t)u.pm * 12 + brb * 4 + u.pn) * 65536 + wl;
.LBB0_655:
	s_cmp_lg_u32 s33, 0
	s_cbranch_scc1 .Lsd2_done
	s_and_b64 vcc, exec, s[46:47]
	s_cbranch_vccnz .Lsd2_done
	v_readlane_b32 s90, v253, 3
	v_readlane_b32 s91, v253, 4
	s_cmp_lg_u64 s[90:91], 0
	s_cbranch_scc1 .Lsd2_done
	s_mov_b64 s[64:65], exec
	s_lshl_b32 s84, s23, 1
	s_add_u32 s90, s26, 0x6000
	s_addc_u32 s91, s27, 0
	s_add_u32 s90, s90, s84
	s_addc_u32 s91, s91, 0
	v_readlane_b32 s92, v254, 54
	s_mov_b32 exec_lo, -1
	s_mov_b32 exec_hi, 0
	s_add_i32 s92, s92, 2
	v_mbcnt_lo_u32_b32 v212, -1, 0
	v_lshlrev_b32_e32 v212, 2, v212
	v_mov_b32_e32 v213, s92
	s_mov_b32 s93, 0
	v_cmp_lt_u32_e32 vcc, v249, v213
	s_nop 1
	s_cmp_eq_u64 vcc, 0
	s_cbranch_scc1 .Lsd2_ok2

; __device__ __forceinline__ unsigned xb_ld(unsigned* p)              { return __hip_atomic_load(p, __ATOMIC_RELAXED, __HIP_MEMORY_SCOPE_AGENT); }
; #define XB_SPIN(cond, bar) do { unsigned _sp = 0; while (cond) { __builtin_amdgcn_s_sleep(1); \
;     if ((++_sp & 255u) == 0u) { if (xb_ld(&(bar)[XB_TMO])) break; if (_sp > XB_SPIN_CAP) { atomicAdd(&(bar)[XB_TMO], 1u); break; } } } } while (0)
; __device__ __forceinline__ bool is_t0(int wave) { return wave == 0 && olane() == 0; }
; __device__ __forceinline__ void xcdl_wait_t0(const XcdBarrier& b) {
;     if (is_t0(b.wave)) {
;         unsigned* bar = b.bar; asm volatile("" : "+s"(bar));
;         const unsigned gen = b.st[5];
;         XB_SPIN(xb_ld(&bar[XB_LGEN(b.x)]) == gen, bar);
;         __builtin_amdgcn_fence(__ATOMIC_ACQUIRE, "agent");
;         asm volatile("s_waitcnt vmcnt(0)" ::: "memory");
;     }
; }
.Lsd2_ok2:
	s_nop 0
	s_nop 0
	s_nop 0
	s_nop 0
	s_nop 0
	s_nop 0
	s_nop 0
	s_nop 0
	s_nop 0
	s_nop 0
	s_nop 0
	s_nop 0
	s_mov_b64 exec, s[64:65]
